# de-serialize GEMM epilogues: hoisted/pipelined loads with counted vmcnt in UQ, UKV, MixA, MixB, Res(P6), GU, Res(P8)
# speedup vs baseline: 1.0008x; 1.0008x over previous
; template <int MASK> DI float shx(float v, int lane) { return __builtin_bit_cast(float, __builtin_amdgcn_ds_bpermute((lane ^ MASK) << 2, __builtin_bit_cast(int, v))); }
; DI float dot4(f32x4 v) { return (v[0] * v[0] + v[1] * v[1]) + (v[2] * v[2] + v[3] * v[3]); }
; #define FOR_ROWS _Pragma("unroll") for (int ai = 0; ai < 2; ++ai) _Pragma("unroll") for (int m = 0; m < 4; ++m)
; #define FOR_BJ _Pragma("unroll") for (int bj = 0; bj < 2; ++bj)
;     DI void operator()(AccRef acc, const Unit& u, int wr, int wc, int fr, int fq) const {
;     ...
;         FOR_ROWS { const int row = row0 + ai * 128 + m * 16; const float rs = __builtin_amdgcn_rsqf(ssq_q[row] * (1.0f / 768.0f) + EPS) * QSCALE_MLA;
;             if (pn < 8) {
;                 FOR_BJ { const f32x4 v0 = acc[ai][bj][m][0] * rs, v1 = acc[ai][bj][m][1] * rs; float sq = dot4(v0) + dot4(v1);
;                     sq += shx<16>(sq, fr | (fq << 4)); sq += shx<32>(sq, fr | (fq << 4)); mxp[bj] = __builtin_fmaxf(mxp[bj], sq);
;                     store8_bf16(Q + (size_t)row * 3072 + (2 * pn + bj) * 192 + c8, v0, v1); }
;             } else {
;                 const int head = 4 * (pn - 8) + wc, pos = row & (SEQ - 1);
;                 f32x4 o1[2], o2[2]; float sq = 0.f;
; #pragma unroll
;                 for (int n = 0; n < 2; ++n) { const f32x4 c = *(const f32x4*)(rcos + pos * 32 + 8 * fq + 4 * n), s = *(const f32x4*)(rsin + pos * 32 + 8 * fq + 4 * n);
;                     const f32x4 x1 = acc[ai][0][m][n] * rs, x2 = acc[ai][1][m][n] * rs; o1[n] = x1 * c - x2 * s; o2[n] = x2 * c + x1 * s; sq += dot4(o1[n]) + dot4(o2[n]); }
;                 sq += shx<16>(sq, fr | (fq << 4)); sq += shx<32>(sq, fr | (fq << 4)); mxp[0] = __builtin_fmaxf(mxp[0], sq);
;                 store8_bf16(Q + (size_t)row * 3072 + head * 192 + 128 + 8 * fq, o1[0], o1[1]); store8_bf16(Q + (size_t)row * 3072 + head * 192 + 160 + 8 * fq, o2[0], o2[1]);
;             } }
.LBB0_898:
	v_lshl_add_u32 v156, s62, 8, v139
	v_ashrrev_i32_e32 v157, 31, v156
	v_lshl_add_u64 v[158:159], v[156:157], 2, s[22:23]
	global_load_dword v216, v[158:159], off
	global_load_dword v217, v[158:159], off offset:64
	global_load_dword v218, v[158:159], off offset:128
	global_load_dword v219, v[158:159], off offset:192
	global_load_dword v220, v[158:159], off offset:512
	global_load_dword v221, v[158:159], off offset:576
	global_load_dword v222, v[158:159], off offset:640
	global_load_dword v223, v[158:159], off offset:704
	s_cmp_gt_i32 s33, 7
	s_cselect_b64 s[26:27], -1, 0
	s_lshl_b32 s50, s33, 2
	s_add_i32 s50, s50, s56
	s_mov_b64 s[8:9], -1
	v_lshlrev_b32_e32 v154, 1, v138
	s_and_b64 vcc, exec, s[26:27]
	s_mul_i32 s10, s50, 0xc0
	s_waitcnt vmcnt(7)
	v_mov_b32_e32 v136, v216
	v_fmamk_f32 v136, v136, 0x3aaaaaab, v170
	v_rsq_f32_e32 v136, v136
	s_nop 0
	v_mul_f32_e32 v160, 0x3dd53b95, v136
	s_cbranch_vccz .LBB0_900
	v_lshlrev_b32_e32 v136, 7, v156
	v_and_b32_e32 v136, 0xfe780, v136
	v_lshl_add_u64 v[176:177], v[144:145], 0, v[136:137]
	global_load_dwordx4 v[172:175], v[176:177], off
	s_nop 0
	global_load_dwordx4 v[176:179], v[176:177], off offset:16
	v_lshl_add_u64 v[184:185], v[142:143], 0, v[136:137]
	global_load_dwordx4 v[180:183], v[184:185], off
	s_nop 0
	global_load_dwordx4 v[184:187], v[184:185], off offset:16
	v_pk_mul_f32 v[188:189], v[126:127], v[160:161] op_sel_hi:[1,0]
	v_pk_mul_f32 v[190:191], v[124:125], v[160:161] op_sel_hi:[1,0]
	v_pk_mul_f32 v[192:193], v[118:119], v[160:161] op_sel_hi:[1,0]
	v_pk_mul_f32 v[194:195], v[116:117], v[160:161] op_sel_hi:[1,0]
	v_pk_mul_f32 v[196:197], v[122:123], v[160:161] op_sel_hi:[1,0]
	v_pk_mul_f32 v[198:199], v[120:121], v[160:161] op_sel_hi:[1,0]
	v_pk_mul_f32 v[200:201], v[114:115], v[160:161] op_sel_hi:[1,0]
	v_pk_mul_f32 v[202:203], v[112:113], v[160:161] op_sel_hi:[1,0]
	v_mov_b64_e32 v[204:205], s[42:43]
	v_mad_i64_i32 v[204:205], s[8:9], v156, s67, v[204:205]
	v_mov_b32_e32 v155, v137
	v_lshl_add_u64 v[204:205], s[10:11], 1, v[204:205]
	v_lshl_add_u64 v[204:205], v[204:205], 0, v[154:155]
	s_mov_b64 s[8:9], 0
	s_waitcnt vmcnt(3)
	v_pk_mul_f32 v[206:207], v[192:193], v[174:175]
	v_pk_mul_f32 v[208:209], v[194:195], v[172:173]
	v_pk_mul_f32 v[174:175], v[188:189], v[174:175]
	v_pk_mul_f32 v[172:173], v[190:191], v[172:173]
	s_waitcnt vmcnt(2)
	v_pk_mul_f32 v[210:211], v[200:201], v[178:179]
	v_pk_mul_f32 v[212:213], v[202:203], v[176:177]
	v_pk_mul_f32 v[178:179], v[196:197], v[178:179]
	v_pk_mul_f32 v[176:177], v[198:199], v[176:177]
	s_waitcnt vmcnt(1)
	v_pk_fma_f32 v[188:189], v[188:189], v[182:183], v[206:207] neg_lo:[0,0,1] neg_hi:[0,0,1]
	v_pk_fma_f32 v[190:191], v[190:191], v[180:181], v[208:209] neg_lo:[0,0,1] neg_hi:[0,0,1]
	v_pk_fma_f32 v[182:183], v[192:193], v[182:183], v[174:175]
	v_pk_fma_f32 v[180:181], v[194:195], v[180:181], v[172:173]
	s_waitcnt vmcnt(0)
	v_pk_fma_f32 v[192:193], v[196:197], v[186:187], v[210:211] neg_lo:[0,0,1] neg_hi:[0,0,1]
	v_pk_fma_f32 v[174:175], v[198:199], v[184:185], v[212:213] neg_lo:[0,0,1] neg_hi:[0,0,1]
	v_pk_fma_f32 v[186:187], v[200:201], v[186:187], v[178:179]
	v_pk_fma_f32 v[178:179], v[202:203], v[184:185], v[176:177]
	v_mov_b32_e32 v184, v191
	v_mov_b32_e32 v185, v175
	v_mov_b32_e32 v196, v189
	v_mov_b32_e32 v197, v193
	v_mov_b32_e32 v200, v181
	v_mov_b32_e32 v201, v179
	v_mov_b32_e32 v206, v183
	v_mov_b32_e32 v207, v187
	v_mov_b32_e32 v176, v190
	v_mov_b32_e32 v177, v174
	v_mov_b32_e32 v194, v188
	v_mov_b32_e32 v195, v192
	v_mov_b32_e32 v198, v180
	v_mov_b32_e32 v199, v178
	v_mov_b32_e32 v202, v182
	v_mov_b32_e32 v203, v186
	v_cvt_pk_bf16_f32 v172, v190, v191
	v_cvt_pk_bf16_f32 v173, v188, v189
	v_pk_mul_f32 v[184:185], v[184:185], v[184:185]
	v_pk_mul_f32 v[188:189], v[196:197], v[196:197]
	v_pk_mul_f32 v[190:191], v[200:201], v[200:201]
	v_pk_mul_f32 v[196:197], v[206:207], v[206:207]
	v_pk_fma_f32 v[176:177], v[176:177], v[176:177], v[184:185]
	v_pk_fma_f32 v[184:185], v[194:195], v[194:195], v[188:189]
	v_pk_fma_f32 v[188:189], v[198:199], v[198:199], v[190:191]
	v_pk_fma_f32 v[190:191], v[202:203], v[202:203], v[196:197]
	v_pk_add_f32 v[176:177], v[176:177], v[184:185]
	v_pk_add_f32 v[184:185], v[188:189], v[190:191]
	v_cvt_pk_bf16_f32 v174, v174, v175
	v_pk_add_f32 v[176:177], v[176:177], v[184:185]
	v_cvt_pk_bf16_f32 v175, v192, v193
	v_add_f32_e32 v136, v176, v177
	ds_bpermute_b32 v155, v161, v136
	v_cvt_pk_bf16_f32 v176, v180, v181
	v_cvt_pk_bf16_f32 v177, v182, v183
	v_cvt_pk_bf16_f32 v178, v178, v179
	v_cvt_pk_bf16_f32 v179, v186, v187
	s_waitcnt lgkmcnt(0)
	v_add_f32_e32 v136, v136, v155
	ds_bpermute_b32 v155, v162, v136
	global_store_dwordx4 v[204:205], v[172:175], off offset:256
	global_store_dwordx4 v[204:205], v[176:179], off offset:320
	s_waitcnt lgkmcnt(0)
	v_add_f32_e32 v136, v136, v155
	v_max_f32_e32 v155, 0, v136

; template <int MASK> DI float shx(float v, int lane) { return __builtin_bit_cast(float, __builtin_amdgcn_ds_bpermute((lane ^ MASK) << 2, __builtin_bit_cast(int, v))); }
; DI float dot4(f32x4 v) { return (v[0] * v[0] + v[1] * v[1]) + (v[2] * v[2] + v[3] * v[3]); }
; #define FOR_ROWS _Pragma("unroll") for (int ai = 0; ai < 2; ++ai) _Pragma("unroll") for (int m = 0; m < 4; ++m)
; #define FOR_BJ _Pragma("unroll") for (int bj = 0; bj < 2; ++bj)
;     DI void operator()(AccRef acc, const Unit& u, int wr, int wc, int fr, int fq) const {
;     ...
;         FOR_ROWS { const int row = row0 + ai * 128 + m * 16; const float rs = __builtin_amdgcn_rsqf(ssq_q[row] * (1.0f / 768.0f) + EPS) * QSCALE_MLA;
;             if (pn < 8) {
;                 FOR_BJ { const f32x4 v0 = acc[ai][bj][m][0] * rs, v1 = acc[ai][bj][m][1] * rs; float sq = dot4(v0) + dot4(v1);
;                     sq += shx<16>(sq, fr | (fq << 4)); sq += shx<32>(sq, fr | (fq << 4)); mxp[bj] = __builtin_fmaxf(mxp[bj], sq);
;                     store8_bf16(Q + (size_t)row * 3072 + (2 * pn + bj) * 192 + c8, v0, v1); }
;             } else {
;                 const int head = 4 * (pn - 8) + wc, pos = row & (SEQ - 1);
;                 f32x4 o1[2], o2[2]; float sq = 0.f;
; #pragma unroll
;                 for (int n = 0; n < 2; ++n) { const f32x4 c = *(const f32x4*)(rcos + pos * 32 + 8 * fq + 4 * n), s = *(const f32x4*)(rsin + pos * 32 + 8 * fq + 4 * n);
;                     const f32x4 x1 = acc[ai][0][m][n] * rs, x2 = acc[ai][1][m][n] * rs; o1[n] = x1 * c - x2 * s; o2[n] = x2 * c + x1 * s; sq += dot4(o1[n]) + dot4(o2[n]); }
;                 sq += shx<16>(sq, fr | (fq << 4)); sq += shx<32>(sq, fr | (fq << 4)); mxp[0] = __builtin_fmaxf(mxp[0], sq);
;                 store8_bf16(Q + (size_t)row * 3072 + head * 192 + 128 + 8 * fq, o1[0], o1[1]); store8_bf16(Q + (size_t)row * 3072 + head * 192 + 160 + 8 * fq, o2[0], o2[1]);
;             } }
.LBB0_902:
	s_nop 1
	v_or_b32_e32 v114, 16, v156
	v_ashrrev_i32_e32 v115, 31, v114
	v_lshl_add_u64 v[112:113], v[114:115], 2, s[22:23]
	s_nop 0
	v_cndmask_b32_e64 v113, 0, 1, s[26:27]
	s_mov_b64 s[54:55], -1
	v_cmp_ne_u32_e64 s[8:9], 1, v113
	s_andn2_b64 vcc, exec, s[26:27]
	v_max_f32_e32 v113, v155, v155
	s_waitcnt vmcnt(8)
	v_mov_b32_e32 v112, v217
	v_fmamk_f32 v112, v112, 0x3aaaaaab, v170
	v_rsq_f32_e32 v112, v112
	s_nop 0
	v_mul_f32_e32 v112, 0x3dd53b95, v112
	s_cbranch_vccnz .LBB0_904
	v_lshlrev_b32_e32 v115, 7, v114
	v_and_b32_e32 v124, 0xfef80, v115
	v_mov_b32_e32 v125, v137
	v_lshl_add_u64 v[120:121], v[144:145], 0, v[124:125]
	global_load_dwordx4 v[116:119], v[120:121], off
	s_nop 0
	global_load_dwordx4 v[120:123], v[120:121], off offset:16
	v_lshl_add_u64 v[172:173], v[142:143], 0, v[124:125]
	global_load_dwordx4 v[124:127], v[172:173], off
	s_nop 0
	global_load_dwordx4 v[172:175], v[172:173], off offset:16
	v_pk_mul_f32 v[176:177], v[110:111], v[112:113] op_sel_hi:[1,0]
	v_pk_mul_f32 v[178:179], v[108:109], v[112:113] op_sel_hi:[1,0]
	v_pk_mul_f32 v[180:181], v[102:103], v[112:113] op_sel_hi:[1,0]
	v_pk_mul_f32 v[182:183], v[100:101], v[112:113] op_sel_hi:[1,0]
	v_pk_mul_f32 v[184:185], v[106:107], v[112:113] op_sel_hi:[1,0]
	v_pk_mul_f32 v[186:187], v[104:105], v[112:113] op_sel_hi:[1,0]
	v_pk_mul_f32 v[188:189], v[98:99], v[112:113] op_sel_hi:[1,0]
	v_pk_mul_f32 v[190:191], v[96:97], v[112:113] op_sel_hi:[1,0]
	v_mov_b64_e32 v[192:193], s[42:43]
	v_mad_i64_i32 v[192:193], s[46:47], v114, s67, v[192:193]
	v_mov_b32_e32 v155, v137
	v_lshl_add_u64 v[192:193], s[10:11], 1, v[192:193]
	v_lshl_add_u64 v[192:193], v[192:193], 0, v[154:155]
	s_mov_b64 s[54:55], 0
	s_waitcnt vmcnt(3)
	v_pk_mul_f32 v[194:195], v[180:181], v[118:119]
	v_pk_mul_f32 v[196:197], v[182:183], v[116:117]
	v_pk_mul_f32 v[118:119], v[176:177], v[118:119]
	v_pk_mul_f32 v[116:117], v[178:179], v[116:117]
	s_waitcnt vmcnt(2)
	v_pk_mul_f32 v[198:199], v[188:189], v[122:123]
	v_pk_mul_f32 v[200:201], v[190:191], v[120:121]
	v_pk_mul_f32 v[122:123], v[184:185], v[122:123]
	v_pk_mul_f32 v[120:121], v[186:187], v[120:121]
	s_waitcnt vmcnt(1)
	v_pk_fma_f32 v[176:177], v[176:177], v[126:127], v[194:195] neg_lo:[0,0,1] neg_hi:[0,0,1]
	v_pk_fma_f32 v[178:179], v[178:179], v[124:125], v[196:197] neg_lo:[0,0,1] neg_hi:[0,0,1]
	v_pk_fma_f32 v[126:127], v[180:181], v[126:127], v[118:119]
	v_pk_fma_f32 v[124:125], v[182:183], v[124:125], v[116:117]
	s_waitcnt vmcnt(0)
	v_pk_fma_f32 v[180:181], v[184:185], v[174:175], v[198:199] neg_lo:[0,0,1] neg_hi:[0,0,1]
	v_pk_fma_f32 v[118:119], v[186:187], v[172:173], v[200:201] neg_lo:[0,0,1] neg_hi:[0,0,1]
	v_pk_fma_f32 v[174:175], v[188:189], v[174:175], v[122:123]
	v_pk_fma_f32 v[122:123], v[190:191], v[172:173], v[120:121]
	v_mov_b32_e32 v172, v179
	v_mov_b32_e32 v173, v119
	v_mov_b32_e32 v184, v177
	v_mov_b32_e32 v185, v181
	v_mov_b32_e32 v188, v125
	v_mov_b32_e32 v189, v123
	v_mov_b32_e32 v194, v127
	v_mov_b32_e32 v195, v175
	v_mov_b32_e32 v120, v178
	v_mov_b32_e32 v121, v118
	v_mov_b32_e32 v182, v176
	v_mov_b32_e32 v183, v180
	v_mov_b32_e32 v186, v124
	v_mov_b32_e32 v187, v122
	v_mov_b32_e32 v190, v126
	v_mov_b32_e32 v191, v174
	v_cvt_pk_bf16_f32 v116, v178, v179
	v_cvt_pk_bf16_f32 v117, v176, v177
	v_pk_mul_f32 v[172:173], v[172:173], v[172:173]
	v_pk_mul_f32 v[176:177], v[184:185], v[184:185]
	v_pk_mul_f32 v[178:179], v[188:189], v[188:189]
	v_pk_mul_f32 v[184:185], v[194:195], v[194:195]
	v_pk_fma_f32 v[120:121], v[120:121], v[120:121], v[172:173]
	v_pk_fma_f32 v[172:173], v[182:183], v[182:183], v[176:177]
	v_pk_fma_f32 v[176:177], v[186:187], v[186:187], v[178:179]
	v_pk_fma_f32 v[178:179], v[190:191], v[190:191], v[184:185]
	v_pk_add_f32 v[120:121], v[120:121], v[172:173]
	v_pk_add_f32 v[172:173], v[176:177], v[178:179]
	v_cvt_pk_bf16_f32 v118, v118, v119
	v_pk_add_f32 v[120:121], v[120:121], v[172:173]
	v_cvt_pk_bf16_f32 v119, v180, v181
	v_add_f32_e32 v115, v120, v121
	ds_bpermute_b32 v155, v161, v115
	v_cvt_pk_bf16_f32 v120, v124, v125
	v_cvt_pk_bf16_f32 v121, v126, v127
	v_cvt_pk_bf16_f32 v122, v122, v123
	v_cvt_pk_bf16_f32 v123, v174, v175
	s_waitcnt lgkmcnt(0)
	v_add_f32_e32 v115, v115, v155
	ds_bpermute_b32 v124, v162, v115
	global_store_dwordx4 v[192:193], v[116:119], off offset:256
	global_store_dwordx4 v[192:193], v[120:123], off offset:320
	s_waitcnt lgkmcnt(0)
	v_add_f32_e32 v115, v115, v124
	v_max_f32_e32 v115, v113, v115

; template <int MASK> DI float shx(float v, int lane) { return __builtin_bit_cast(float, __builtin_amdgcn_ds_bpermute((lane ^ MASK) << 2, __builtin_bit_cast(int, v))); }
; DI float dot4(f32x4 v) { return (v[0] * v[0] + v[1] * v[1]) + (v[2] * v[2] + v[3] * v[3]); }
; #define FOR_ROWS _Pragma("unroll") for (int ai = 0; ai < 2; ++ai) _Pragma("unroll") for (int m = 0; m < 4; ++m)
; #define FOR_BJ _Pragma("unroll") for (int bj = 0; bj < 2; ++bj)
;     DI void operator()(AccRef acc, const Unit& u, int wr, int wc, int fr, int fq) const {
;     ...
;         FOR_ROWS { const int row = row0 + ai * 128 + m * 16; const float rs = __builtin_amdgcn_rsqf(ssq_q[row] * (1.0f / 768.0f) + EPS) * QSCALE_MLA;
;             if (pn < 8) {
;                 FOR_BJ { const f32x4 v0 = acc[ai][bj][m][0] * rs, v1 = acc[ai][bj][m][1] * rs; float sq = dot4(v0) + dot4(v1);
;                     sq += shx<16>(sq, fr | (fq << 4)); sq += shx<32>(sq, fr | (fq << 4)); mxp[bj] = __builtin_fmaxf(mxp[bj], sq);
;                     store8_bf16(Q + (size_t)row * 3072 + (2 * pn + bj) * 192 + c8, v0, v1); }
;             } else {
;                 const int head = 4 * (pn - 8) + wc, pos = row & (SEQ - 1);
;                 f32x4 o1[2], o2[2]; float sq = 0.f;
; #pragma unroll
;                 for (int n = 0; n < 2; ++n) { const f32x4 c = *(const f32x4*)(rcos + pos * 32 + 8 * fq + 4 * n), s = *(const f32x4*)(rsin + pos * 32 + 8 * fq + 4 * n);
;                     const f32x4 x1 = acc[ai][0][m][n] * rs, x2 = acc[ai][1][m][n] * rs; o1[n] = x1 * c - x2 * s; o2[n] = x2 * c + x1 * s; sq += dot4(o1[n]) + dot4(o2[n]); }
;                 sq += shx<16>(sq, fr | (fq << 4)); sq += shx<32>(sq, fr | (fq << 4)); mxp[0] = __builtin_fmaxf(mxp[0], sq);
;                 store8_bf16(Q + (size_t)row * 3072 + head * 192 + 128 + 8 * fq, o1[0], o1[1]); store8_bf16(Q + (size_t)row * 3072 + head * 192 + 160 + 8 * fq, o2[0], o2[1]);
;             } }
.LBB0_906:
	s_nop 1
	v_or_b32_e32 v98, 32, v156
	v_ashrrev_i32_e32 v99, 31, v98
	v_lshl_add_u64 v[96:97], v[98:99], 2, s[22:23]
	s_nop 0
	s_mov_b64 s[54:55], -1
	s_and_b64 vcc, exec, s[8:9]
	v_max_f32_e32 v97, v115, v115
	s_waitcnt vmcnt(9)
	v_mov_b32_e32 v96, v218
	v_fmamk_f32 v96, v96, 0x3aaaaaab, v170
	v_rsq_f32_e32 v96, v96
	s_nop 0
	v_mul_f32_e32 v96, 0x3dd53b95, v96
	s_cbranch_vccnz .LBB0_908
	v_lshlrev_b32_e32 v99, 7, v98
	v_and_b32_e32 v108, 0xff780, v99
	v_mov_b32_e32 v109, v137
	v_lshl_add_u64 v[104:105], v[144:145], 0, v[108:109]
	global_load_dwordx4 v[100:103], v[104:105], off
	s_nop 0
	global_load_dwordx4 v[104:107], v[104:105], off offset:16
	v_lshl_add_u64 v[112:113], v[142:143], 0, v[108:109]
	global_load_dwordx4 v[108:111], v[112:113], off
	s_nop 0
	global_load_dwordx4 v[112:115], v[112:113], off offset:16
	v_pk_mul_f32 v[116:117], v[94:95], v[96:97] op_sel_hi:[1,0]
	v_pk_mul_f32 v[118:119], v[92:93], v[96:97] op_sel_hi:[1,0]
	v_pk_mul_f32 v[120:121], v[86:87], v[96:97] op_sel_hi:[1,0]
	v_pk_mul_f32 v[122:123], v[84:85], v[96:97] op_sel_hi:[1,0]
	v_pk_mul_f32 v[124:125], v[90:91], v[96:97] op_sel_hi:[1,0]
	v_pk_mul_f32 v[126:127], v[88:89], v[96:97] op_sel_hi:[1,0]
	v_pk_mul_f32 v[172:173], v[82:83], v[96:97] op_sel_hi:[1,0]
	v_pk_mul_f32 v[174:175], v[80:81], v[96:97] op_sel_hi:[1,0]
	v_mov_b64_e32 v[176:177], s[42:43]
	v_mad_i64_i32 v[176:177], s[46:47], v98, s67, v[176:177]
	v_mov_b32_e32 v155, v137
	v_lshl_add_u64 v[176:177], s[10:11], 1, v[176:177]
	v_lshl_add_u64 v[176:177], v[176:177], 0, v[154:155]
	s_mov_b64 s[54:55], 0
	s_waitcnt vmcnt(3)
	v_pk_mul_f32 v[178:179], v[120:121], v[102:103]
	v_pk_mul_f32 v[180:181], v[122:123], v[100:101]
	v_pk_mul_f32 v[102:103], v[116:117], v[102:103]
	v_pk_mul_f32 v[100:101], v[118:119], v[100:101]
	s_waitcnt vmcnt(2)
	v_pk_mul_f32 v[182:183], v[172:173], v[106:107]
	v_pk_mul_f32 v[184:185], v[174:175], v[104:105]
	v_pk_mul_f32 v[106:107], v[124:125], v[106:107]
	v_pk_mul_f32 v[104:105], v[126:127], v[104:105]
	s_waitcnt vmcnt(1)
	v_pk_fma_f32 v[116:117], v[116:117], v[110:111], v[178:179] neg_lo:[0,0,1] neg_hi:[0,0,1]
	v_pk_fma_f32 v[118:119], v[118:119], v[108:109], v[180:181] neg_lo:[0,0,1] neg_hi:[0,0,1]
	v_pk_fma_f32 v[110:111], v[120:121], v[110:111], v[102:103]
	v_pk_fma_f32 v[108:109], v[122:123], v[108:109], v[100:101]
	s_waitcnt vmcnt(0)
	v_pk_fma_f32 v[120:121], v[124:125], v[114:115], v[182:183] neg_lo:[0,0,1] neg_hi:[0,0,1]
	v_pk_fma_f32 v[102:103], v[126:127], v[112:113], v[184:185] neg_lo:[0,0,1] neg_hi:[0,0,1]
	v_pk_fma_f32 v[114:115], v[172:173], v[114:115], v[106:107]
	v_pk_fma_f32 v[106:107], v[174:175], v[112:113], v[104:105]
	v_mov_b32_e32 v112, v119
	v_mov_b32_e32 v113, v103
	v_mov_b32_e32 v124, v117
	v_mov_b32_e32 v125, v121
	v_mov_b32_e32 v172, v109
	v_mov_b32_e32 v173, v107
	v_mov_b32_e32 v178, v111
	v_mov_b32_e32 v179, v115
	v_mov_b32_e32 v104, v118
	v_mov_b32_e32 v105, v102
	v_mov_b32_e32 v122, v116
	v_mov_b32_e32 v123, v120
	v_mov_b32_e32 v126, v108
	v_mov_b32_e32 v127, v106
	v_mov_b32_e32 v174, v110
	v_mov_b32_e32 v175, v114
	v_cvt_pk_bf16_f32 v100, v118, v119
	v_cvt_pk_bf16_f32 v101, v116, v117
	v_pk_mul_f32 v[112:113], v[112:113], v[112:113]
	v_pk_mul_f32 v[116:117], v[124:125], v[124:125]
	v_pk_mul_f32 v[118:119], v[172:173], v[172:173]
	v_pk_mul_f32 v[124:125], v[178:179], v[178:179]
	v_pk_fma_f32 v[104:105], v[104:105], v[104:105], v[112:113]
	v_pk_fma_f32 v[112:113], v[122:123], v[122:123], v[116:117]
	v_pk_fma_f32 v[116:117], v[126:127], v[126:127], v[118:119]
	v_pk_fma_f32 v[118:119], v[174:175], v[174:175], v[124:125]
	v_pk_add_f32 v[104:105], v[104:105], v[112:113]
	v_pk_add_f32 v[112:113], v[116:117], v[118:119]
	v_cvt_pk_bf16_f32 v102, v102, v103
	v_pk_add_f32 v[104:105], v[104:105], v[112:113]
	v_cvt_pk_bf16_f32 v103, v120, v121
	v_add_f32_e32 v99, v104, v105
	ds_bpermute_b32 v112, v161, v99
	v_cvt_pk_bf16_f32 v104, v108, v109
	v_cvt_pk_bf16_f32 v105, v110, v111
	v_cvt_pk_bf16_f32 v106, v106, v107
	v_cvt_pk_bf16_f32 v107, v114, v115
	s_waitcnt lgkmcnt(0)
	v_add_f32_e32 v99, v99, v112
	ds_bpermute_b32 v108, v162, v99
	global_store_dwordx4 v[176:177], v[100:103], off offset:256
	global_store_dwordx4 v[176:177], v[104:107], off offset:320
	s_waitcnt lgkmcnt(0)
	v_add_f32_e32 v99, v99, v108
	v_max_f32_e32 v99, v97, v99

; template <int MASK> DI float shx(float v, int lane) { return __builtin_bit_cast(float, __builtin_amdgcn_ds_bpermute((lane ^ MASK) << 2, __builtin_bit_cast(int, v))); }
; DI float dot4(f32x4 v) { return (v[0] * v[0] + v[1] * v[1]) + (v[2] * v[2] + v[3] * v[3]); }
; #define FOR_ROWS _Pragma("unroll") for (int ai = 0; ai < 2; ++ai) _Pragma("unroll") for (int m = 0; m < 4; ++m)
; #define FOR_BJ _Pragma("unroll") for (int bj = 0; bj < 2; ++bj)
;     DI void operator()(AccRef acc, const Unit& u, int wr, int wc, int fr, int fq) const {
;     ...
;         FOR_ROWS { const int row = row0 + ai * 128 + m * 16; const float rs = __builtin_amdgcn_rsqf(ssq_q[row] * (1.0f / 768.0f) + EPS) * QSCALE_MLA;
;             if (pn < 8) {
;                 FOR_BJ { const f32x4 v0 = acc[ai][bj][m][0] * rs, v1 = acc[ai][bj][m][1] * rs; float sq = dot4(v0) + dot4(v1);
;                     sq += shx<16>(sq, fr | (fq << 4)); sq += shx<32>(sq, fr | (fq << 4)); mxp[bj] = __builtin_fmaxf(mxp[bj], sq);
;                     store8_bf16(Q + (size_t)row * 3072 + (2 * pn + bj) * 192 + c8, v0, v1); }
;             } else {
;                 const int head = 4 * (pn - 8) + wc, pos = row & (SEQ - 1);
;                 f32x4 o1[2], o2[2]; float sq = 0.f;
; #pragma unroll
;                 for (int n = 0; n < 2; ++n) { const f32x4 c = *(const f32x4*)(rcos + pos * 32 + 8 * fq + 4 * n), s = *(const f32x4*)(rsin + pos * 32 + 8 * fq + 4 * n);
;                     const f32x4 x1 = acc[ai][0][m][n] * rs, x2 = acc[ai][1][m][n] * rs; o1[n] = x1 * c - x2 * s; o2[n] = x2 * c + x1 * s; sq += dot4(o1[n]) + dot4(o2[n]); }
;                 sq += shx<16>(sq, fr | (fq << 4)); sq += shx<32>(sq, fr | (fq << 4)); mxp[0] = __builtin_fmaxf(mxp[0], sq);
;                 store8_bf16(Q + (size_t)row * 3072 + head * 192 + 128 + 8 * fq, o1[0], o1[1]); store8_bf16(Q + (size_t)row * 3072 + head * 192 + 160 + 8 * fq, o2[0], o2[1]);
;             } }
.LBB0_910:
	s_nop 1
	v_or_b32_e32 v82, 48, v156
	v_ashrrev_i32_e32 v83, 31, v82
	v_lshl_add_u64 v[80:81], v[82:83], 2, s[22:23]
	s_nop 0
	s_mov_b64 s[54:55], -1
	s_and_b64 vcc, exec, s[8:9]
	v_max_f32_e32 v81, v99, v99
	s_waitcnt vmcnt(10)
	v_mov_b32_e32 v80, v219
	v_fmamk_f32 v80, v80, 0x3aaaaaab, v170
	v_rsq_f32_e32 v80, v80
	s_nop 0
	v_mul_f32_e32 v80, 0x3dd53b95, v80
	s_cbranch_vccnz .LBB0_912
	v_lshlrev_b32_e32 v83, 7, v82
	v_and_b32_e32 v92, 0xfff80, v83
	v_mov_b32_e32 v93, v137
	v_lshl_add_u64 v[88:89], v[144:145], 0, v[92:93]
	global_load_dwordx4 v[84:87], v[88:89], off
	s_nop 0
	global_load_dwordx4 v[88:91], v[88:89], off offset:16
	v_lshl_add_u64 v[96:97], v[142:143], 0, v[92:93]
	global_load_dwordx4 v[92:95], v[96:97], off
	s_nop 0
	global_load_dwordx4 v[96:99], v[96:97], off offset:16
	v_pk_mul_f32 v[100:101], v[78:79], v[80:81] op_sel_hi:[1,0]
	v_pk_mul_f32 v[102:103], v[76:77], v[80:81] op_sel_hi:[1,0]
	v_pk_mul_f32 v[104:105], v[70:71], v[80:81] op_sel_hi:[1,0]
	v_pk_mul_f32 v[106:107], v[68:69], v[80:81] op_sel_hi:[1,0]
	v_pk_mul_f32 v[108:109], v[74:75], v[80:81] op_sel_hi:[1,0]
	v_pk_mul_f32 v[110:111], v[72:73], v[80:81] op_sel_hi:[1,0]
	v_pk_mul_f32 v[112:113], v[66:67], v[80:81] op_sel_hi:[1,0]
	v_pk_mul_f32 v[114:115], v[64:65], v[80:81] op_sel_hi:[1,0]
	v_mov_b64_e32 v[116:117], s[42:43]
	v_mad_i64_i32 v[116:117], s[46:47], v82, s67, v[116:117]
	v_mov_b32_e32 v155, v137
	v_lshl_add_u64 v[116:117], s[10:11], 1, v[116:117]
	v_lshl_add_u64 v[116:117], v[116:117], 0, v[154:155]
	s_mov_b64 s[54:55], 0
	s_waitcnt vmcnt(3)
	v_pk_mul_f32 v[118:119], v[104:105], v[86:87]
	v_pk_mul_f32 v[120:121], v[106:107], v[84:85]
	v_pk_mul_f32 v[86:87], v[100:101], v[86:87]
	v_pk_mul_f32 v[84:85], v[102:103], v[84:85]
	s_waitcnt vmcnt(2)
	v_pk_mul_f32 v[122:123], v[112:113], v[90:91]
	v_pk_mul_f32 v[124:125], v[114:115], v[88:89]
	v_pk_mul_f32 v[90:91], v[108:109], v[90:91]
	v_pk_mul_f32 v[88:89], v[110:111], v[88:89]
	s_waitcnt vmcnt(1)
	v_pk_fma_f32 v[100:101], v[100:101], v[94:95], v[118:119] neg_lo:[0,0,1] neg_hi:[0,0,1]
	v_pk_fma_f32 v[102:103], v[102:103], v[92:93], v[120:121] neg_lo:[0,0,1] neg_hi:[0,0,1]
	v_pk_fma_f32 v[94:95], v[104:105], v[94:95], v[86:87]
	v_pk_fma_f32 v[92:93], v[106:107], v[92:93], v[84:85]
	s_waitcnt vmcnt(0)
	v_pk_fma_f32 v[104:105], v[108:109], v[98:99], v[122:123] neg_lo:[0,0,1] neg_hi:[0,0,1]
	v_pk_fma_f32 v[86:87], v[110:111], v[96:97], v[124:125] neg_lo:[0,0,1] neg_hi:[0,0,1]
	v_pk_fma_f32 v[98:99], v[112:113], v[98:99], v[90:91]
	v_pk_fma_f32 v[90:91], v[114:115], v[96:97], v[88:89]
	v_mov_b32_e32 v96, v103
	v_mov_b32_e32 v97, v87
	v_mov_b32_e32 v108, v101
	v_mov_b32_e32 v109, v105
	v_mov_b32_e32 v112, v93
	v_mov_b32_e32 v113, v91
	v_mov_b32_e32 v118, v95
	v_mov_b32_e32 v119, v99
	v_mov_b32_e32 v88, v102
	v_mov_b32_e32 v89, v86
	v_mov_b32_e32 v106, v100
	v_mov_b32_e32 v107, v104
	v_mov_b32_e32 v110, v92
	v_mov_b32_e32 v111, v90
	v_mov_b32_e32 v114, v94
	v_mov_b32_e32 v115, v98
	v_cvt_pk_bf16_f32 v84, v102, v103
	v_cvt_pk_bf16_f32 v85, v100, v101
	v_pk_mul_f32 v[96:97], v[96:97], v[96:97]
	v_pk_mul_f32 v[100:101], v[108:109], v[108:109]
	v_pk_mul_f32 v[102:103], v[112:113], v[112:113]
	v_pk_mul_f32 v[108:109], v[118:119], v[118:119]
	v_pk_fma_f32 v[88:89], v[88:89], v[88:89], v[96:97]
	v_pk_fma_f32 v[96:97], v[106:107], v[106:107], v[100:101]
	v_pk_fma_f32 v[100:101], v[110:111], v[110:111], v[102:103]
	v_pk_fma_f32 v[102:103], v[114:115], v[114:115], v[108:109]
	v_pk_add_f32 v[88:89], v[88:89], v[96:97]
	v_pk_add_f32 v[96:97], v[100:101], v[102:103]
	v_cvt_pk_bf16_f32 v86, v86, v87
	v_pk_add_f32 v[88:89], v[88:89], v[96:97]
	v_cvt_pk_bf16_f32 v87, v104, v105
	v_add_f32_e32 v83, v88, v89
	ds_bpermute_b32 v96, v161, v83
	v_cvt_pk_bf16_f32 v88, v92, v93
	v_cvt_pk_bf16_f32 v89, v94, v95
	v_cvt_pk_bf16_f32 v90, v90, v91
	v_cvt_pk_bf16_f32 v91, v98, v99
	s_waitcnt lgkmcnt(0)
	v_add_f32_e32 v83, v83, v96
	ds_bpermute_b32 v92, v162, v83
	global_store_dwordx4 v[116:117], v[84:87], off offset:256
	global_store_dwordx4 v[116:117], v[88:91], off offset:320
	s_waitcnt lgkmcnt(0)
	v_add_f32_e32 v83, v83, v92
	v_max_f32_e32 v83, v81, v83

; template <int MASK> DI float shx(float v, int lane) { return __builtin_bit_cast(float, __builtin_amdgcn_ds_bpermute((lane ^ MASK) << 2, __builtin_bit_cast(int, v))); }
; DI float dot4(f32x4 v) { return (v[0] * v[0] + v[1] * v[1]) + (v[2] * v[2] + v[3] * v[3]); }
; #define FOR_ROWS _Pragma("unroll") for (int ai = 0; ai < 2; ++ai) _Pragma("unroll") for (int m = 0; m < 4; ++m)
; #define FOR_BJ _Pragma("unroll") for (int bj = 0; bj < 2; ++bj)
;     DI void operator()(AccRef acc, const Unit& u, int wr, int wc, int fr, int fq) const {
;     ...
;         FOR_ROWS { const int row = row0 + ai * 128 + m * 16; const float rs = __builtin_amdgcn_rsqf(ssq_q[row] * (1.0f / 768.0f) + EPS) * QSCALE_MLA;
;             if (pn < 8) {
;                 FOR_BJ { const f32x4 v0 = acc[ai][bj][m][0] * rs, v1 = acc[ai][bj][m][1] * rs; float sq = dot4(v0) + dot4(v1);
;                     sq += shx<16>(sq, fr | (fq << 4)); sq += shx<32>(sq, fr | (fq << 4)); mxp[bj] = __builtin_fmaxf(mxp[bj], sq);
;                     store8_bf16(Q + (size_t)row * 3072 + (2 * pn + bj) * 192 + c8, v0, v1); }
;             } else {
;                 const int head = 4 * (pn - 8) + wc, pos = row & (SEQ - 1);
;                 f32x4 o1[2], o2[2]; float sq = 0.f;
; #pragma unroll
;                 for (int n = 0; n < 2; ++n) { const f32x4 c = *(const f32x4*)(rcos + pos * 32 + 8 * fq + 4 * n), s = *(const f32x4*)(rsin + pos * 32 + 8 * fq + 4 * n);
;                     const f32x4 x1 = acc[ai][0][m][n] * rs, x2 = acc[ai][1][m][n] * rs; o1[n] = x1 * c - x2 * s; o2[n] = x2 * c + x1 * s; sq += dot4(o1[n]) + dot4(o2[n]); }
;                 sq += shx<16>(sq, fr | (fq << 4)); sq += shx<32>(sq, fr | (fq << 4)); mxp[0] = __builtin_fmaxf(mxp[0], sq);
;                 store8_bf16(Q + (size_t)row * 3072 + head * 192 + 128 + 8 * fq, o1[0], o1[1]); store8_bf16(Q + (size_t)row * 3072 + head * 192 + 160 + 8 * fq, o2[0], o2[1]);
;             } }
.LBB0_914:
	s_nop 0
	s_nop 0
	v_add_u32_e32 v65, 0x80, v156
	s_mov_b64 s[54:55], -1
	s_and_b64 vcc, exec, s[8:9]
	v_max_f32_e32 v66, v83, v83
	s_waitcnt vmcnt(11)
	v_mov_b32_e32 v64, v220
	v_fmamk_f32 v64, v64, 0x3aaaaaab, v170
	v_rsq_f32_e32 v64, v64
	s_nop 0
	v_mul_f32_e32 v64, 0x3dd53b95, v64
	s_cbranch_vccnz .LBB0_916
	v_lshlrev_b32_e32 v67, 7, v65
	v_and_b32_e32 v76, 0xfe780, v67
	v_mov_b32_e32 v77, v137
	v_lshl_add_u64 v[72:73], v[144:145], 0, v[76:77]
	global_load_dwordx4 v[68:71], v[72:73], off
	s_nop 0
	global_load_dwordx4 v[72:75], v[72:73], off offset:16
	v_lshl_add_u64 v[80:81], v[142:143], 0, v[76:77]
	global_load_dwordx4 v[76:79], v[80:81], off
	s_nop 0
	global_load_dwordx4 v[80:83], v[80:81], off offset:16
	v_pk_mul_f32 v[84:85], v[62:63], v[64:65] op_sel_hi:[1,0]
	v_pk_mul_f32 v[86:87], v[60:61], v[64:65] op_sel_hi:[1,0]
	v_pk_mul_f32 v[88:89], v[54:55], v[64:65] op_sel_hi:[1,0]
	v_pk_mul_f32 v[90:91], v[52:53], v[64:65] op_sel_hi:[1,0]
	v_pk_mul_f32 v[92:93], v[58:59], v[64:65] op_sel_hi:[1,0]
	v_pk_mul_f32 v[94:95], v[56:57], v[64:65] op_sel_hi:[1,0]
	v_pk_mul_f32 v[96:97], v[50:51], v[64:65] op_sel_hi:[1,0]
	v_pk_mul_f32 v[98:99], v[48:49], v[64:65] op_sel_hi:[1,0]
	v_mov_b64_e32 v[100:101], s[42:43]
	v_mad_i64_i32 v[100:101], s[46:47], v65, s67, v[100:101]
	v_mov_b32_e32 v155, v137
	v_lshl_add_u64 v[100:101], s[10:11], 1, v[100:101]
	v_lshl_add_u64 v[100:101], v[100:101], 0, v[154:155]
	s_mov_b64 s[54:55], 0
	s_waitcnt vmcnt(3)
	v_pk_mul_f32 v[102:103], v[88:89], v[70:71]
	v_pk_mul_f32 v[104:105], v[90:91], v[68:69]
	v_pk_mul_f32 v[70:71], v[84:85], v[70:71]
	v_pk_mul_f32 v[68:69], v[86:87], v[68:69]
	s_waitcnt vmcnt(2)
	v_pk_mul_f32 v[106:107], v[96:97], v[74:75]
	v_pk_mul_f32 v[108:109], v[98:99], v[72:73]
	v_pk_mul_f32 v[74:75], v[92:93], v[74:75]
	v_pk_mul_f32 v[72:73], v[94:95], v[72:73]
	s_waitcnt vmcnt(1)
	v_pk_fma_f32 v[84:85], v[84:85], v[78:79], v[102:103] neg_lo:[0,0,1] neg_hi:[0,0,1]
	v_pk_fma_f32 v[86:87], v[86:87], v[76:77], v[104:105] neg_lo:[0,0,1] neg_hi:[0,0,1]
	v_pk_fma_f32 v[78:79], v[88:89], v[78:79], v[70:71]
	v_pk_fma_f32 v[76:77], v[90:91], v[76:77], v[68:69]
	s_waitcnt vmcnt(0)
	v_pk_fma_f32 v[88:89], v[92:93], v[82:83], v[106:107] neg_lo:[0,0,1] neg_hi:[0,0,1]
	v_pk_fma_f32 v[70:71], v[94:95], v[80:81], v[108:109] neg_lo:[0,0,1] neg_hi:[0,0,1]
	v_pk_fma_f32 v[82:83], v[96:97], v[82:83], v[74:75]
	v_pk_fma_f32 v[74:75], v[98:99], v[80:81], v[72:73]
	v_mov_b32_e32 v80, v87
	v_mov_b32_e32 v81, v71
	v_mov_b32_e32 v92, v85
	v_mov_b32_e32 v93, v89
	v_mov_b32_e32 v96, v77
	v_mov_b32_e32 v97, v75
	v_mov_b32_e32 v102, v79
	v_mov_b32_e32 v103, v83
	v_mov_b32_e32 v72, v86
	v_mov_b32_e32 v73, v70
	v_mov_b32_e32 v90, v84
	v_mov_b32_e32 v91, v88
	v_mov_b32_e32 v94, v76
	v_mov_b32_e32 v95, v74
	v_mov_b32_e32 v98, v78
	v_mov_b32_e32 v99, v82
	v_cvt_pk_bf16_f32 v68, v86, v87
	v_cvt_pk_bf16_f32 v69, v84, v85
	v_pk_mul_f32 v[80:81], v[80:81], v[80:81]
	v_pk_mul_f32 v[84:85], v[92:93], v[92:93]
	v_pk_mul_f32 v[86:87], v[96:97], v[96:97]
	v_pk_mul_f32 v[92:93], v[102:103], v[102:103]
	v_pk_fma_f32 v[72:73], v[72:73], v[72:73], v[80:81]
	v_pk_fma_f32 v[80:81], v[90:91], v[90:91], v[84:85]
	v_pk_fma_f32 v[84:85], v[94:95], v[94:95], v[86:87]
	v_pk_fma_f32 v[86:87], v[98:99], v[98:99], v[92:93]
	v_pk_add_f32 v[72:73], v[72:73], v[80:81]
	v_pk_add_f32 v[80:81], v[84:85], v[86:87]
	v_cvt_pk_bf16_f32 v70, v70, v71
	v_pk_add_f32 v[72:73], v[72:73], v[80:81]
	v_cvt_pk_bf16_f32 v71, v88, v89
	v_add_f32_e32 v67, v72, v73
	ds_bpermute_b32 v80, v161, v67
	v_cvt_pk_bf16_f32 v72, v76, v77
	v_cvt_pk_bf16_f32 v73, v78, v79
	v_cvt_pk_bf16_f32 v74, v74, v75
	v_cvt_pk_bf16_f32 v75, v82, v83
	s_waitcnt lgkmcnt(0)
	v_add_f32_e32 v67, v67, v80
	ds_bpermute_b32 v76, v162, v67
	global_store_dwordx4 v[100:101], v[68:71], off offset:256
	global_store_dwordx4 v[100:101], v[72:75], off offset:320
	s_waitcnt lgkmcnt(0)
	v_add_f32_e32 v67, v67, v76
	v_max_f32_e32 v67, v66, v67

; template <int MASK> DI float shx(float v, int lane) { return __builtin_bit_cast(float, __builtin_amdgcn_ds_bpermute((lane ^ MASK) << 2, __builtin_bit_cast(int, v))); }
; DI float dot4(f32x4 v) { return (v[0] * v[0] + v[1] * v[1]) + (v[2] * v[2] + v[3] * v[3]); }
; #define FOR_ROWS _Pragma("unroll") for (int ai = 0; ai < 2; ++ai) _Pragma("unroll") for (int m = 0; m < 4; ++m)
; #define FOR_BJ _Pragma("unroll") for (int bj = 0; bj < 2; ++bj)
;     DI void operator()(AccRef acc, const Unit& u, int wr, int wc, int fr, int fq) const {
;     ...
;         FOR_ROWS { const int row = row0 + ai * 128 + m * 16; const float rs = __builtin_amdgcn_rsqf(ssq_q[row] * (1.0f / 768.0f) + EPS) * QSCALE_MLA;
;             if (pn < 8) {
;                 FOR_BJ { const f32x4 v0 = acc[ai][bj][m][0] * rs, v1 = acc[ai][bj][m][1] * rs; float sq = dot4(v0) + dot4(v1);
;                     sq += shx<16>(sq, fr | (fq << 4)); sq += shx<32>(sq, fr | (fq << 4)); mxp[bj] = __builtin_fmaxf(mxp[bj], sq);
;                     store8_bf16(Q + (size_t)row * 3072 + (2 * pn + bj) * 192 + c8, v0, v1); }
;             } else {
;                 const int head = 4 * (pn - 8) + wc, pos = row & (SEQ - 1);
;                 f32x4 o1[2], o2[2]; float sq = 0.f;
; #pragma unroll
;                 for (int n = 0; n < 2; ++n) { const f32x4 c = *(const f32x4*)(rcos + pos * 32 + 8 * fq + 4 * n), s = *(const f32x4*)(rsin + pos * 32 + 8 * fq + 4 * n);
;                     const f32x4 x1 = acc[ai][0][m][n] * rs, x2 = acc[ai][1][m][n] * rs; o1[n] = x1 * c - x2 * s; o2[n] = x2 * c + x1 * s; sq += dot4(o1[n]) + dot4(o2[n]); }
;                 sq += shx<16>(sq, fr | (fq << 4)); sq += shx<32>(sq, fr | (fq << 4)); mxp[0] = __builtin_fmaxf(mxp[0], sq);
;                 store8_bf16(Q + (size_t)row * 3072 + head * 192 + 128 + 8 * fq, o1[0], o1[1]); store8_bf16(Q + (size_t)row * 3072 + head * 192 + 160 + 8 * fq, o2[0], o2[1]);
;             } }
.LBB0_918:
	s_nop 0
	s_nop 0
	v_add_u32_e32 v49, 0x90, v156
	s_mov_b64 s[54:55], -1
	s_and_b64 vcc, exec, s[8:9]
	v_max_f32_e32 v50, v67, v67
	s_waitcnt vmcnt(12)
	v_mov_b32_e32 v48, v221
	v_fmamk_f32 v48, v48, 0x3aaaaaab, v170
	v_rsq_f32_e32 v48, v48
	s_nop 0
	v_mul_f32_e32 v48, 0x3dd53b95, v48
	s_cbranch_vccnz .LBB0_920
	v_lshlrev_b32_e32 v51, 7, v49
	v_and_b32_e32 v60, 0xfef80, v51
	v_mov_b32_e32 v61, v137
	v_lshl_add_u64 v[56:57], v[144:145], 0, v[60:61]
	global_load_dwordx4 v[52:55], v[56:57], off
	s_nop 0
	global_load_dwordx4 v[56:59], v[56:57], off offset:16
	v_lshl_add_u64 v[64:65], v[142:143], 0, v[60:61]
	global_load_dwordx4 v[60:63], v[64:65], off
	s_nop 0
	global_load_dwordx4 v[64:67], v[64:65], off offset:16
	v_pk_mul_f32 v[68:69], v[46:47], v[48:49] op_sel_hi:[1,0]
	v_pk_mul_f32 v[70:71], v[44:45], v[48:49] op_sel_hi:[1,0]
	v_pk_mul_f32 v[72:73], v[38:39], v[48:49] op_sel_hi:[1,0]
	v_pk_mul_f32 v[74:75], v[36:37], v[48:49] op_sel_hi:[1,0]
	v_pk_mul_f32 v[76:77], v[42:43], v[48:49] op_sel_hi:[1,0]
	v_pk_mul_f32 v[78:79], v[40:41], v[48:49] op_sel_hi:[1,0]
	v_pk_mul_f32 v[80:81], v[34:35], v[48:49] op_sel_hi:[1,0]
	v_pk_mul_f32 v[82:83], v[32:33], v[48:49] op_sel_hi:[1,0]
	v_mov_b64_e32 v[84:85], s[42:43]
	v_mad_i64_i32 v[84:85], s[46:47], v49, s67, v[84:85]
	v_mov_b32_e32 v155, v137
	v_lshl_add_u64 v[84:85], s[10:11], 1, v[84:85]
	v_lshl_add_u64 v[84:85], v[84:85], 0, v[154:155]
	s_mov_b64 s[54:55], 0
	s_waitcnt vmcnt(3)
	v_pk_mul_f32 v[86:87], v[72:73], v[54:55]
	v_pk_mul_f32 v[88:89], v[74:75], v[52:53]
	v_pk_mul_f32 v[54:55], v[68:69], v[54:55]
	v_pk_mul_f32 v[52:53], v[70:71], v[52:53]
	s_waitcnt vmcnt(2)
	v_pk_mul_f32 v[90:91], v[80:81], v[58:59]
	v_pk_mul_f32 v[92:93], v[82:83], v[56:57]
	v_pk_mul_f32 v[58:59], v[76:77], v[58:59]
	v_pk_mul_f32 v[56:57], v[78:79], v[56:57]
	s_waitcnt vmcnt(1)
	v_pk_fma_f32 v[68:69], v[68:69], v[62:63], v[86:87] neg_lo:[0,0,1] neg_hi:[0,0,1]
	v_pk_fma_f32 v[70:71], v[70:71], v[60:61], v[88:89] neg_lo:[0,0,1] neg_hi:[0,0,1]
	v_pk_fma_f32 v[62:63], v[72:73], v[62:63], v[54:55]
	v_pk_fma_f32 v[60:61], v[74:75], v[60:61], v[52:53]
	s_waitcnt vmcnt(0)
	v_pk_fma_f32 v[72:73], v[76:77], v[66:67], v[90:91] neg_lo:[0,0,1] neg_hi:[0,0,1]
	v_pk_fma_f32 v[54:55], v[78:79], v[64:65], v[92:93] neg_lo:[0,0,1] neg_hi:[0,0,1]
	v_pk_fma_f32 v[66:67], v[80:81], v[66:67], v[58:59]
	v_pk_fma_f32 v[58:59], v[82:83], v[64:65], v[56:57]
	v_mov_b32_e32 v64, v71
	v_mov_b32_e32 v65, v55
	v_mov_b32_e32 v76, v69
	v_mov_b32_e32 v77, v73
	v_mov_b32_e32 v80, v61
	v_mov_b32_e32 v81, v59
	v_mov_b32_e32 v86, v63
	v_mov_b32_e32 v87, v67
	v_mov_b32_e32 v56, v70
	v_mov_b32_e32 v57, v54
	v_mov_b32_e32 v74, v68
	v_mov_b32_e32 v75, v72
	v_mov_b32_e32 v78, v60
	v_mov_b32_e32 v79, v58
	v_mov_b32_e32 v82, v62
	v_mov_b32_e32 v83, v66
	v_cvt_pk_bf16_f32 v52, v70, v71
	v_cvt_pk_bf16_f32 v53, v68, v69
	v_pk_mul_f32 v[64:65], v[64:65], v[64:65]
	v_pk_mul_f32 v[68:69], v[76:77], v[76:77]
	v_pk_mul_f32 v[70:71], v[80:81], v[80:81]
	v_pk_mul_f32 v[76:77], v[86:87], v[86:87]
	v_pk_fma_f32 v[56:57], v[56:57], v[56:57], v[64:65]
	v_pk_fma_f32 v[64:65], v[74:75], v[74:75], v[68:69]
	v_pk_fma_f32 v[68:69], v[78:79], v[78:79], v[70:71]
	v_pk_fma_f32 v[70:71], v[82:83], v[82:83], v[76:77]
	v_pk_add_f32 v[56:57], v[56:57], v[64:65]
	v_pk_add_f32 v[64:65], v[68:69], v[70:71]
	v_cvt_pk_bf16_f32 v54, v54, v55
	v_pk_add_f32 v[56:57], v[56:57], v[64:65]
	v_cvt_pk_bf16_f32 v55, v72, v73
	v_add_f32_e32 v51, v56, v57
	ds_bpermute_b32 v64, v161, v51
	v_cvt_pk_bf16_f32 v56, v60, v61
	v_cvt_pk_bf16_f32 v57, v62, v63
	v_cvt_pk_bf16_f32 v58, v58, v59
	v_cvt_pk_bf16_f32 v59, v66, v67
	s_waitcnt lgkmcnt(0)
	v_add_f32_e32 v51, v51, v64
	ds_bpermute_b32 v60, v162, v51
	global_store_dwordx4 v[84:85], v[52:55], off offset:256
	global_store_dwordx4 v[84:85], v[56:59], off offset:320
	s_waitcnt lgkmcnt(0)
	v_add_f32_e32 v51, v51, v60
	v_max_f32_e32 v51, v50, v51

; template <int MASK> DI float shx(float v, int lane) { return __builtin_bit_cast(float, __builtin_amdgcn_ds_bpermute((lane ^ MASK) << 2, __builtin_bit_cast(int, v))); }
; DI float dot4(f32x4 v) { return (v[0] * v[0] + v[1] * v[1]) + (v[2] * v[2] + v[3] * v[3]); }
; #define FOR_ROWS _Pragma("unroll") for (int ai = 0; ai < 2; ++ai) _Pragma("unroll") for (int m = 0; m < 4; ++m)
; #define FOR_BJ _Pragma("unroll") for (int bj = 0; bj < 2; ++bj)
;     DI void operator()(AccRef acc, const Unit& u, int wr, int wc, int fr, int fq) const {
;     ...
;         FOR_ROWS { const int row = row0 + ai * 128 + m * 16; const float rs = __builtin_amdgcn_rsqf(ssq_q[row] * (1.0f / 768.0f) + EPS) * QSCALE_MLA;
;             if (pn < 8) {
;                 FOR_BJ { const f32x4 v0 = acc[ai][bj][m][0] * rs, v1 = acc[ai][bj][m][1] * rs; float sq = dot4(v0) + dot4(v1);
;                     sq += shx<16>(sq, fr | (fq << 4)); sq += shx<32>(sq, fr | (fq << 4)); mxp[bj] = __builtin_fmaxf(mxp[bj], sq);
;                     store8_bf16(Q + (size_t)row * 3072 + (2 * pn + bj) * 192 + c8, v0, v1); }
;             } else {
;                 const int head = 4 * (pn - 8) + wc, pos = row & (SEQ - 1);
;                 f32x4 o1[2], o2[2]; float sq = 0.f;
; #pragma unroll
;                 for (int n = 0; n < 2; ++n) { const f32x4 c = *(const f32x4*)(rcos + pos * 32 + 8 * fq + 4 * n), s = *(const f32x4*)(rsin + pos * 32 + 8 * fq + 4 * n);
;                     const f32x4 x1 = acc[ai][0][m][n] * rs, x2 = acc[ai][1][m][n] * rs; o1[n] = x1 * c - x2 * s; o2[n] = x2 * c + x1 * s; sq += dot4(o1[n]) + dot4(o2[n]); }
;                 sq += shx<16>(sq, fr | (fq << 4)); sq += shx<32>(sq, fr | (fq << 4)); mxp[0] = __builtin_fmaxf(mxp[0], sq);
;                 store8_bf16(Q + (size_t)row * 3072 + head * 192 + 128 + 8 * fq, o1[0], o1[1]); store8_bf16(Q + (size_t)row * 3072 + head * 192 + 160 + 8 * fq, o2[0], o2[1]);
;             } }
.LBB0_922:
	s_nop 0
	s_nop 0
	v_add_u32_e32 v33, 0xa0, v156
	s_mov_b64 s[54:55], -1
	s_and_b64 vcc, exec, s[8:9]
	v_max_f32_e32 v34, v51, v51
	s_waitcnt vmcnt(13)
	v_mov_b32_e32 v32, v222
	v_fmamk_f32 v32, v32, 0x3aaaaaab, v170
	v_rsq_f32_e32 v32, v32
	s_nop 0
	v_mul_f32_e32 v32, 0x3dd53b95, v32
	s_cbranch_vccnz .LBB0_924
	v_lshlrev_b32_e32 v35, 7, v33
	v_and_b32_e32 v44, 0xff780, v35
	v_mov_b32_e32 v45, v137
	v_lshl_add_u64 v[40:41], v[144:145], 0, v[44:45]
	global_load_dwordx4 v[36:39], v[40:41], off
	s_nop 0
	global_load_dwordx4 v[40:43], v[40:41], off offset:16
	v_lshl_add_u64 v[48:49], v[142:143], 0, v[44:45]
	global_load_dwordx4 v[44:47], v[48:49], off
	s_nop 0
	global_load_dwordx4 v[48:51], v[48:49], off offset:16
	v_pk_mul_f32 v[52:53], v[30:31], v[32:33] op_sel_hi:[1,0]
	v_pk_mul_f32 v[54:55], v[28:29], v[32:33] op_sel_hi:[1,0]
	v_pk_mul_f32 v[56:57], v[22:23], v[32:33] op_sel_hi:[1,0]
	v_pk_mul_f32 v[58:59], v[20:21], v[32:33] op_sel_hi:[1,0]
	v_pk_mul_f32 v[60:61], v[26:27], v[32:33] op_sel_hi:[1,0]
	v_pk_mul_f32 v[62:63], v[24:25], v[32:33] op_sel_hi:[1,0]
	v_pk_mul_f32 v[64:65], v[18:19], v[32:33] op_sel_hi:[1,0]
	v_pk_mul_f32 v[66:67], v[16:17], v[32:33] op_sel_hi:[1,0]
	v_mov_b64_e32 v[68:69], s[42:43]
	v_mad_i64_i32 v[68:69], s[46:47], v33, s67, v[68:69]
	v_mov_b32_e32 v155, v137
	v_lshl_add_u64 v[68:69], s[10:11], 1, v[68:69]
	v_lshl_add_u64 v[68:69], v[68:69], 0, v[154:155]
	s_mov_b64 s[54:55], 0
	s_waitcnt vmcnt(3)
	v_pk_mul_f32 v[70:71], v[56:57], v[38:39]
	v_pk_mul_f32 v[72:73], v[58:59], v[36:37]
	v_pk_mul_f32 v[38:39], v[52:53], v[38:39]
	v_pk_mul_f32 v[36:37], v[54:55], v[36:37]
	s_waitcnt vmcnt(2)
	v_pk_mul_f32 v[74:75], v[64:65], v[42:43]
	v_pk_mul_f32 v[76:77], v[66:67], v[40:41]
	v_pk_mul_f32 v[42:43], v[60:61], v[42:43]
	v_pk_mul_f32 v[40:41], v[62:63], v[40:41]
	s_waitcnt vmcnt(1)
	v_pk_fma_f32 v[52:53], v[52:53], v[46:47], v[70:71] neg_lo:[0,0,1] neg_hi:[0,0,1]
	v_pk_fma_f32 v[54:55], v[54:55], v[44:45], v[72:73] neg_lo:[0,0,1] neg_hi:[0,0,1]
	v_pk_fma_f32 v[46:47], v[56:57], v[46:47], v[38:39]
	v_pk_fma_f32 v[44:45], v[58:59], v[44:45], v[36:37]
	s_waitcnt vmcnt(0)
	v_pk_fma_f32 v[56:57], v[60:61], v[50:51], v[74:75] neg_lo:[0,0,1] neg_hi:[0,0,1]
	v_pk_fma_f32 v[38:39], v[62:63], v[48:49], v[76:77] neg_lo:[0,0,1] neg_hi:[0,0,1]
	v_pk_fma_f32 v[50:51], v[64:65], v[50:51], v[42:43]
	v_pk_fma_f32 v[42:43], v[66:67], v[48:49], v[40:41]
	v_mov_b32_e32 v48, v55
	v_mov_b32_e32 v49, v39
	v_mov_b32_e32 v60, v53
	v_mov_b32_e32 v61, v57
	v_mov_b32_e32 v64, v45
	v_mov_b32_e32 v65, v43
	v_mov_b32_e32 v70, v47
	v_mov_b32_e32 v71, v51
	v_mov_b32_e32 v40, v54
	v_mov_b32_e32 v41, v38
	v_mov_b32_e32 v58, v52
	v_mov_b32_e32 v59, v56
	v_mov_b32_e32 v62, v44
	v_mov_b32_e32 v63, v42
	v_mov_b32_e32 v66, v46
	v_mov_b32_e32 v67, v50
	v_cvt_pk_bf16_f32 v36, v54, v55
	v_cvt_pk_bf16_f32 v37, v52, v53
	v_pk_mul_f32 v[48:49], v[48:49], v[48:49]
	v_pk_mul_f32 v[52:53], v[60:61], v[60:61]
	v_pk_mul_f32 v[54:55], v[64:65], v[64:65]
	v_pk_mul_f32 v[60:61], v[70:71], v[70:71]
	v_pk_fma_f32 v[40:41], v[40:41], v[40:41], v[48:49]
	v_pk_fma_f32 v[48:49], v[58:59], v[58:59], v[52:53]
	v_pk_fma_f32 v[52:53], v[62:63], v[62:63], v[54:55]
	v_pk_fma_f32 v[54:55], v[66:67], v[66:67], v[60:61]
	v_pk_add_f32 v[40:41], v[40:41], v[48:49]
	v_pk_add_f32 v[48:49], v[52:53], v[54:55]
	v_cvt_pk_bf16_f32 v38, v38, v39
	v_pk_add_f32 v[40:41], v[40:41], v[48:49]
	v_cvt_pk_bf16_f32 v39, v56, v57
	v_add_f32_e32 v35, v40, v41
	ds_bpermute_b32 v48, v161, v35
	v_cvt_pk_bf16_f32 v40, v44, v45
	v_cvt_pk_bf16_f32 v41, v46, v47
	v_cvt_pk_bf16_f32 v42, v42, v43
	v_cvt_pk_bf16_f32 v43, v50, v51
	s_waitcnt lgkmcnt(0)
	v_add_f32_e32 v35, v35, v48
	ds_bpermute_b32 v44, v162, v35
	global_store_dwordx4 v[68:69], v[36:39], off offset:256
	global_store_dwordx4 v[68:69], v[40:43], off offset:320
	s_waitcnt lgkmcnt(0)
	v_add_f32_e32 v35, v35, v44
	v_max_f32_e32 v35, v34, v35

; template <int MASK> DI float shx(float v, int lane) { return __builtin_bit_cast(float, __builtin_amdgcn_ds_bpermute((lane ^ MASK) << 2, __builtin_bit_cast(int, v))); }
; DI float dot4(f32x4 v) { return (v[0] * v[0] + v[1] * v[1]) + (v[2] * v[2] + v[3] * v[3]); }
; #define FOR_ROWS _Pragma("unroll") for (int ai = 0; ai < 2; ++ai) _Pragma("unroll") for (int m = 0; m < 4; ++m)
; #define FOR_BJ _Pragma("unroll") for (int bj = 0; bj < 2; ++bj)
;     DI void operator()(AccRef acc, const Unit& u, int wr, int wc, int fr, int fq) const {
;     ...
;         FOR_ROWS { const int row = row0 + ai * 128 + m * 16; const float rs = __builtin_amdgcn_rsqf(ssq_q[row] * (1.0f / 768.0f) + EPS) * QSCALE_MLA;
;             if (pn < 8) {
;                 FOR_BJ { const f32x4 v0 = acc[ai][bj][m][0] * rs, v1 = acc[ai][bj][m][1] * rs; float sq = dot4(v0) + dot4(v1);
;                     sq += shx<16>(sq, fr | (fq << 4)); sq += shx<32>(sq, fr | (fq << 4)); mxp[bj] = __builtin_fmaxf(mxp[bj], sq);
;                     store8_bf16(Q + (size_t)row * 3072 + (2 * pn + bj) * 192 + c8, v0, v1); }
;             } else {
;                 const int head = 4 * (pn - 8) + wc, pos = row & (SEQ - 1);
;                 f32x4 o1[2], o2[2]; float sq = 0.f;
; #pragma unroll
;                 for (int n = 0; n < 2; ++n) { const f32x4 c = *(const f32x4*)(rcos + pos * 32 + 8 * fq + 4 * n), s = *(const f32x4*)(rsin + pos * 32 + 8 * fq + 4 * n);
;                     const f32x4 x1 = acc[ai][0][m][n] * rs, x2 = acc[ai][1][m][n] * rs; o1[n] = x1 * c - x2 * s; o2[n] = x2 * c + x1 * s; sq += dot4(o1[n]) + dot4(o2[n]); }
;                 sq += shx<16>(sq, fr | (fq << 4)); sq += shx<32>(sq, fr | (fq << 4)); mxp[0] = __builtin_fmaxf(mxp[0], sq);
;                 store8_bf16(Q + (size_t)row * 3072 + head * 192 + 128 + 8 * fq, o1[0], o1[1]); store8_bf16(Q + (size_t)row * 3072 + head * 192 + 160 + 8 * fq, o2[0], o2[1]);
;             } }
.LBB0_926:
	s_nop 0
	s_nop 0
	v_add_u32_e32 v17, 0xb0, v156
	s_mov_b64 s[54:55], -1
	s_and_b64 vcc, exec, s[8:9]
	v_max_f32_e32 v18, v35, v35
	s_waitcnt vmcnt(14)
	v_mov_b32_e32 v16, v223
	v_fmamk_f32 v16, v16, 0x3aaaaaab, v170
	v_rsq_f32_e32 v16, v16
	s_nop 0
	v_mul_f32_e32 v16, 0x3dd53b95, v16
	s_cbranch_vccnz .LBB0_928
	v_lshlrev_b32_e32 v19, 7, v17
	v_and_b32_e32 v28, 0xfff80, v19
	v_mov_b32_e32 v29, v137
	v_lshl_add_u64 v[24:25], v[144:145], 0, v[28:29]
	global_load_dwordx4 v[20:23], v[24:25], off
	s_nop 0
	global_load_dwordx4 v[24:27], v[24:25], off offset:16
	v_lshl_add_u64 v[32:33], v[142:143], 0, v[28:29]
	global_load_dwordx4 v[28:31], v[32:33], off
	s_nop 0
	global_load_dwordx4 v[32:35], v[32:33], off offset:16
	v_pk_mul_f32 v[36:37], v[14:15], v[16:17] op_sel_hi:[1,0]
	v_pk_mul_f32 v[38:39], v[12:13], v[16:17] op_sel_hi:[1,0]
	v_pk_mul_f32 v[40:41], v[6:7], v[16:17] op_sel_hi:[1,0]
	v_pk_mul_f32 v[42:43], v[4:5], v[16:17] op_sel_hi:[1,0]
	v_pk_mul_f32 v[44:45], v[10:11], v[16:17] op_sel_hi:[1,0]
	v_pk_mul_f32 v[46:47], v[8:9], v[16:17] op_sel_hi:[1,0]
	v_pk_mul_f32 v[48:49], v[2:3], v[16:17] op_sel_hi:[1,0]
	v_pk_mul_f32 v[50:51], v[0:1], v[16:17] op_sel_hi:[1,0]
	v_mov_b64_e32 v[52:53], s[42:43]
	v_mad_i64_i32 v[52:53], s[8:9], v17, s67, v[52:53]
	v_mov_b32_e32 v155, v137
	v_lshl_add_u64 v[52:53], s[10:11], 1, v[52:53]
	v_lshl_add_u64 v[52:53], v[52:53], 0, v[154:155]
	s_mov_b64 s[54:55], 0
	s_waitcnt vmcnt(3)
	v_pk_mul_f32 v[54:55], v[40:41], v[22:23]
	v_pk_mul_f32 v[56:57], v[42:43], v[20:21]
	v_pk_mul_f32 v[22:23], v[36:37], v[22:23]
	v_pk_mul_f32 v[20:21], v[38:39], v[20:21]
	s_waitcnt vmcnt(2)
	v_pk_mul_f32 v[58:59], v[48:49], v[26:27]
	v_pk_mul_f32 v[60:61], v[50:51], v[24:25]
	v_pk_mul_f32 v[26:27], v[44:45], v[26:27]
	v_pk_mul_f32 v[24:25], v[46:47], v[24:25]
	s_waitcnt vmcnt(1)
	v_pk_fma_f32 v[36:37], v[36:37], v[30:31], v[54:55] neg_lo:[0,0,1] neg_hi:[0,0,1]
	v_pk_fma_f32 v[38:39], v[38:39], v[28:29], v[56:57] neg_lo:[0,0,1] neg_hi:[0,0,1]
	v_pk_fma_f32 v[30:31], v[40:41], v[30:31], v[22:23]
	v_pk_fma_f32 v[28:29], v[42:43], v[28:29], v[20:21]
	s_waitcnt vmcnt(0)
	v_pk_fma_f32 v[40:41], v[44:45], v[34:35], v[58:59] neg_lo:[0,0,1] neg_hi:[0,0,1]
	v_pk_fma_f32 v[22:23], v[46:47], v[32:33], v[60:61] neg_lo:[0,0,1] neg_hi:[0,0,1]
	v_pk_fma_f32 v[34:35], v[48:49], v[34:35], v[26:27]
	v_pk_fma_f32 v[26:27], v[50:51], v[32:33], v[24:25]
	v_mov_b32_e32 v32, v39
	v_mov_b32_e32 v33, v23
	v_mov_b32_e32 v44, v37
	v_mov_b32_e32 v45, v41
	v_mov_b32_e32 v48, v29
	v_mov_b32_e32 v49, v27
	v_mov_b32_e32 v54, v31
	v_mov_b32_e32 v55, v35
	v_mov_b32_e32 v24, v38
	v_mov_b32_e32 v25, v22
	v_mov_b32_e32 v42, v36
	v_mov_b32_e32 v43, v40
	v_mov_b32_e32 v46, v28
	v_mov_b32_e32 v47, v26
	v_mov_b32_e32 v50, v30
	v_mov_b32_e32 v51, v34
	v_cvt_pk_bf16_f32 v20, v38, v39
	v_cvt_pk_bf16_f32 v21, v36, v37
	v_pk_mul_f32 v[32:33], v[32:33], v[32:33]
	v_pk_mul_f32 v[36:37], v[44:45], v[44:45]
	v_pk_mul_f32 v[38:39], v[48:49], v[48:49]
	v_pk_mul_f32 v[44:45], v[54:55], v[54:55]
	v_pk_fma_f32 v[24:25], v[24:25], v[24:25], v[32:33]
	v_pk_fma_f32 v[32:33], v[42:43], v[42:43], v[36:37]
	v_pk_fma_f32 v[36:37], v[46:47], v[46:47], v[38:39]
	v_pk_fma_f32 v[38:39], v[50:51], v[50:51], v[44:45]
	v_pk_add_f32 v[24:25], v[24:25], v[32:33]
	v_pk_add_f32 v[32:33], v[36:37], v[38:39]
	v_cvt_pk_bf16_f32 v22, v22, v23
	v_pk_add_f32 v[24:25], v[24:25], v[32:33]
	v_cvt_pk_bf16_f32 v23, v40, v41
	v_add_f32_e32 v19, v24, v25
	ds_bpermute_b32 v32, v161, v19
	v_cvt_pk_bf16_f32 v24, v28, v29
	v_cvt_pk_bf16_f32 v25, v30, v31
	v_cvt_pk_bf16_f32 v26, v26, v27
	v_cvt_pk_bf16_f32 v27, v34, v35
	s_waitcnt lgkmcnt(0)
	v_add_f32_e32 v19, v19, v32
	ds_bpermute_b32 v28, v162, v19
	global_store_dwordx4 v[52:53], v[20:23], off offset:256
	global_store_dwordx4 v[52:53], v[24:27], off offset:320
	s_waitcnt lgkmcnt(0)
	v_add_f32_e32 v19, v19, v28
	v_max_f32_e32 v19, v18, v19

; template <int MASK> DI float shx(float v, int lane) { return __builtin_bit_cast(float, __builtin_amdgcn_ds_bpermute((lane ^ MASK) << 2, __builtin_bit_cast(int, v))); }
; DI float dot4(f32x4 v) { return (v[0] * v[0] + v[1] * v[1]) + (v[2] * v[2] + v[3] * v[3]); }
; #define FOR_ROWS _Pragma("unroll") for (int ai = 0; ai < 2; ++ai) _Pragma("unroll") for (int m = 0; m < 4; ++m)
; #define FOR_BJ _Pragma("unroll") for (int bj = 0; bj < 2; ++bj)
;     DI void operator()(AccRef acc, const Unit& u, int wr, int wc, int fr, int fq) const {
;     ...
;         FOR_ROWS { const int row = row0 + ai * 128 + m * 16; const float rs = __builtin_amdgcn_rsqf(ssq_kv[row] * (1.0f / 512.0f) + EPS);
;             FOR_BJ { const f32x4 v0 = acc[ai][bj][m][0] * rs, v1 = acc[ai][bj][m][1] * rs;
;                 if (bj == 0) { float sq = dot4(v0) + dot4(v1); sq += shx<16>(sq, fr | (fq << 4)); sq += shx<32>(sq, fr | (fq << 4)); mxk = __builtin_fmaxf(mxk, sq); }
;                 store8_bf16(KV + (size_t)row * 4096 + u.pn * 256 + bj * 128 + c8, v0, v1); } }
.LBB0_975:
	v_lshl_add_u32 v150, s33, 8, v152
	v_ashrrev_i32_e32 v151, 31, v150
	v_lshl_add_u64 v[148:149], v[150:151], 2, s[20:21]
	global_load_dword v200, v[148:149], off
	global_load_dword v201, v[148:149], off offset:64
	global_load_dword v202, v[148:149], off offset:128
	global_load_dword v203, v[148:149], off offset:192
	global_load_dword v204, v[148:149], off offset:512
	global_load_dword v205, v[148:149], off offset:576
	global_load_dword v206, v[148:149], off offset:640
	global_load_dword v207, v[148:149], off offset:704
	v_lshlrev_b64 v[146:147], 13, v[150:151]
	s_lshl_b32 s8, s68, 8
	s_ashr_i32 s9, s8, 31
	s_lshl_b64 s[8:9], s[8:9], 1
	v_lshl_add_u64 v[146:147], s[52:53], 0, v[146:147]
	v_or_b32_e32 v164, 16, v150
	v_lshl_add_u64 v[146:147], v[146:147], 0, s[8:9]
	v_ashrrev_i32_e32 v165, 31, v164
	v_lshl_add_u64 v[146:147], v[146:147], 0, v[136:137]
	v_lshl_add_u64 v[168:169], v[164:165], 2, s[20:21]
	s_waitcnt vmcnt(7)
	v_mov_b32_e32 v166, v200
	v_fmamk_f32 v151, v166, 0x3b000000, v163
	v_rsq_f32_e32 v166, v151
	s_nop 0
	v_pk_mul_f32 v[126:127], v[126:127], v[166:167] op_sel_hi:[1,0]
	v_pk_mul_f32 v[124:125], v[124:125], v[166:167] op_sel_hi:[1,0]
	v_pk_mul_f32 v[122:123], v[122:123], v[166:167] op_sel_hi:[1,0]
	v_pk_mul_f32 v[120:121], v[120:121], v[166:167] op_sel_hi:[1,0]
	v_pk_mul_f32 v[170:171], v[114:115], v[166:167] op_sel_hi:[1,0]
	v_pk_mul_f32 v[172:173], v[112:113], v[166:167] op_sel_hi:[1,0]
	v_pk_mul_f32 v[118:119], v[118:119], v[166:167] op_sel_hi:[1,0]
	v_pk_mul_f32 v[116:117], v[116:117], v[166:167] op_sel_hi:[1,0]
	v_cvt_pk_bf16_f32 v112, v124, v125
	v_cvt_pk_bf16_f32 v113, v126, v127
	v_cvt_pk_bf16_f32 v114, v120, v121
	v_cvt_pk_bf16_f32 v115, v122, v123
	v_cvt_pk_bf16_f32 v116, v116, v117
	v_cvt_pk_bf16_f32 v117, v118, v119
	v_cvt_pk_bf16_f32 v118, v172, v173
	v_cvt_pk_bf16_f32 v119, v170, v171
	global_store_dwordx4 v[146:147], v[112:115], off
	global_store_dwordx4 v[146:147], v[116:119], off offset:256
	s_nop 0
	v_lshlrev_b64 v[114:115], 13, v[164:165]
	v_lshl_add_u64 v[114:115], s[52:53], 0, v[114:115]
	v_or_b32_e32 v112, 32, v150
	v_lshl_add_u64 v[114:115], v[114:115], 0, s[8:9]
	v_ashrrev_i32_e32 v113, 31, v112
	v_lshl_add_u64 v[114:115], v[114:115], 0, v[136:137]
	v_lshl_add_u64 v[116:117], v[112:113], 2, s[20:21]
	s_waitcnt vmcnt(8)
	v_mov_b32_e32 v118, v201
	v_fmamk_f32 v118, v118, 0x3b000000, v163
	v_rsq_f32_e32 v118, v118
	s_nop 0
	v_pk_mul_f32 v[110:111], v[110:111], v[118:119] op_sel_hi:[1,0]
	v_pk_mul_f32 v[108:109], v[108:109], v[118:119] op_sel_hi:[1,0]
	v_pk_mul_f32 v[106:107], v[106:107], v[118:119] op_sel_hi:[1,0]
	v_pk_mul_f32 v[104:105], v[104:105], v[118:119] op_sel_hi:[1,0]
	v_pk_mul_f32 v[164:165], v[98:99], v[118:119] op_sel_hi:[1,0]
	v_pk_mul_f32 v[166:167], v[96:97], v[118:119] op_sel_hi:[1,0]
	v_pk_mul_f32 v[102:103], v[102:103], v[118:119] op_sel_hi:[1,0]
	v_pk_mul_f32 v[100:101], v[100:101], v[118:119] op_sel_hi:[1,0]
	v_cvt_pk_bf16_f32 v96, v108, v109
	v_cvt_pk_bf16_f32 v97, v110, v111
	v_cvt_pk_bf16_f32 v98, v104, v105
	v_cvt_pk_bf16_f32 v99, v106, v107
	v_cvt_pk_bf16_f32 v100, v100, v101
	v_cvt_pk_bf16_f32 v101, v102, v103
	v_cvt_pk_bf16_f32 v102, v166, v167
	v_cvt_pk_bf16_f32 v103, v164, v165
	global_store_dwordx4 v[114:115], v[96:99], off
	global_store_dwordx4 v[114:115], v[100:103], off offset:256
	s_nop 0
	v_lshlrev_b64 v[98:99], 13, v[112:113]
	v_lshl_add_u64 v[98:99], s[52:53], 0, v[98:99]
	v_or_b32_e32 v96, 48, v150
	v_lshl_add_u64 v[98:99], v[98:99], 0, s[8:9]
	v_ashrrev_i32_e32 v97, 31, v96
	v_lshl_add_u64 v[98:99], v[98:99], 0, v[136:137]
	v_lshl_add_u64 v[100:101], v[96:97], 2, s[20:21]
	s_waitcnt vmcnt(9)
	v_mov_b32_e32 v102, v202
	v_fmamk_f32 v102, v102, 0x3b000000, v163
	v_rsq_f32_e32 v102, v102
	s_nop 0
	v_pk_mul_f32 v[94:95], v[94:95], v[102:103] op_sel_hi:[1,0]
	v_pk_mul_f32 v[92:93], v[92:93], v[102:103] op_sel_hi:[1,0]
	v_pk_mul_f32 v[90:91], v[90:91], v[102:103] op_sel_hi:[1,0]
	v_pk_mul_f32 v[88:89], v[88:89], v[102:103] op_sel_hi:[1,0]
	v_pk_mul_f32 v[112:113], v[82:83], v[102:103] op_sel_hi:[1,0]
	v_pk_mul_f32 v[114:115], v[80:81], v[102:103] op_sel_hi:[1,0]
	v_pk_mul_f32 v[86:87], v[86:87], v[102:103] op_sel_hi:[1,0]
	v_pk_mul_f32 v[84:85], v[84:85], v[102:103] op_sel_hi:[1,0]
	v_cvt_pk_bf16_f32 v80, v92, v93
	v_cvt_pk_bf16_f32 v81, v94, v95
	v_cvt_pk_bf16_f32 v82, v88, v89
	v_cvt_pk_bf16_f32 v83, v90, v91
	v_cvt_pk_bf16_f32 v84, v84, v85
	v_cvt_pk_bf16_f32 v85, v86, v87
	v_cvt_pk_bf16_f32 v86, v114, v115
	v_cvt_pk_bf16_f32 v87, v112, v113
	global_store_dwordx4 v[98:99], v[80:83], off
	global_store_dwordx4 v[98:99], v[84:87], off offset:256
	s_nop 0
	v_lshlrev_b64 v[80:81], 13, v[96:97]
	v_lshl_add_u64 v[80:81], s[52:53], 0, v[80:81]
	v_lshl_add_u64 v[80:81], v[80:81], 0, s[8:9]
	v_lshl_add_u64 v[80:81], v[80:81], 0, v[136:137]
	s_waitcnt vmcnt(10)
	v_mov_b32_e32 v82, v203
	v_fmamk_f32 v82, v82, 0x3b000000, v163
	v_rsq_f32_e32 v82, v82
	s_nop 0
	v_pk_mul_f32 v[78:79], v[78:79], v[82:83] op_sel_hi:[1,0]
	v_pk_mul_f32 v[76:77], v[76:77], v[82:83] op_sel_hi:[1,0]
	v_pk_mul_f32 v[74:75], v[74:75], v[82:83] op_sel_hi:[1,0]
	v_pk_mul_f32 v[72:73], v[72:73], v[82:83] op_sel_hi:[1,0]
	v_pk_mul_f32 v[84:85], v[66:67], v[82:83] op_sel_hi:[1,0]
	v_pk_mul_f32 v[86:87], v[64:65], v[82:83] op_sel_hi:[1,0]
	v_pk_mul_f32 v[70:71], v[70:71], v[82:83] op_sel_hi:[1,0]
	v_pk_mul_f32 v[68:69], v[68:69], v[82:83] op_sel_hi:[1,0]
	v_cvt_pk_bf16_f32 v64, v76, v77
	v_cvt_pk_bf16_f32 v65, v78, v79
	v_cvt_pk_bf16_f32 v66, v72, v73
	v_cvt_pk_bf16_f32 v67, v74, v75
	v_cvt_pk_bf16_f32 v68, v68, v69
	v_cvt_pk_bf16_f32 v69, v70, v71
	v_cvt_pk_bf16_f32 v70, v86, v87
	v_cvt_pk_bf16_f32 v71, v84, v85
	global_store_dwordx4 v[80:81], v[64:67], off
	global_store_dwordx4 v[80:81], v[68:71], off offset:256
	s_nop 0
	v_lshl_add_u64 v[64:65], v[146:147], 0, s[16:17]
	v_add_co_u32_e32 v68, vcc, s71, v146
	s_waitcnt vmcnt(11)
; template <int MASK> DI float shx(float v, int lane) { return __builtin_bit_cast(float, __builtin_amdgcn_ds_bpermute((lane ^ MASK) << 2, __builtin_bit_cast(int, v))); }
; DI float dot4(f32x4 v) { return (v[0] * v[0] + v[1] * v[1]) + (v[2] * v[2] + v[3] * v[3]); }
; #define FOR_ROWS _Pragma("unroll") for (int ai = 0; ai < 2; ++ai) _Pragma("unroll") for (int m = 0; m < 4; ++m)
; #define FOR_BJ _Pragma("unroll") for (int bj = 0; bj < 2; ++bj)
;     DI void operator()(AccRef acc, const Unit& u, int wr, int wc, int fr, int fq) const {
;     ...
;         FOR_ROWS { const int row = row0 + ai * 128 + m * 16; const float rs = __builtin_amdgcn_rsqf(ssq_kv[row] * (1.0f / 512.0f) + EPS);
;             FOR_BJ { const f32x4 v0 = acc[ai][bj][m][0] * rs, v1 = acc[ai][bj][m][1] * rs;
;                 if (bj == 0) { float sq = dot4(v0) + dot4(v1); sq += shx<16>(sq, fr | (fq << 4)); sq += shx<32>(sq, fr | (fq << 4)); mxk = __builtin_fmaxf(mxk, sq); }
;                 store8_bf16(KV + (size_t)row * 4096 + u.pn * 256 + bj * 128 + c8, v0, v1); } }
	v_mov_b32_e32 v66, v204
	v_fmamk_f32 v66, v66, 0x3b000000, v163
	v_rsq_f32_e32 v66, v66
	v_addc_co_u32_e32 v69, vcc, 0, v147, vcc
	v_pk_mul_f32 v[62:63], v[62:63], v[66:67] op_sel_hi:[1,0]
	v_pk_mul_f32 v[60:61], v[60:61], v[66:67] op_sel_hi:[1,0]
	v_pk_mul_f32 v[58:59], v[58:59], v[66:67] op_sel_hi:[1,0]
	v_pk_mul_f32 v[56:57], v[56:57], v[66:67] op_sel_hi:[1,0]
	v_pk_mul_f32 v[70:71], v[50:51], v[66:67] op_sel_hi:[1,0]
	v_pk_mul_f32 v[80:81], v[48:49], v[66:67] op_sel_hi:[1,0]
	v_pk_mul_f32 v[54:55], v[54:55], v[66:67] op_sel_hi:[1,0]
	v_pk_mul_f32 v[52:53], v[52:53], v[66:67] op_sel_hi:[1,0]
	v_cvt_pk_bf16_f32 v48, v60, v61
	v_cvt_pk_bf16_f32 v49, v62, v63
	v_cvt_pk_bf16_f32 v50, v56, v57
	v_cvt_pk_bf16_f32 v51, v58, v59
	v_cvt_pk_bf16_f32 v52, v52, v53
	v_cvt_pk_bf16_f32 v53, v54, v55
	v_cvt_pk_bf16_f32 v54, v80, v81
	v_cvt_pk_bf16_f32 v55, v70, v71
	global_store_dwordx4 v[68:69], v[48:51], off
	global_store_dwordx4 v[64:65], v[52:55], off offset:256
	s_nop 0
	v_lshl_add_u64 v[48:49], v[146:147], 0, s[18:19]
	v_add_co_u32_e32 v52, vcc, s72, v146
	s_waitcnt vmcnt(12)
	v_mov_b32_e32 v50, v205
	v_fmamk_f32 v50, v50, 0x3b000000, v163
	v_rsq_f32_e32 v50, v50
	v_addc_co_u32_e32 v53, vcc, 0, v147, vcc
	v_pk_mul_f32 v[46:47], v[46:47], v[50:51] op_sel_hi:[1,0]
	v_pk_mul_f32 v[44:45], v[44:45], v[50:51] op_sel_hi:[1,0]
	v_pk_mul_f32 v[42:43], v[42:43], v[50:51] op_sel_hi:[1,0]
	v_pk_mul_f32 v[40:41], v[40:41], v[50:51] op_sel_hi:[1,0]
	v_pk_mul_f32 v[54:55], v[34:35], v[50:51] op_sel_hi:[1,0]
	v_pk_mul_f32 v[64:65], v[32:33], v[50:51] op_sel_hi:[1,0]
	v_pk_mul_f32 v[38:39], v[38:39], v[50:51] op_sel_hi:[1,0]
	v_pk_mul_f32 v[36:37], v[36:37], v[50:51] op_sel_hi:[1,0]
	v_cvt_pk_bf16_f32 v32, v44, v45
	v_cvt_pk_bf16_f32 v33, v46, v47
	v_cvt_pk_bf16_f32 v34, v40, v41
	v_cvt_pk_bf16_f32 v35, v42, v43
	v_cvt_pk_bf16_f32 v36, v36, v37
	v_cvt_pk_bf16_f32 v37, v38, v39
	v_cvt_pk_bf16_f32 v38, v64, v65
	v_cvt_pk_bf16_f32 v39, v54, v55
	global_store_dwordx4 v[52:53], v[32:35], off
	global_store_dwordx4 v[48:49], v[36:39], off offset:256
	s_nop 0
	v_mul_f32_e32 v48, v123, v123
	v_mul_f32_e32 v37, v125, v125
	v_mul_f32_e32 v38, v127, v127
	v_mul_f32_e32 v39, v121, v121
	v_fmac_f32_e32 v37, v124, v124
	v_fmac_f32_e32 v38, v126, v126
	v_fmac_f32_e32 v39, v120, v120
	v_fmac_f32_e32 v48, v122, v122
	v_add_f32_e32 v37, v37, v38
	v_add_f32_e32 v38, v39, v48
	v_add_f32_e32 v37, v37, v38
	v_add_co_u32_e32 v34, vcc, s73, v146
	v_lshl_add_u64 v[32:33], v[146:147], 0, s[22:23]
	s_nop 0
	v_addc_co_u32_e32 v35, vcc, 0, v147, vcc
	v_mul_f32_e32 v51, v109, v109
	v_mul_f32_e32 v52, v111, v111
	v_mul_f32_e32 v53, v105, v105
	v_mul_f32_e32 v54, v107, v107
	v_fmac_f32_e32 v51, v108, v108
	v_fmac_f32_e32 v52, v110, v110
	v_fmac_f32_e32 v53, v104, v104
	v_fmac_f32_e32 v54, v106, v106
	ds_bpermute_b32 v50, v154, v37
	s_waitcnt vmcnt(13)
	v_mov_b32_e32 v36, v206
	v_fmamk_f32 v36, v36, 0x3b000000, v163
	v_rsq_f32_e32 v36, v36
	s_nop 0
	v_pk_mul_f32 v[30:31], v[30:31], v[36:37] op_sel_hi:[1,0]
	v_pk_mul_f32 v[28:29], v[28:29], v[36:37] op_sel_hi:[1,0]
	v_pk_mul_f32 v[26:27], v[26:27], v[36:37] op_sel_hi:[1,0]
	v_pk_mul_f32 v[24:25], v[24:25], v[36:37] op_sel_hi:[1,0]
	v_pk_mul_f32 v[38:39], v[18:19], v[36:37] op_sel_hi:[1,0]
	v_pk_mul_f32 v[48:49], v[16:17], v[36:37] op_sel_hi:[1,0]
	v_pk_mul_f32 v[22:23], v[22:23], v[36:37] op_sel_hi:[1,0]
	v_pk_mul_f32 v[20:21], v[20:21], v[36:37] op_sel_hi:[1,0]
	v_cvt_pk_bf16_f32 v16, v28, v29
	v_cvt_pk_bf16_f32 v17, v30, v31
	v_cvt_pk_bf16_f32 v18, v24, v25
	v_cvt_pk_bf16_f32 v19, v26, v27
	v_cvt_pk_bf16_f32 v20, v20, v21
	v_cvt_pk_bf16_f32 v21, v22, v23
	v_cvt_pk_bf16_f32 v22, v48, v49
	v_cvt_pk_bf16_f32 v23, v38, v39
	global_store_dwordx4 v[34:35], v[16:19], off
	global_store_dwordx4 v[32:33], v[20:23], off offset:256
	s_nop 0
	v_add_f32_e32 v16, v51, v52
	v_add_f32_e32 v17, v53, v54
	v_add_f32_e32 v19, v16, v17
	ds_bpermute_b32 v20, v154, v19
	v_mul_f32_e32 v23, v93, v93
	v_mul_f32_e32 v32, v95, v95
	v_mul_f32_e32 v33, v89, v89
	v_mul_f32_e32 v34, v91, v91
	v_fmac_f32_e32 v23, v92, v92
	v_fmac_f32_e32 v32, v94, v94
	v_fmac_f32_e32 v33, v88, v88
	v_fmac_f32_e32 v34, v90, v90
	v_add_f32_e32 v23, v23, v32
	v_add_f32_e32 v32, v33, v34
	v_mul_f32_e32 v33, v77, v77
	v_mul_f32_e32 v34, v79, v79
	v_mul_f32_e32 v35, v73, v73
	v_mul_f32_e32 v36, v75, v75
	v_fmac_f32_e32 v33, v76, v76
	v_fmac_f32_e32 v34, v78, v78
	v_fmac_f32_e32 v35, v72, v72
	v_fmac_f32_e32 v36, v74, v74
	v_add_f32_e32 v33, v33, v34
	v_add_f32_e32 v34, v35, v36
	s_waitcnt lgkmcnt(0)
; template <int MASK> DI float shx(float v, int lane) { return __builtin_bit_cast(float, __builtin_amdgcn_ds_bpermute((lane ^ MASK) << 2, __builtin_bit_cast(int, v))); }
; DI float dot4(f32x4 v) { return (v[0] * v[0] + v[1] * v[1]) + (v[2] * v[2] + v[3] * v[3]); }
; #define FOR_ROWS _Pragma("unroll") for (int ai = 0; ai < 2; ++ai) _Pragma("unroll") for (int m = 0; m < 4; ++m)
; #define FOR_BJ _Pragma("unroll") for (int bj = 0; bj < 2; ++bj)
; DI void wave16_atomic_max(unsigned* p, float mv, int fr, int fq) {
;     const int ln = fr | (fq << 4);
;     mv = __builtin_fmaxf(mv, shx<1>(mv, ln)); mv = __builtin_fmaxf(mv, shx<2>(mv, ln)); mv = __builtin_fmaxf(mv, shx<4>(mv, ln)); mv = __builtin_fmaxf(mv, shx<8>(mv, ln));
;     if (fr == 0 && fq == 0) (void)__hip_atomic_fetch_max(p, __builtin_bit_cast(unsigned, mv), __ATOMIC_RELAXED, __HIP_MEMORY_SCOPE_AGENT);
;     DI void operator()(AccRef acc, const Unit& u, int wr, int wc, int fr, int fq) const {
;     ...
;         FOR_ROWS { const int row = row0 + ai * 128 + m * 16; const float rs = __builtin_amdgcn_rsqf(ssq_kv[row] * (1.0f / 512.0f) + EPS);
;             FOR_BJ { const f32x4 v0 = acc[ai][bj][m][0] * rs, v1 = acc[ai][bj][m][1] * rs;
;                 if (bj == 0) { float sq = dot4(v0) + dot4(v1); sq += shx<16>(sq, fr | (fq << 4)); sq += shx<32>(sq, fr | (fq << 4)); mxk = __builtin_fmaxf(mxk, sq); }
;                 store8_bf16(KV + (size_t)row * 4096 + u.pn * 256 + bj * 128 + c8, v0, v1); } }
;         wave16_atomic_max(ctl + CW_NK + (((u.pm >> 5) * 16 + u.pn) * 4 + wc), mxk, fr, fq);
	v_add_f32_e32 v19, v19, v20
	v_add_f32_e32 v23, v23, v32
	v_add_f32_e32 v33, v33, v34
	ds_bpermute_b32 v20, v155, v19
	ds_bpermute_b32 v32, v154, v23
	ds_bpermute_b32 v34, v154, v33
	v_add_f32_e32 v21, v37, v50
	ds_bpermute_b32 v22, v155, v21
	s_waitcnt lgkmcnt(3)
	v_add_f32_e32 v19, v19, v20
	s_waitcnt lgkmcnt(2)
	v_add_f32_e32 v20, v23, v32
	s_waitcnt lgkmcnt(1)
	v_add_f32_e32 v23, v33, v34
	v_mul_f32_e32 v33, v61, v61
	v_mul_f32_e32 v34, v63, v63
	v_mul_f32_e32 v35, v57, v57
	v_mul_f32_e32 v36, v59, v59
	v_fmac_f32_e32 v33, v60, v60
	v_fmac_f32_e32 v34, v62, v62
	v_fmac_f32_e32 v35, v56, v56
	v_fmac_f32_e32 v36, v58, v58
	v_add_f32_e32 v33, v33, v34
	v_add_f32_e32 v34, v35, v36
	s_waitcnt lgkmcnt(0)
	v_add_f32_e32 v21, v21, v22
	ds_bpermute_b32 v22, v155, v20
	ds_bpermute_b32 v32, v155, v23
	v_add_f32_e32 v33, v33, v34
	ds_bpermute_b32 v34, v154, v33
	v_max3_f32 v19, v21, 0, v19
	s_waitcnt lgkmcnt(2)
	v_add_f32_e32 v20, v20, v22
	s_waitcnt lgkmcnt(1)
	v_add_f32_e32 v21, v23, v32
	v_max3_f32 v19, v19, v20, v21
	s_waitcnt lgkmcnt(0)
	v_add_f32_e32 v22, v33, v34
	v_mul_f32_e32 v20, v45, v45
	v_mul_f32_e32 v21, v47, v47
	v_mul_f32_e32 v32, v41, v41
	v_mul_f32_e32 v33, v43, v43
	v_fmac_f32_e32 v20, v44, v44
	v_fmac_f32_e32 v21, v46, v46
	v_fmac_f32_e32 v32, v40, v40
	v_fmac_f32_e32 v33, v42, v42
	v_add_f32_e32 v20, v20, v21
	v_add_f32_e32 v21, v32, v33
	v_add_f32_e32 v32, v20, v21
	v_mul_f32_e32 v20, v29, v29
	v_mul_f32_e32 v21, v31, v31
	v_mul_f32_e32 v25, v25, v25
	v_mul_f32_e32 v27, v27, v27
	v_fmac_f32_e32 v20, v28, v28
	v_fmac_f32_e32 v21, v30, v30
	v_fmac_f32_e32 v25, v24, v24
	v_fmac_f32_e32 v27, v26, v26
	v_add_f32_e32 v20, v20, v21
	v_add_f32_e32 v21, v25, v27
	v_add_f32_e32 v24, v20, v21
	ds_bpermute_b32 v33, v154, v32
	ds_bpermute_b32 v25, v154, v24
	s_waitcnt vmcnt(14)
	v_mov_b32_e32 v18, v207
	v_fmamk_f32 v18, v18, 0x3b000000, v163
	v_rsq_f32_e32 v18, v18
	ds_bpermute_b32 v23, v155, v22
	v_lshl_add_u64 v[16:17], v[146:147], 0, s[24:25]
	s_waitcnt lgkmcnt(1)
	v_add_f32_e32 v24, v24, v25
	v_pk_mul_f32 v[14:15], v[14:15], v[18:19] op_sel_hi:[1,0]
	v_pk_mul_f32 v[12:13], v[12:13], v[18:19] op_sel_hi:[1,0]
	v_pk_mul_f32 v[20:21], v[10:11], v[18:19] op_sel_hi:[1,0]
	v_pk_mul_f32 v[10:11], v[8:9], v[18:19] op_sel_hi:[1,0]
	v_mul_f32_e32 v8, v13, v13
	v_mul_f32_e32 v9, v15, v15
	v_mul_f32_e32 v26, v11, v11
	v_mul_f32_e32 v27, v21, v21
	v_fmac_f32_e32 v8, v12, v12
	v_fmac_f32_e32 v9, v14, v14
	v_fmac_f32_e32 v26, v10, v10
	v_fmac_f32_e32 v27, v20, v20
	v_add_f32_e32 v8, v8, v9
	v_add_f32_e32 v9, v26, v27
	v_add_f32_e32 v8, v8, v9
	ds_bpermute_b32 v9, v154, v8
	v_add_f32_e32 v26, v32, v33
	ds_bpermute_b32 v27, v155, v26
	ds_bpermute_b32 v25, v155, v24
	s_waitcnt lgkmcnt(3)
	v_add_f32_e32 v22, v22, v23
	s_waitcnt lgkmcnt(2)
	v_add_f32_e32 v8, v8, v9
	ds_bpermute_b32 v9, v155, v8
	s_waitcnt lgkmcnt(2)
	v_add_f32_e32 v23, v26, v27
	v_max3_f32 v19, v19, v22, v23
	s_waitcnt lgkmcnt(1)
	v_add_f32_e32 v22, v24, v25
	v_cvt_pk_bf16_f32 v10, v10, v11
	s_waitcnt lgkmcnt(0)
	v_add_f32_e32 v8, v8, v9
	v_max3_f32 v19, v19, v22, v8
	ds_bpermute_b32 v22, v156, v19
	v_cvt_pk_bf16_f32 v8, v12, v13
	v_cvt_pk_bf16_f32 v9, v14, v15
	v_cvt_pk_bf16_f32 v11, v20, v21
	v_pk_mul_f32 v[6:7], v[6:7], v[18:19] op_sel_hi:[1,0]
	s_waitcnt lgkmcnt(0)
	v_max_f32_e32 v12, v22, v22
	v_max_f32_e32 v14, v19, v12
	ds_bpermute_b32 v15, v157, v14
	v_add_co_u32_e32 v12, vcc, s74, v146
	s_nop 1
	v_addc_co_u32_e32 v13, vcc, 0, v147, vcc
	global_store_dwordx4 v[12:13], v[8:11], off
	s_nop 1
	v_pk_mul_f32 v[8:9], v[2:3], v[18:19] op_sel_hi:[1,0]
	s_waitcnt lgkmcnt(0)
	v_max_f32_e32 v2, v15, v15
	v_max_f32_e32 v3, v14, v2
	ds_bpermute_b32 v12, v158, v3
	v_pk_mul_f32 v[10:11], v[0:1], v[18:19] op_sel_hi:[1,0]
	v_pk_mul_f32 v[0:1], v[4:5], v[18:19] op_sel_hi:[1,0]
	v_cvt_pk_bf16_f32 v4, v10, v11
	v_cvt_pk_bf16_f32 v2, v0, v1
	s_waitcnt lgkmcnt(0)
	v_max_f32_e32 v0, v12, v12
	v_max_f32_e32 v0, v3, v0
	ds_bpermute_b32 v1, v159, v0
	v_cvt_pk_bf16_f32 v3, v6, v7
	v_cvt_pk_bf16_f32 v5, v8, v9
	global_store_dwordx4 v[16:17], v[2:5], off offset:256
	s_and_saveexec_b64 s[8:9], s[4:5]
	s_cbranch_execz .LBB0_980
	s_waitcnt lgkmcnt(0)
	v_max_f32_e32 v1, v1, v1
	v_max_f32_e32 v0, v0, v0
	s_mov_b64 s[58:59], exec
	v_max_f32_e32 v0, v0, v1
	s_mov_b32 s27, 0

; #define FOR_ROWS _Pragma("unroll") for (int ai = 0; ai < 2; ++ai) _Pragma("unroll") for (int m = 0; m < 4; ++m)
; #define FOR_BJ _Pragma("unroll") for (int bj = 0; bj < 2; ++bj)
;     DI void operator()(AccRef acc, const Unit& u, int wr, int wc, int fr, int fq) const {
;     ...
;         FOR_ROWS { const int row = row0 + ai * 128 + m * 16;
;             FOR_BJ { const int col = u.pn * 256 + bj * 128 + c8; f32x4 g0, g1; load8_bf16(gates + (size_t)row * 4096 + col, g0, g1);
;                 store8_bf16(merged + (size_t)row * 2048 + col, acc[ai][bj][m][0] * g0, acc[ai][bj][m][1] * g1); } }
.LBB0_1627:
	v_lshl_add_u32 v146, s24, 8, v148
	v_lshl_or_b32 v144, s53, 8, v150
	v_ashrrev_i32_e32 v147, 31, v146
	v_lshlrev_b64 v[154:155], 13, v[146:147]
	v_ashrrev_i32_e32 v145, 31, v144
	v_lshl_add_u64 v[154:155], s[34:35], 0, v[154:155]
	v_lshlrev_b64 v[144:145], 1, v[144:145]
	v_lshl_add_u64 v[158:159], v[154:155], 0, v[144:145]
	v_mov_b32_e32 v214, v158
	v_mov_b32_e32 v215, v159
	v_mov_b32_e32 v216, 0x20000
	v_mov_b32_e32 v217, 0
	global_load_dwordx4 v[166:169], v[214:215], off
	global_load_dwordx4 v[170:173], v[214:215], off offset:256
	v_lshl_add_u64 v[214:215], v[214:215], 0, v[216:217]
	global_load_dwordx4 v[174:177], v[214:215], off
	global_load_dwordx4 v[178:181], v[214:215], off offset:256
	v_lshl_add_u64 v[214:215], v[214:215], 0, v[216:217]
	global_load_dwordx4 v[182:185], v[214:215], off
	global_load_dwordx4 v[186:189], v[214:215], off offset:256
	v_lshl_add_u64 v[214:215], v[214:215], 0, v[216:217]
	global_load_dwordx4 v[190:193], v[214:215], off
	global_load_dwordx4 v[194:197], v[214:215], off offset:256
	v_lshl_add_u64 v[214:215], v[216:217], 2, v[214:215]
	v_lshl_add_u64 v[214:215], v[214:215], 0, v[216:217]
	global_load_dwordx4 v[198:201], v[214:215], off
	global_load_dwordx4 v[202:205], v[214:215], off offset:256
	v_lshl_add_u64 v[214:215], v[214:215], 0, v[216:217]
	global_load_dwordx4 v[206:209], v[214:215], off
	global_load_dwordx4 v[210:213], v[214:215], off offset:256
	s_waitcnt vmcnt(11)
	s_nop 1
	v_mov_b32_e32 v154, v166
	v_mov_b32_e32 v155, v167
	v_mov_b32_e32 v156, v168
	v_mov_b32_e32 v157, v169
	v_lshl_add_u64 v[214:215], v[214:215], 0, v[216:217]
	global_load_dwordx4 v[166:169], v[214:215], off
	v_lshlrev_b64 v[160:161], 12, v[146:147]
	v_lshl_add_u64 v[160:161], s[10:11], 0, v[160:161]
	v_lshl_add_u64 v[160:161], v[160:161], 0, v[144:145]
	s_andn2_b64 vcc, exec, s[6:7]
	s_mov_b64 s[6:7], -1
	v_lshlrev_b32_e32 v162, 16, v154
	v_and_b32_e32 v163, 0xffff0000, v154
	v_lshlrev_b32_e32 v154, 16, v155
	v_and_b32_e32 v155, 0xffff0000, v155
	v_lshlrev_b32_e32 v164, 16, v156
	v_and_b32_e32 v165, 0xffff0000, v156
	v_lshlrev_b32_e32 v156, 16, v157
	v_and_b32_e32 v157, 0xffff0000, v157
	v_pk_mul_f32 v[126:127], v[126:127], v[154:155]
	v_pk_mul_f32 v[124:125], v[124:125], v[162:163]
	v_pk_mul_f32 v[154:155], v[122:123], v[156:157]
	v_pk_mul_f32 v[122:123], v[120:121], v[164:165]
	v_cvt_pk_bf16_f32 v120, v124, v125
	v_cvt_pk_bf16_f32 v121, v126, v127
	v_cvt_pk_bf16_f32 v122, v122, v123
	v_cvt_pk_bf16_f32 v123, v154, v155
	global_store_dwordx4 v[160:161], v[120:123], off
	s_waitcnt vmcnt(12)
	s_nop 1
	v_mov_b32_e32 v120, v170
	v_mov_b32_e32 v121, v171
	v_mov_b32_e32 v122, v172
	v_mov_b32_e32 v123, v173
	global_load_dwordx4 v[170:173], v[214:215], off offset:256
	v_or_b32_e32 v124, 16, v146
	v_ashrrev_i32_e32 v125, 31, v124
	v_lshlrev_b64 v[126:127], 13, v[124:125]
	v_lshl_add_u64 v[126:127], s[34:35], 0, v[126:127]
	v_lshl_add_u64 v[126:127], v[126:127], 0, v[144:145]
	v_lshlrev_b32_e32 v154, 16, v120
	v_and_b32_e32 v155, 0xffff0000, v120
	v_lshlrev_b32_e32 v120, 16, v121
	v_and_b32_e32 v121, 0xffff0000, v121
	v_lshlrev_b32_e32 v156, 16, v122
	v_and_b32_e32 v157, 0xffff0000, v122
	v_lshlrev_b32_e32 v122, 16, v123
	v_and_b32_e32 v123, 0xffff0000, v123
	v_pk_mul_f32 v[118:119], v[118:119], v[120:121]
	v_pk_mul_f32 v[116:117], v[116:117], v[154:155]
	v_pk_mul_f32 v[120:121], v[114:115], v[122:123]
	v_pk_mul_f32 v[114:115], v[112:113], v[156:157]
	v_cvt_pk_bf16_f32 v112, v116, v117
	v_cvt_pk_bf16_f32 v113, v118, v119
	v_cvt_pk_bf16_f32 v114, v114, v115
	v_cvt_pk_bf16_f32 v115, v120, v121
	global_store_dwordx4 v[160:161], v[112:115], off offset:256
	s_waitcnt vmcnt(13)
	s_nop 1
	v_mov_b32_e32 v112, v174
	v_mov_b32_e32 v113, v175
	v_mov_b32_e32 v114, v176
	v_mov_b32_e32 v115, v177
	v_lshl_add_u64 v[214:215], v[214:215], 0, v[216:217]
	global_load_dwordx4 v[174:177], v[214:215], off
	v_lshlrev_b64 v[116:117], 12, v[124:125]
	v_lshl_add_u64 v[116:117], s[10:11], 0, v[116:117]
	v_lshl_add_u64 v[116:117], v[116:117], 0, v[144:145]
	v_lshlrev_b32_e32 v118, 16, v112
	v_and_b32_e32 v119, 0xffff0000, v112
	v_lshlrev_b32_e32 v112, 16, v113
	v_and_b32_e32 v113, 0xffff0000, v113
	v_lshlrev_b32_e32 v120, 16, v114
	v_and_b32_e32 v121, 0xffff0000, v114
	v_lshlrev_b32_e32 v114, 16, v115
	v_and_b32_e32 v115, 0xffff0000, v115
	v_pk_mul_f32 v[110:111], v[110:111], v[112:113]
	v_pk_mul_f32 v[108:109], v[108:109], v[118:119]
	v_pk_mul_f32 v[112:113], v[106:107], v[114:115]
	v_pk_mul_f32 v[106:107], v[104:105], v[120:121]
	v_cvt_pk_bf16_f32 v104, v108, v109
	v_cvt_pk_bf16_f32 v105, v110, v111
	v_cvt_pk_bf16_f32 v106, v106, v107
	v_cvt_pk_bf16_f32 v107, v112, v113
	global_store_dwordx4 v[116:117], v[104:107], off
	s_waitcnt vmcnt(14)
	s_nop 1
	v_mov_b32_e32 v104, v178
	v_mov_b32_e32 v105, v179
	v_mov_b32_e32 v106, v180
	v_mov_b32_e32 v107, v181
	global_load_dwordx4 v[178:181], v[214:215], off offset:256
	v_or_b32_e32 v108, 32, v146
	v_ashrrev_i32_e32 v109, 31, v108
	v_lshlrev_b64 v[110:111], 13, v[108:109]
	v_lshl_add_u64 v[110:111], s[34:35], 0, v[110:111]
	v_lshl_add_u64 v[110:111], v[110:111], 0, v[144:145]
	v_lshlrev_b32_e32 v112, 16, v104
	v_and_b32_e32 v113, 0xffff0000, v104
	v_lshlrev_b32_e32 v104, 16, v105
	v_and_b32_e32 v105, 0xffff0000, v105
	v_lshlrev_b32_e32 v114, 16, v106
	v_and_b32_e32 v115, 0xffff0000, v106
	v_lshlrev_b32_e32 v106, 16, v107
	v_and_b32_e32 v107, 0xffff0000, v107
	v_pk_mul_f32 v[102:103], v[102:103], v[104:105]
	v_pk_mul_f32 v[100:101], v[100:101], v[112:113]
	v_pk_mul_f32 v[104:105], v[98:99], v[106:107]
	v_pk_mul_f32 v[98:99], v[96:97], v[114:115]
	v_cvt_pk_bf16_f32 v96, v100, v101
	v_cvt_pk_bf16_f32 v97, v102, v103
	v_cvt_pk_bf16_f32 v98, v98, v99
	v_cvt_pk_bf16_f32 v99, v104, v105
	global_store_dwordx4 v[116:117], v[96:99], off offset:256
	s_waitcnt vmcnt(15)
; #define FOR_ROWS _Pragma("unroll") for (int ai = 0; ai < 2; ++ai) _Pragma("unroll") for (int m = 0; m < 4; ++m)
; #define FOR_BJ _Pragma("unroll") for (int bj = 0; bj < 2; ++bj)
;     DI void operator()(AccRef acc, const Unit& u, int wr, int wc, int fr, int fq) const {
;     ...
;         FOR_ROWS { const int row = row0 + ai * 128 + m * 16;
;             FOR_BJ { const int col = u.pn * 256 + bj * 128 + c8; f32x4 g0, g1; load8_bf16(gates + (size_t)row * 4096 + col, g0, g1);
;                 store8_bf16(merged + (size_t)row * 2048 + col, acc[ai][bj][m][0] * g0, acc[ai][bj][m][1] * g1); } }
	s_nop 1
	v_mov_b32_e32 v96, v182
	v_mov_b32_e32 v97, v183
	v_mov_b32_e32 v98, v184
	v_mov_b32_e32 v99, v185
	v_lshlrev_b64 v[100:101], 12, v[108:109]
	v_lshl_add_u64 v[100:101], s[10:11], 0, v[100:101]
	v_lshl_add_u64 v[100:101], v[100:101], 0, v[144:145]
	v_lshlrev_b32_e32 v102, 16, v96
	v_and_b32_e32 v103, 0xffff0000, v96
	v_lshlrev_b32_e32 v96, 16, v97
	v_and_b32_e32 v97, 0xffff0000, v97
	v_lshlrev_b32_e32 v104, 16, v98
	v_and_b32_e32 v105, 0xffff0000, v98
	v_lshlrev_b32_e32 v98, 16, v99
	v_and_b32_e32 v99, 0xffff0000, v99
	v_pk_mul_f32 v[94:95], v[94:95], v[96:97]
	v_pk_mul_f32 v[92:93], v[92:93], v[102:103]
	v_pk_mul_f32 v[96:97], v[90:91], v[98:99]
	v_pk_mul_f32 v[90:91], v[88:89], v[104:105]
	v_cvt_pk_bf16_f32 v88, v92, v93
	v_cvt_pk_bf16_f32 v89, v94, v95
	v_cvt_pk_bf16_f32 v90, v90, v91
	v_cvt_pk_bf16_f32 v91, v96, v97
	global_store_dwordx4 v[100:101], v[88:91], off
	s_waitcnt vmcnt(15)
	s_nop 1
	v_mov_b32_e32 v88, v186
	v_mov_b32_e32 v89, v187
	v_mov_b32_e32 v90, v188
	v_mov_b32_e32 v91, v189
	v_or_b32_e32 v92, 48, v146
	v_ashrrev_i32_e32 v93, 31, v92
	v_lshlrev_b64 v[94:95], 13, v[92:93]
	v_lshl_add_u64 v[94:95], s[34:35], 0, v[94:95]
	v_lshl_add_u64 v[94:95], v[94:95], 0, v[144:145]
	v_lshlrev_b32_e32 v96, 16, v88
	v_and_b32_e32 v97, 0xffff0000, v88
	v_lshlrev_b32_e32 v88, 16, v89
	v_and_b32_e32 v89, 0xffff0000, v89
	v_lshlrev_b32_e32 v98, 16, v90
	v_and_b32_e32 v99, 0xffff0000, v90
	v_lshlrev_b32_e32 v90, 16, v91
	v_and_b32_e32 v91, 0xffff0000, v91
	v_pk_mul_f32 v[86:87], v[86:87], v[88:89]
	v_pk_mul_f32 v[84:85], v[84:85], v[96:97]
	v_pk_mul_f32 v[88:89], v[82:83], v[90:91]
	v_pk_mul_f32 v[82:83], v[80:81], v[98:99]
	v_cvt_pk_bf16_f32 v80, v84, v85
	v_cvt_pk_bf16_f32 v81, v86, v87
	v_cvt_pk_bf16_f32 v82, v82, v83
	v_cvt_pk_bf16_f32 v83, v88, v89
	global_store_dwordx4 v[100:101], v[80:83], off offset:256
	s_waitcnt vmcnt(15)
	s_nop 1
	v_mov_b32_e32 v80, v190
	v_mov_b32_e32 v81, v191
	v_mov_b32_e32 v82, v192
	v_mov_b32_e32 v83, v193
	v_lshlrev_b64 v[84:85], 12, v[92:93]
	v_lshl_add_u64 v[84:85], s[10:11], 0, v[84:85]
	v_lshl_add_u64 v[84:85], v[84:85], 0, v[144:145]
	v_lshlrev_b32_e32 v86, 16, v80
	v_and_b32_e32 v87, 0xffff0000, v80
	v_lshlrev_b32_e32 v80, 16, v81
	v_and_b32_e32 v81, 0xffff0000, v81
	v_lshlrev_b32_e32 v88, 16, v82
	v_and_b32_e32 v89, 0xffff0000, v82
	v_lshlrev_b32_e32 v82, 16, v83
	v_and_b32_e32 v83, 0xffff0000, v83
	v_pk_mul_f32 v[78:79], v[78:79], v[80:81]
	v_pk_mul_f32 v[76:77], v[76:77], v[86:87]
	v_pk_mul_f32 v[80:81], v[74:75], v[82:83]
	v_pk_mul_f32 v[74:75], v[72:73], v[88:89]
	v_cvt_pk_bf16_f32 v72, v76, v77
	v_cvt_pk_bf16_f32 v73, v78, v79
	v_cvt_pk_bf16_f32 v74, v74, v75
	v_cvt_pk_bf16_f32 v75, v80, v81
	global_store_dwordx4 v[84:85], v[72:75], off
	s_waitcnt vmcnt(15)
	s_nop 1
	v_mov_b32_e32 v72, v194
	v_mov_b32_e32 v73, v195
	v_mov_b32_e32 v74, v196
	v_mov_b32_e32 v75, v197
	v_add_u32_e32 v76, 0x80, v146
	v_ashrrev_i32_e32 v77, 31, v76
	v_lshlrev_b64 v[78:79], 13, v[76:77]
	v_lshl_add_u64 v[78:79], s[34:35], 0, v[78:79]
	v_lshl_add_u64 v[78:79], v[78:79], 0, v[144:145]
	v_lshlrev_b32_e32 v80, 16, v72
	v_and_b32_e32 v81, 0xffff0000, v72
	v_lshlrev_b32_e32 v72, 16, v73
	v_and_b32_e32 v73, 0xffff0000, v73
	v_lshlrev_b32_e32 v82, 16, v74
	v_and_b32_e32 v83, 0xffff0000, v74
	v_lshlrev_b32_e32 v74, 16, v75
	v_and_b32_e32 v75, 0xffff0000, v75
	v_pk_mul_f32 v[70:71], v[70:71], v[72:73]
	v_pk_mul_f32 v[68:69], v[68:69], v[80:81]
	v_pk_mul_f32 v[72:73], v[66:67], v[74:75]
	v_pk_mul_f32 v[66:67], v[64:65], v[82:83]
	v_cvt_pk_bf16_f32 v64, v68, v69
	v_cvt_pk_bf16_f32 v65, v70, v71
	v_cvt_pk_bf16_f32 v66, v66, v67
	v_cvt_pk_bf16_f32 v67, v72, v73
	global_store_dwordx4 v[84:85], v[64:67], off offset:256
	s_waitcnt vmcnt(15)
	s_nop 1
	v_mov_b32_e32 v64, v198
	v_mov_b32_e32 v65, v199
	v_mov_b32_e32 v66, v200
	v_mov_b32_e32 v67, v201
	v_lshlrev_b64 v[68:69], 12, v[76:77]
	v_lshl_add_u64 v[68:69], s[10:11], 0, v[68:69]
	v_lshl_add_u64 v[68:69], v[68:69], 0, v[144:145]
	v_lshlrev_b32_e32 v70, 16, v64
	v_and_b32_e32 v71, 0xffff0000, v64
	v_lshlrev_b32_e32 v64, 16, v65
	v_and_b32_e32 v65, 0xffff0000, v65
	v_lshlrev_b32_e32 v72, 16, v66
	v_and_b32_e32 v73, 0xffff0000, v66
	v_lshlrev_b32_e32 v66, 16, v67
	v_and_b32_e32 v67, 0xffff0000, v67
	v_pk_mul_f32 v[62:63], v[62:63], v[64:65]
	v_pk_mul_f32 v[60:61], v[60:61], v[70:71]
	v_pk_mul_f32 v[64:65], v[58:59], v[66:67]
	v_pk_mul_f32 v[58:59], v[56:57], v[72:73]
	v_cvt_pk_bf16_f32 v56, v60, v61
	v_cvt_pk_bf16_f32 v57, v62, v63
	v_cvt_pk_bf16_f32 v58, v58, v59
	v_cvt_pk_bf16_f32 v59, v64, v65
	global_store_dwordx4 v[68:69], v[56:59], off
	s_waitcnt vmcnt(15)
	s_nop 1
	v_mov_b32_e32 v56, v202
	v_mov_b32_e32 v57, v203
	v_mov_b32_e32 v58, v204
	v_mov_b32_e32 v59, v205
	v_add_u32_e32 v60, 0x90, v146
	v_ashrrev_i32_e32 v61, 31, v60
	v_lshlrev_b64 v[62:63], 13, v[60:61]
	v_lshl_add_u64 v[62:63], s[34:35], 0, v[62:63]
	v_lshl_add_u64 v[62:63], v[62:63], 0, v[144:145]
	v_lshlrev_b32_e32 v64, 16, v56
	v_and_b32_e32 v65, 0xffff0000, v56
	v_lshlrev_b32_e32 v56, 16, v57
	v_and_b32_e32 v57, 0xffff0000, v57
	v_lshlrev_b32_e32 v66, 16, v58
	v_and_b32_e32 v67, 0xffff0000, v58
	v_lshlrev_b32_e32 v58, 16, v59
	v_and_b32_e32 v59, 0xffff0000, v59
	v_pk_mul_f32 v[54:55], v[54:55], v[56:57]
	v_pk_mul_f32 v[52:53], v[52:53], v[64:65]
	v_pk_mul_f32 v[56:57], v[50:51], v[58:59]
	v_pk_mul_f32 v[50:51], v[48:49], v[66:67]
	v_cvt_pk_bf16_f32 v48, v52, v53
	v_cvt_pk_bf16_f32 v49, v54, v55
	v_cvt_pk_bf16_f32 v50, v50, v51
	v_cvt_pk_bf16_f32 v51, v56, v57
	global_store_dwordx4 v[68:69], v[48:51], off offset:256
	s_waitcnt vmcnt(15)
; #define PG8_BAR __builtin_amdgcn_s_barrier()
; #define FOR_ROWS _Pragma("unroll") for (int ai = 0; ai < 2; ++ai) _Pragma("unroll") for (int m = 0; m < 4; ++m)
; #define FOR_BJ _Pragma("unroll") for (int bj = 0; bj < 2; ++bj)
; template <class Epi, class Sched>
; DI void gemm_phase(LAS unsigned char* lds, const Gemm g, const Sched& S, const Epi& E) {
;     ...
;         cur = nxt; cA = nA; cB = nB; ++ui;
;         if (wr == 1) PG8_BAR;
;     DI void operator()(AccRef acc, const Unit& u, int wr, int wc, int fr, int fq) const {
;     ...
;         FOR_ROWS { const int row = row0 + ai * 128 + m * 16;
;             FOR_BJ { const int col = u.pn * 256 + bj * 128 + c8; f32x4 g0, g1; load8_bf16(gates + (size_t)row * 4096 + col, g0, g1);
;                 store8_bf16(merged + (size_t)row * 2048 + col, acc[ai][bj][m][0] * g0, acc[ai][bj][m][1] * g1); } }
	s_nop 1
	v_mov_b32_e32 v48, v206
	v_mov_b32_e32 v49, v207
	v_mov_b32_e32 v50, v208
	v_mov_b32_e32 v51, v209
	v_lshlrev_b64 v[52:53], 12, v[60:61]
	v_lshl_add_u64 v[52:53], s[10:11], 0, v[52:53]
	v_lshl_add_u64 v[52:53], v[52:53], 0, v[144:145]
	v_lshlrev_b32_e32 v54, 16, v48
	v_and_b32_e32 v55, 0xffff0000, v48
	v_lshlrev_b32_e32 v48, 16, v49
	v_and_b32_e32 v49, 0xffff0000, v49
	v_lshlrev_b32_e32 v56, 16, v50
	v_and_b32_e32 v57, 0xffff0000, v50
	v_lshlrev_b32_e32 v50, 16, v51
	v_and_b32_e32 v51, 0xffff0000, v51
	v_pk_mul_f32 v[46:47], v[46:47], v[48:49]
	v_pk_mul_f32 v[44:45], v[44:45], v[54:55]
	v_pk_mul_f32 v[48:49], v[42:43], v[50:51]
	v_pk_mul_f32 v[42:43], v[40:41], v[56:57]
	v_cvt_pk_bf16_f32 v40, v44, v45
	v_cvt_pk_bf16_f32 v41, v46, v47
	v_cvt_pk_bf16_f32 v42, v42, v43
	v_cvt_pk_bf16_f32 v43, v48, v49
	global_store_dwordx4 v[52:53], v[40:43], off
	s_waitcnt vmcnt(15)
	s_nop 1
	v_mov_b32_e32 v40, v210
	v_mov_b32_e32 v41, v211
	v_mov_b32_e32 v42, v212
	v_mov_b32_e32 v43, v213
	v_add_u32_e32 v44, 0xa0, v146
	v_ashrrev_i32_e32 v45, 31, v44
	v_lshlrev_b64 v[46:47], 13, v[44:45]
	v_lshl_add_u64 v[46:47], s[34:35], 0, v[46:47]
	v_lshl_add_u64 v[46:47], v[46:47], 0, v[144:145]
	v_lshlrev_b32_e32 v48, 16, v40
	v_and_b32_e32 v49, 0xffff0000, v40
	v_lshlrev_b32_e32 v40, 16, v41
	v_and_b32_e32 v41, 0xffff0000, v41
	v_lshlrev_b32_e32 v50, 16, v42
	v_and_b32_e32 v51, 0xffff0000, v42
	v_lshlrev_b32_e32 v42, 16, v43
	v_and_b32_e32 v43, 0xffff0000, v43
	v_pk_mul_f32 v[38:39], v[38:39], v[40:41]
	v_pk_mul_f32 v[36:37], v[36:37], v[48:49]
	v_pk_mul_f32 v[40:41], v[34:35], v[42:43]
	v_pk_mul_f32 v[34:35], v[32:33], v[50:51]
	v_cvt_pk_bf16_f32 v32, v36, v37
	v_cvt_pk_bf16_f32 v33, v38, v39
	v_cvt_pk_bf16_f32 v34, v34, v35
	v_cvt_pk_bf16_f32 v35, v40, v41
	global_store_dwordx4 v[52:53], v[32:35], off offset:256
	s_waitcnt vmcnt(15)
	s_nop 1
	v_mov_b32_e32 v32, v166
	v_mov_b32_e32 v33, v167
	v_mov_b32_e32 v34, v168
	v_mov_b32_e32 v35, v169
	v_lshlrev_b64 v[36:37], 12, v[44:45]
	v_lshl_add_u64 v[36:37], s[10:11], 0, v[36:37]
	v_lshl_add_u64 v[36:37], v[36:37], 0, v[144:145]
	v_lshlrev_b32_e32 v38, 16, v32
	v_and_b32_e32 v39, 0xffff0000, v32
	v_lshlrev_b32_e32 v32, 16, v33
	v_and_b32_e32 v33, 0xffff0000, v33
	v_lshlrev_b32_e32 v40, 16, v34
	v_and_b32_e32 v41, 0xffff0000, v34
	v_lshlrev_b32_e32 v34, 16, v35
	v_and_b32_e32 v35, 0xffff0000, v35
	v_pk_mul_f32 v[30:31], v[30:31], v[32:33]
	v_pk_mul_f32 v[28:29], v[28:29], v[38:39]
	v_pk_mul_f32 v[32:33], v[26:27], v[34:35]
	v_pk_mul_f32 v[26:27], v[24:25], v[40:41]
	v_cvt_pk_bf16_f32 v24, v28, v29
	v_cvt_pk_bf16_f32 v25, v30, v31
	v_cvt_pk_bf16_f32 v26, v26, v27
	v_cvt_pk_bf16_f32 v27, v32, v33
	global_store_dwordx4 v[36:37], v[24:27], off
	s_waitcnt vmcnt(14)
	s_nop 1
	v_mov_b32_e32 v24, v170
	v_mov_b32_e32 v25, v171
	v_mov_b32_e32 v26, v172
	v_mov_b32_e32 v27, v173
	v_add_u32_e32 v28, 0xb0, v146
	v_ashrrev_i32_e32 v29, 31, v28
	v_lshlrev_b64 v[30:31], 13, v[28:29]
	v_lshl_add_u64 v[30:31], s[34:35], 0, v[30:31]
	v_lshl_add_u64 v[30:31], v[30:31], 0, v[144:145]
	v_lshlrev_b32_e32 v32, 16, v24
	v_and_b32_e32 v33, 0xffff0000, v24
	v_lshlrev_b32_e32 v24, 16, v25
	v_and_b32_e32 v25, 0xffff0000, v25
	v_lshlrev_b32_e32 v34, 16, v26
	v_and_b32_e32 v35, 0xffff0000, v26
	v_lshlrev_b32_e32 v26, 16, v27
	v_and_b32_e32 v27, 0xffff0000, v27
	v_pk_mul_f32 v[22:23], v[22:23], v[24:25]
	v_pk_mul_f32 v[20:21], v[20:21], v[32:33]
	v_pk_mul_f32 v[24:25], v[18:19], v[26:27]
	v_pk_mul_f32 v[18:19], v[16:17], v[34:35]
	v_cvt_pk_bf16_f32 v16, v20, v21
	v_cvt_pk_bf16_f32 v17, v22, v23
	v_cvt_pk_bf16_f32 v18, v18, v19
	v_cvt_pk_bf16_f32 v19, v24, v25
	global_store_dwordx4 v[36:37], v[16:19], off offset:256
	s_waitcnt vmcnt(13)
	s_nop 1
	v_mov_b32_e32 v16, v174
	v_mov_b32_e32 v17, v175
	v_mov_b32_e32 v18, v176
	v_mov_b32_e32 v19, v177
	v_lshlrev_b64 v[20:21], 12, v[28:29]
	v_lshl_add_u64 v[20:21], s[10:11], 0, v[20:21]
	v_lshl_add_u64 v[20:21], v[20:21], 0, v[144:145]
	v_lshlrev_b32_e32 v22, 16, v16
	v_and_b32_e32 v23, 0xffff0000, v16
	v_lshlrev_b32_e32 v16, 16, v17
	v_and_b32_e32 v17, 0xffff0000, v17
	v_lshlrev_b32_e32 v24, 16, v18
	v_and_b32_e32 v25, 0xffff0000, v18
	v_lshlrev_b32_e32 v18, 16, v19
	v_and_b32_e32 v19, 0xffff0000, v19
	v_pk_mul_f32 v[14:15], v[14:15], v[16:17]
	v_pk_mul_f32 v[12:13], v[12:13], v[22:23]
	v_pk_mul_f32 v[16:17], v[10:11], v[18:19]
	v_pk_mul_f32 v[10:11], v[8:9], v[24:25]
	v_cvt_pk_bf16_f32 v8, v12, v13
	v_cvt_pk_bf16_f32 v9, v14, v15
	v_cvt_pk_bf16_f32 v10, v10, v11
	v_cvt_pk_bf16_f32 v11, v16, v17
	global_store_dwordx4 v[20:21], v[8:11], off
	s_waitcnt vmcnt(12)
	s_nop 1
	v_mov_b32_e32 v8, v178
	v_mov_b32_e32 v9, v179
	v_mov_b32_e32 v10, v180
	v_mov_b32_e32 v11, v181
	v_lshlrev_b32_e32 v12, 16, v8
	v_and_b32_e32 v13, 0xffff0000, v8
	v_lshlrev_b32_e32 v8, 16, v9
	v_and_b32_e32 v9, 0xffff0000, v9
	v_lshlrev_b32_e32 v14, 16, v10
	v_and_b32_e32 v15, 0xffff0000, v10
	v_lshlrev_b32_e32 v10, 16, v11
	v_and_b32_e32 v11, 0xffff0000, v11
	v_pk_mul_f32 v[6:7], v[6:7], v[8:9]
	v_pk_mul_f32 v[4:5], v[4:5], v[12:13]
	v_pk_mul_f32 v[8:9], v[2:3], v[10:11]
	v_pk_mul_f32 v[2:3], v[0:1], v[14:15]
	v_cvt_pk_bf16_f32 v0, v4, v5
	v_cvt_pk_bf16_f32 v1, v6, v7
	v_cvt_pk_bf16_f32 v2, v2, v3
	v_cvt_pk_bf16_f32 v3, v8, v9
	global_store_dwordx4 v[20:21], v[0:3], off offset:256
	s_cbranch_vccnz .LBB0_1616
	s_andn2_b64 vcc, exec, s[8:9]
	s_cbranch_vccnz .LBB0_1615
	s_barrier
	s_branch .LBB0_1615

; #define FOR_ROWS _Pragma("unroll") for (int ai = 0; ai < 2; ++ai) _Pragma("unroll") for (int m = 0; m < 4; ++m)
; #define FOR_BJ _Pragma("unroll") for (int bj = 0; bj < 2; ++bj)
;     DI void operator()(AccRef acc, const Unit& u, int wr, int wc, int fr, int fq) const {
;     ...
;         FOR_ROWS { const int row = row0 + ai * 128 + m * 16;
;             FOR_BJ { const int col = u.pn * 256 + bj * 128 + c8; f32x4 g0, g1; load8_bf16(gates + (size_t)row * 4096 + 2048 + col, g0, g1);
;                 f32x4 t0, t1; load8_bf16(merged + (size_t)row * 2048 + col, t0, t1);
;                 store8_bf16(merged + (size_t)row * 2048 + col, t0 + acc[ai][bj][m][0] * g0, t1 + acc[ai][bj][m][1] * g1); } }
.LBB0_1651:
	v_lshl_add_u32 v148, s26, 8, v150
	v_ashrrev_i32_e32 v149, 31, v148
	v_lshl_or_b32 v144, s46, 8, v152
	v_lshlrev_b64 v[160:161], 13, v[148:149]
	v_lshlrev_b64 v[156:157], 12, v[148:149]
	v_ashrrev_i32_e32 v145, 31, v144
	v_lshl_add_u64 v[160:161], s[34:35], 0, v[160:161]
	v_lshlrev_b64 v[146:147], 1, v[144:145]
	v_lshl_add_u64 v[156:157], s[10:11], 0, v[156:157]
	v_lshl_add_u64 v[164:165], v[160:161], 0, s[16:17]
	v_lshl_add_u64 v[168:169], v[156:157], 0, v[146:147]
	v_lshl_add_u64 v[160:161], v[164:165], 0, v[146:147]
	v_mov_b32_e32 v216, v168
	v_mov_b32_e32 v217, v169
	v_mov_b32_e32 v218, 0x10000
	v_mov_b32_e32 v219, 0
	v_or_b32_e32 v144, 0x80, v144
	v_mov_b32_e32 v220, v160
	v_mov_b32_e32 v221, v161
	v_mov_b32_e32 v222, 0x20000
	v_mov_b32_e32 v223, 0
	global_load_dwordx4 v[180:183], v[216:217], off
	global_load_dwordx4 v[184:187], v[220:221], off
	global_load_dwordx4 v[188:191], v[216:217], off offset:256
	global_load_dwordx4 v[192:195], v[220:221], off offset:256
	v_lshl_add_u64 v[216:217], v[216:217], 0, v[218:219]
	global_load_dwordx4 v[196:199], v[216:217], off
	v_lshl_add_u64 v[220:221], v[220:221], 0, v[222:223]
	global_load_dwordx4 v[200:203], v[220:221], off
	global_load_dwordx4 v[204:207], v[216:217], off offset:256
	global_load_dwordx4 v[208:211], v[220:221], off offset:256
	v_lshl_add_u64 v[216:217], v[216:217], 0, v[218:219]
	global_load_dwordx4 v[212:215], v[216:217], off
	v_lshl_add_u64 v[220:221], v[220:221], 0, v[222:223]
	global_load_dwordx4 v[226:229], v[220:221], off
	global_load_dwordx4 v[230:233], v[216:217], off offset:256
	global_load_dwordx4 v[234:237], v[220:221], off offset:256
	v_lshl_add_u64 v[216:217], v[216:217], 0, v[218:219]
	global_load_dwordx4 v[238:241], v[216:217], off
	v_lshl_add_u64 v[220:221], v[220:221], 0, v[222:223]
	global_load_dwordx4 v[244:247], v[220:221], off
	global_load_dwordx4 v[248:251], v[216:217], off offset:256
	s_waitcnt vmcnt(14)
	s_nop 1
	v_mov_b32_e32 v156, v180
	v_mov_b32_e32 v157, v181
	v_mov_b32_e32 v158, v182
	v_mov_b32_e32 v159, v183
	global_load_dwordx4 v[180:183], v[220:221], off offset:256
	s_waitcnt vmcnt(14)
	s_nop 1
	v_mov_b32_e32 v160, v184
	v_mov_b32_e32 v161, v185
	v_mov_b32_e32 v162, v186
	v_mov_b32_e32 v163, v187
	v_lshl_add_u64 v[216:217], v[218:219], 2, v[216:217]
	v_lshl_add_u64 v[216:217], v[216:217], 0, v[218:219]
	global_load_dwordx4 v[184:187], v[216:217], off
	v_ashrrev_i32_e32 v145, 31, v144
	v_lshlrev_b64 v[144:145], 1, v[144:145]
	v_lshl_add_u64 v[170:171], v[164:165], 0, v[144:145]
	s_waitcnt vmcnt(14)
	s_nop 1
	v_mov_b32_e32 v164, v188
	v_mov_b32_e32 v165, v189
	v_mov_b32_e32 v166, v190
	v_mov_b32_e32 v167, v191
	v_lshl_add_u64 v[220:221], v[222:223], 2, v[220:221]
	v_lshl_add_u64 v[220:221], v[220:221], 0, v[222:223]
	global_load_dwordx4 v[188:191], v[220:221], off
	s_andn2_b64 vcc, exec, s[6:7]
	s_mov_b64 s[6:7], -1
	v_lshlrev_b32_e32 v172, 16, v156
	v_and_b32_e32 v173, 0xffff0000, v156
	v_lshlrev_b32_e32 v156, 16, v157
	v_and_b32_e32 v157, 0xffff0000, v157
	v_lshlrev_b32_e32 v174, 16, v158
	v_and_b32_e32 v175, 0xffff0000, v158
	v_lshlrev_b32_e32 v158, 16, v159
	v_and_b32_e32 v159, 0xffff0000, v159
	v_lshlrev_b32_e32 v176, 16, v160
	v_and_b32_e32 v177, 0xffff0000, v160
	v_lshlrev_b32_e32 v160, 16, v161
	v_and_b32_e32 v161, 0xffff0000, v161
	v_lshlrev_b32_e32 v178, 16, v162
	v_and_b32_e32 v179, 0xffff0000, v162
	v_lshlrev_b32_e32 v162, 16, v163
	v_and_b32_e32 v163, 0xffff0000, v163
	v_pk_fma_f32 v[126:127], v[126:127], v[160:161], v[156:157]
	v_pk_fma_f32 v[124:125], v[124:125], v[176:177], v[172:173]
	v_pk_fma_f32 v[156:157], v[122:123], v[162:163], v[158:159]
	v_pk_fma_f32 v[122:123], v[120:121], v[178:179], v[174:175]
	v_cvt_pk_bf16_f32 v120, v124, v125
	v_cvt_pk_bf16_f32 v121, v126, v127
	v_cvt_pk_bf16_f32 v122, v122, v123
	v_cvt_pk_bf16_f32 v123, v156, v157
	global_store_dwordx4 v[168:169], v[120:123], off
	s_waitcnt vmcnt(15)
	s_nop 1
	v_mov_b32_e32 v120, v192
	v_mov_b32_e32 v121, v193
	v_mov_b32_e32 v122, v194
	v_mov_b32_e32 v123, v195
	global_load_dwordx4 v[192:195], v[216:217], off offset:256
	v_or_b32_e32 v124, 16, v148
	v_ashrrev_i32_e32 v125, 31, v124
	v_lshlrev_b64 v[126:127], 13, v[124:125]
	v_lshlrev_b32_e32 v162, 16, v164
	v_and_b32_e32 v163, 0xffff0000, v164
	v_lshlrev_b32_e32 v164, 16, v165
	v_and_b32_e32 v165, 0xffff0000, v165
	v_lshlrev_b32_e32 v170, 16, v166
	v_and_b32_e32 v171, 0xffff0000, v166
	v_lshlrev_b32_e32 v166, 16, v167
	v_and_b32_e32 v167, 0xffff0000, v167
	v_lshlrev_b64 v[124:125], 12, v[124:125]
	v_lshl_add_u64 v[126:127], s[34:35], 0, v[126:127]
	v_lshl_add_u64 v[124:125], s[10:11], 0, v[124:125]
	v_lshl_add_u64 v[156:157], v[126:127], 0, s[16:17]
	v_lshl_add_u64 v[158:159], v[124:125], 0, v[146:147]
	v_lshl_add_u64 v[160:161], v[156:157], 0, v[146:147]
	s_waitcnt vmcnt(15)
	s_nop 1
	v_mov_b32_e32 v124, v196
	v_mov_b32_e32 v125, v197
	v_mov_b32_e32 v126, v198
	v_mov_b32_e32 v127, v199
	global_load_dwordx4 v[196:199], v[220:221], off offset:256
	v_lshlrev_b32_e32 v172, 16, v120
	v_and_b32_e32 v173, 0xffff0000, v120
	v_lshlrev_b32_e32 v120, 16, v121
	v_and_b32_e32 v121, 0xffff0000, v121
	v_lshlrev_b32_e32 v174, 16, v122
	v_and_b32_e32 v175, 0xffff0000, v122
	v_lshlrev_b32_e32 v122, 16, v123
	v_and_b32_e32 v123, 0xffff0000, v123
	v_pk_fma_f32 v[118:119], v[118:119], v[120:121], v[164:165]
	v_pk_fma_f32 v[116:117], v[116:117], v[172:173], v[162:163]
	v_pk_fma_f32 v[120:121], v[114:115], v[122:123], v[166:167]
	v_pk_fma_f32 v[114:115], v[112:113], v[174:175], v[170:171]
	v_cvt_pk_bf16_f32 v112, v116, v117
	v_cvt_pk_bf16_f32 v113, v118, v119
	v_cvt_pk_bf16_f32 v114, v114, v115
	v_cvt_pk_bf16_f32 v115, v120, v121
	global_store_dwordx4 v[168:169], v[112:115], off offset:256
	s_waitcnt vmcnt(16)
; #define FOR_ROWS _Pragma("unroll") for (int ai = 0; ai < 2; ++ai) _Pragma("unroll") for (int m = 0; m < 4; ++m)
; #define FOR_BJ _Pragma("unroll") for (int bj = 0; bj < 2; ++bj)
;     DI void operator()(AccRef acc, const Unit& u, int wr, int wc, int fr, int fq) const {
;     ...
;         FOR_ROWS { const int row = row0 + ai * 128 + m * 16;
;             FOR_BJ { const int col = u.pn * 256 + bj * 128 + c8; f32x4 g0, g1; load8_bf16(gates + (size_t)row * 4096 + 2048 + col, g0, g1);
;                 f32x4 t0, t1; load8_bf16(merged + (size_t)row * 2048 + col, t0, t1);
;                 store8_bf16(merged + (size_t)row * 2048 + col, t0 + acc[ai][bj][m][0] * g0, t1 + acc[ai][bj][m][1] * g1); } }
	s_nop 1
	v_mov_b32_e32 v112, v200
	v_mov_b32_e32 v113, v201
	v_mov_b32_e32 v114, v202
	v_mov_b32_e32 v115, v203
	v_lshl_add_u64 v[216:217], v[216:217], 0, v[218:219]
	global_load_dwordx4 v[200:203], v[216:217], off
	v_lshl_add_u64 v[120:121], v[156:157], 0, v[144:145]
	v_lshlrev_b32_e32 v122, 16, v124
	v_and_b32_e32 v123, 0xffff0000, v124
	v_lshlrev_b32_e32 v124, 16, v125
	v_and_b32_e32 v125, 0xffff0000, v125
	v_lshlrev_b32_e32 v156, 16, v126
	v_and_b32_e32 v157, 0xffff0000, v126
	v_lshlrev_b32_e32 v126, 16, v127
	v_and_b32_e32 v127, 0xffff0000, v127
	s_waitcnt vmcnt(16)
	s_nop 1
	v_mov_b32_e32 v116, v204
	v_mov_b32_e32 v117, v205
	v_mov_b32_e32 v118, v206
	v_mov_b32_e32 v119, v207
	v_lshl_add_u64 v[220:221], v[220:221], 0, v[222:223]
	global_load_dwordx4 v[204:207], v[220:221], off
	v_lshlrev_b32_e32 v160, 16, v112
	v_and_b32_e32 v161, 0xffff0000, v112
	v_lshlrev_b32_e32 v112, 16, v113
	v_and_b32_e32 v113, 0xffff0000, v113
	v_lshlrev_b32_e32 v162, 16, v114
	v_and_b32_e32 v163, 0xffff0000, v114
	v_lshlrev_b32_e32 v114, 16, v115
	v_and_b32_e32 v115, 0xffff0000, v115
	v_pk_fma_f32 v[110:111], v[110:111], v[112:113], v[124:125]
	v_pk_fma_f32 v[108:109], v[108:109], v[160:161], v[122:123]
	v_pk_fma_f32 v[112:113], v[106:107], v[114:115], v[126:127]
	v_pk_fma_f32 v[106:107], v[104:105], v[162:163], v[156:157]
	v_cvt_pk_bf16_f32 v104, v108, v109
	v_cvt_pk_bf16_f32 v105, v110, v111
	v_cvt_pk_bf16_f32 v106, v106, v107
	v_cvt_pk_bf16_f32 v107, v112, v113
	global_store_dwordx4 v[158:159], v[104:107], off
	s_waitcnt vmcnt(17)
	s_nop 1
	v_mov_b32_e32 v104, v208
	v_mov_b32_e32 v105, v209
	v_mov_b32_e32 v106, v210
	v_mov_b32_e32 v107, v211
	global_load_dwordx4 v[208:211], v[216:217], off offset:256
	v_or_b32_e32 v108, 32, v148
	v_ashrrev_i32_e32 v109, 31, v108
	v_lshlrev_b64 v[110:111], 13, v[108:109]
	v_lshlrev_b32_e32 v122, 16, v116
	v_and_b32_e32 v123, 0xffff0000, v116
	v_lshlrev_b32_e32 v116, 16, v117
	v_and_b32_e32 v117, 0xffff0000, v117
	v_lshlrev_b32_e32 v124, 16, v118
	v_and_b32_e32 v125, 0xffff0000, v118
	v_lshlrev_b32_e32 v118, 16, v119
	v_and_b32_e32 v119, 0xffff0000, v119
	v_lshlrev_b64 v[108:109], 12, v[108:109]
	v_lshl_add_u64 v[110:111], s[34:35], 0, v[110:111]
	v_lshl_add_u64 v[108:109], s[10:11], 0, v[108:109]
	v_lshl_add_u64 v[112:113], v[110:111], 0, s[16:17]
	v_lshl_add_u64 v[114:115], v[108:109], 0, v[146:147]
	v_lshl_add_u64 v[120:121], v[112:113], 0, v[146:147]
	s_waitcnt vmcnt(17)
	s_nop 1
	v_mov_b32_e32 v108, v212
	v_mov_b32_e32 v109, v213
	v_mov_b32_e32 v110, v214
	v_mov_b32_e32 v111, v215
	global_load_dwordx4 v[212:215], v[220:221], off offset:256
	v_lshlrev_b32_e32 v126, 16, v104
	v_and_b32_e32 v127, 0xffff0000, v104
	v_lshlrev_b32_e32 v104, 16, v105
	v_and_b32_e32 v105, 0xffff0000, v105
	v_lshlrev_b32_e32 v156, 16, v106
	v_and_b32_e32 v157, 0xffff0000, v106
	v_lshlrev_b32_e32 v106, 16, v107
	v_and_b32_e32 v107, 0xffff0000, v107
	v_pk_fma_f32 v[102:103], v[102:103], v[104:105], v[116:117]
	v_pk_fma_f32 v[100:101], v[100:101], v[126:127], v[122:123]
	v_pk_fma_f32 v[104:105], v[98:99], v[106:107], v[118:119]
	v_pk_fma_f32 v[98:99], v[96:97], v[156:157], v[124:125]
	v_cvt_pk_bf16_f32 v96, v100, v101
	v_cvt_pk_bf16_f32 v97, v102, v103
	v_cvt_pk_bf16_f32 v98, v98, v99
	v_cvt_pk_bf16_f32 v99, v104, v105
	global_store_dwordx4 v[158:159], v[96:99], off offset:256
	s_waitcnt vmcnt(18)
	s_nop 1
	v_mov_b32_e32 v96, v226
	v_mov_b32_e32 v97, v227
	v_mov_b32_e32 v98, v228
	v_mov_b32_e32 v99, v229
	v_lshl_add_u64 v[216:217], v[216:217], 0, v[218:219]
	global_load_dwordx4 v[226:229], v[216:217], off
	v_lshl_add_u64 v[104:105], v[112:113], 0, v[144:145]
	v_lshlrev_b32_e32 v106, 16, v108
	v_and_b32_e32 v107, 0xffff0000, v108
	v_lshlrev_b32_e32 v108, 16, v109
	v_and_b32_e32 v109, 0xffff0000, v109
	v_lshlrev_b32_e32 v112, 16, v110
	v_and_b32_e32 v113, 0xffff0000, v110
	v_lshlrev_b32_e32 v110, 16, v111
	v_and_b32_e32 v111, 0xffff0000, v111
	s_waitcnt vmcnt(18)
	s_nop 1
	v_mov_b32_e32 v100, v230
	v_mov_b32_e32 v101, v231
	v_mov_b32_e32 v102, v232
	v_mov_b32_e32 v103, v233
	v_lshl_add_u64 v[220:221], v[220:221], 0, v[222:223]
	global_load_dwordx4 v[230:233], v[220:221], off
	v_lshlrev_b32_e32 v116, 16, v96
	v_and_b32_e32 v117, 0xffff0000, v96
	v_lshlrev_b32_e32 v96, 16, v97
	v_and_b32_e32 v97, 0xffff0000, v97
	v_lshlrev_b32_e32 v118, 16, v98
	v_and_b32_e32 v119, 0xffff0000, v98
	v_lshlrev_b32_e32 v98, 16, v99
	v_and_b32_e32 v99, 0xffff0000, v99
	v_pk_fma_f32 v[94:95], v[94:95], v[96:97], v[108:109]
	v_pk_fma_f32 v[92:93], v[92:93], v[116:117], v[106:107]
	v_pk_fma_f32 v[96:97], v[90:91], v[98:99], v[110:111]
	v_pk_fma_f32 v[90:91], v[88:89], v[118:119], v[112:113]
	v_cvt_pk_bf16_f32 v88, v92, v93
	v_cvt_pk_bf16_f32 v89, v94, v95
	v_cvt_pk_bf16_f32 v90, v90, v91
	v_cvt_pk_bf16_f32 v91, v96, v97
	global_store_dwordx4 v[114:115], v[88:91], off
	s_waitcnt vmcnt(19)
	s_nop 1
	v_mov_b32_e32 v88, v234
	v_mov_b32_e32 v89, v235
	v_mov_b32_e32 v90, v236
	v_mov_b32_e32 v91, v237
	global_load_dwordx4 v[234:237], v[216:217], off offset:256
	v_or_b32_e32 v92, 48, v148
	v_ashrrev_i32_e32 v93, 31, v92
	v_lshlrev_b64 v[94:95], 13, v[92:93]
	v_lshlrev_b32_e32 v106, 16, v100
	v_and_b32_e32 v107, 0xffff0000, v100
	v_lshlrev_b32_e32 v100, 16, v101
	v_and_b32_e32 v101, 0xffff0000, v101
	v_lshlrev_b32_e32 v108, 16, v102
	v_and_b32_e32 v109, 0xffff0000, v102
	v_lshlrev_b32_e32 v102, 16, v103
	v_and_b32_e32 v103, 0xffff0000, v103
	v_lshlrev_b64 v[92:93], 12, v[92:93]
	v_lshl_add_u64 v[94:95], s[34:35], 0, v[94:95]
	v_lshl_add_u64 v[92:93], s[10:11], 0, v[92:93]
	v_lshl_add_u64 v[96:97], v[94:95], 0, s[16:17]
	v_lshl_add_u64 v[98:99], v[92:93], 0, v[146:147]
	v_lshl_add_u64 v[104:105], v[96:97], 0, v[146:147]
	s_waitcnt vmcnt(19)
; #define FOR_ROWS _Pragma("unroll") for (int ai = 0; ai < 2; ++ai) _Pragma("unroll") for (int m = 0; m < 4; ++m)
; #define FOR_BJ _Pragma("unroll") for (int bj = 0; bj < 2; ++bj)
;     DI void operator()(AccRef acc, const Unit& u, int wr, int wc, int fr, int fq) const {
;     ...
;         FOR_ROWS { const int row = row0 + ai * 128 + m * 16;
;             FOR_BJ { const int col = u.pn * 256 + bj * 128 + c8; f32x4 g0, g1; load8_bf16(gates + (size_t)row * 4096 + 2048 + col, g0, g1);
;                 f32x4 t0, t1; load8_bf16(merged + (size_t)row * 2048 + col, t0, t1);
;                 store8_bf16(merged + (size_t)row * 2048 + col, t0 + acc[ai][bj][m][0] * g0, t1 + acc[ai][bj][m][1] * g1); } }
	s_nop 1
	v_mov_b32_e32 v92, v238
	v_mov_b32_e32 v93, v239
	v_mov_b32_e32 v94, v240
	v_mov_b32_e32 v95, v241
	global_load_dwordx4 v[238:241], v[220:221], off offset:256
	v_lshlrev_b32_e32 v110, 16, v88
	v_and_b32_e32 v111, 0xffff0000, v88
	v_lshlrev_b32_e32 v88, 16, v89
	v_and_b32_e32 v89, 0xffff0000, v89
	v_lshlrev_b32_e32 v112, 16, v90
	v_and_b32_e32 v113, 0xffff0000, v90
	v_lshlrev_b32_e32 v90, 16, v91
	v_and_b32_e32 v91, 0xffff0000, v91
	v_pk_fma_f32 v[86:87], v[86:87], v[88:89], v[100:101]
	v_pk_fma_f32 v[84:85], v[84:85], v[110:111], v[106:107]
	v_pk_fma_f32 v[88:89], v[82:83], v[90:91], v[102:103]
	v_pk_fma_f32 v[82:83], v[80:81], v[112:113], v[108:109]
	v_cvt_pk_bf16_f32 v80, v84, v85
	v_cvt_pk_bf16_f32 v81, v86, v87
	v_cvt_pk_bf16_f32 v82, v82, v83
	v_cvt_pk_bf16_f32 v83, v88, v89
	global_store_dwordx4 v[114:115], v[80:83], off offset:256
	s_waitcnt vmcnt(20)
	s_nop 1
	v_mov_b32_e32 v80, v244
	v_mov_b32_e32 v81, v245
	v_mov_b32_e32 v82, v246
	v_mov_b32_e32 v83, v247
	v_lshl_add_u64 v[216:217], v[216:217], 0, v[218:219]
	global_load_dwordx4 v[244:247], v[216:217], off
	v_lshl_add_u64 v[88:89], v[96:97], 0, v[144:145]
	v_lshlrev_b32_e32 v90, 16, v92
	v_and_b32_e32 v91, 0xffff0000, v92
	v_lshlrev_b32_e32 v92, 16, v93
	v_and_b32_e32 v93, 0xffff0000, v93
	v_lshlrev_b32_e32 v96, 16, v94
	v_and_b32_e32 v97, 0xffff0000, v94
	v_lshlrev_b32_e32 v94, 16, v95
	v_and_b32_e32 v95, 0xffff0000, v95
	s_waitcnt vmcnt(20)
	s_nop 1
	v_mov_b32_e32 v84, v248
	v_mov_b32_e32 v85, v249
	v_mov_b32_e32 v86, v250
	v_mov_b32_e32 v87, v251
	v_lshl_add_u64 v[220:221], v[220:221], 0, v[222:223]
	global_load_dwordx4 v[248:251], v[220:221], off
	v_lshlrev_b32_e32 v100, 16, v80
	v_and_b32_e32 v101, 0xffff0000, v80
	v_lshlrev_b32_e32 v80, 16, v81
	v_and_b32_e32 v81, 0xffff0000, v81
	v_lshlrev_b32_e32 v102, 16, v82
	v_and_b32_e32 v103, 0xffff0000, v82
	v_lshlrev_b32_e32 v82, 16, v83
	v_and_b32_e32 v83, 0xffff0000, v83
	v_pk_fma_f32 v[78:79], v[78:79], v[80:81], v[92:93]
	v_pk_fma_f32 v[76:77], v[76:77], v[100:101], v[90:91]
	v_pk_fma_f32 v[80:81], v[74:75], v[82:83], v[94:95]
	v_pk_fma_f32 v[74:75], v[72:73], v[102:103], v[96:97]
	v_cvt_pk_bf16_f32 v72, v76, v77
	v_cvt_pk_bf16_f32 v73, v78, v79
	v_cvt_pk_bf16_f32 v74, v74, v75
	v_cvt_pk_bf16_f32 v75, v80, v81
	global_store_dwordx4 v[98:99], v[72:75], off
	s_waitcnt vmcnt(21)
	s_nop 1
	v_mov_b32_e32 v72, v180
	v_mov_b32_e32 v73, v181
	v_mov_b32_e32 v74, v182
	v_mov_b32_e32 v75, v183
	global_load_dwordx4 v[180:183], v[216:217], off offset:256
	v_add_u32_e32 v76, 0x80, v148
	v_ashrrev_i32_e32 v77, 31, v76
	v_lshlrev_b64 v[78:79], 13, v[76:77]
	v_lshlrev_b32_e32 v90, 16, v84
	v_and_b32_e32 v91, 0xffff0000, v84
	v_lshlrev_b32_e32 v84, 16, v85
	v_and_b32_e32 v85, 0xffff0000, v85
	v_lshlrev_b32_e32 v92, 16, v86
	v_and_b32_e32 v93, 0xffff0000, v86
	v_lshlrev_b32_e32 v86, 16, v87
	v_and_b32_e32 v87, 0xffff0000, v87
	v_lshlrev_b64 v[76:77], 12, v[76:77]
	v_lshl_add_u64 v[78:79], s[34:35], 0, v[78:79]
	v_lshl_add_u64 v[76:77], s[10:11], 0, v[76:77]
	v_lshl_add_u64 v[80:81], v[78:79], 0, s[16:17]
	v_lshl_add_u64 v[82:83], v[76:77], 0, v[146:147]
	v_lshl_add_u64 v[88:89], v[80:81], 0, v[146:147]
	s_waitcnt vmcnt(21)
	s_nop 1
	v_mov_b32_e32 v76, v184
	v_mov_b32_e32 v77, v185
	v_mov_b32_e32 v78, v186
	v_mov_b32_e32 v79, v187
	global_load_dwordx4 v[184:187], v[220:221], off offset:256
	v_lshlrev_b32_e32 v94, 16, v72
	v_and_b32_e32 v95, 0xffff0000, v72
	v_lshlrev_b32_e32 v72, 16, v73
	v_and_b32_e32 v73, 0xffff0000, v73
	v_lshlrev_b32_e32 v96, 16, v74
	v_and_b32_e32 v97, 0xffff0000, v74
	v_lshlrev_b32_e32 v74, 16, v75
	v_and_b32_e32 v75, 0xffff0000, v75
	v_pk_fma_f32 v[70:71], v[70:71], v[72:73], v[84:85]
	v_pk_fma_f32 v[68:69], v[68:69], v[94:95], v[90:91]
	v_pk_fma_f32 v[72:73], v[66:67], v[74:75], v[86:87]
	v_pk_fma_f32 v[66:67], v[64:65], v[96:97], v[92:93]
	v_cvt_pk_bf16_f32 v64, v68, v69
	v_cvt_pk_bf16_f32 v65, v70, v71
	v_cvt_pk_bf16_f32 v66, v66, v67
	v_cvt_pk_bf16_f32 v67, v72, v73
	global_store_dwordx4 v[98:99], v[64:67], off offset:256
	s_waitcnt vmcnt(22)
	s_nop 1
	v_mov_b32_e32 v64, v188
	v_mov_b32_e32 v65, v189
	v_mov_b32_e32 v66, v190
	v_mov_b32_e32 v67, v191
	v_lshl_add_u64 v[72:73], v[80:81], 0, v[144:145]
	v_lshlrev_b32_e32 v74, 16, v76
	v_and_b32_e32 v75, 0xffff0000, v76
	v_lshlrev_b32_e32 v76, 16, v77
	v_and_b32_e32 v77, 0xffff0000, v77
	v_lshlrev_b32_e32 v80, 16, v78
	v_and_b32_e32 v81, 0xffff0000, v78
	v_lshlrev_b32_e32 v78, 16, v79
	v_and_b32_e32 v79, 0xffff0000, v79
	s_waitcnt vmcnt(20)
	s_nop 1
	v_mov_b32_e32 v68, v192
	v_mov_b32_e32 v69, v193
	v_mov_b32_e32 v70, v194
	v_mov_b32_e32 v71, v195
	v_lshlrev_b32_e32 v84, 16, v64
	v_and_b32_e32 v85, 0xffff0000, v64
	v_lshlrev_b32_e32 v64, 16, v65
	v_and_b32_e32 v65, 0xffff0000, v65
	v_lshlrev_b32_e32 v86, 16, v66
	v_and_b32_e32 v87, 0xffff0000, v66
	v_lshlrev_b32_e32 v66, 16, v67
	v_and_b32_e32 v67, 0xffff0000, v67
	v_pk_fma_f32 v[62:63], v[62:63], v[64:65], v[76:77]
	v_pk_fma_f32 v[60:61], v[60:61], v[84:85], v[74:75]
	v_pk_fma_f32 v[64:65], v[58:59], v[66:67], v[78:79]
	v_pk_fma_f32 v[58:59], v[56:57], v[86:87], v[80:81]
	v_cvt_pk_bf16_f32 v56, v60, v61
	v_cvt_pk_bf16_f32 v57, v62, v63
	v_cvt_pk_bf16_f32 v58, v58, v59
	v_cvt_pk_bf16_f32 v59, v64, v65
	global_store_dwordx4 v[82:83], v[56:59], off
	s_waitcnt vmcnt(20)
; #define FOR_ROWS _Pragma("unroll") for (int ai = 0; ai < 2; ++ai) _Pragma("unroll") for (int m = 0; m < 4; ++m)
; #define FOR_BJ _Pragma("unroll") for (int bj = 0; bj < 2; ++bj)
;     DI void operator()(AccRef acc, const Unit& u, int wr, int wc, int fr, int fq) const {
;     ...
;         FOR_ROWS { const int row = row0 + ai * 128 + m * 16;
;             FOR_BJ { const int col = u.pn * 256 + bj * 128 + c8; f32x4 g0, g1; load8_bf16(gates + (size_t)row * 4096 + 2048 + col, g0, g1);
;                 f32x4 t0, t1; load8_bf16(merged + (size_t)row * 2048 + col, t0, t1);
;                 store8_bf16(merged + (size_t)row * 2048 + col, t0 + acc[ai][bj][m][0] * g0, t1 + acc[ai][bj][m][1] * g1); } }
	s_nop 1
	v_mov_b32_e32 v56, v196
	v_mov_b32_e32 v57, v197
	v_mov_b32_e32 v58, v198
	v_mov_b32_e32 v59, v199
	v_add_u32_e32 v60, 0x90, v148
	v_ashrrev_i32_e32 v61, 31, v60
	v_lshlrev_b64 v[62:63], 13, v[60:61]
	v_lshlrev_b32_e32 v74, 16, v68
	v_and_b32_e32 v75, 0xffff0000, v68
	v_lshlrev_b32_e32 v68, 16, v69
	v_and_b32_e32 v69, 0xffff0000, v69
	v_lshlrev_b32_e32 v76, 16, v70
	v_and_b32_e32 v77, 0xffff0000, v70
	v_lshlrev_b32_e32 v70, 16, v71
	v_and_b32_e32 v71, 0xffff0000, v71
	v_lshlrev_b64 v[60:61], 12, v[60:61]
	v_lshl_add_u64 v[62:63], s[34:35], 0, v[62:63]
	v_lshl_add_u64 v[60:61], s[10:11], 0, v[60:61]
	v_lshl_add_u64 v[64:65], v[62:63], 0, s[16:17]
	v_lshl_add_u64 v[66:67], v[60:61], 0, v[146:147]
	v_lshl_add_u64 v[72:73], v[64:65], 0, v[146:147]
	s_waitcnt vmcnt(18)
	s_nop 1
	v_mov_b32_e32 v60, v200
	v_mov_b32_e32 v61, v201
	v_mov_b32_e32 v62, v202
	v_mov_b32_e32 v63, v203
	v_lshlrev_b32_e32 v78, 16, v56
	v_and_b32_e32 v79, 0xffff0000, v56
	v_lshlrev_b32_e32 v56, 16, v57
	v_and_b32_e32 v57, 0xffff0000, v57
	v_lshlrev_b32_e32 v80, 16, v58
	v_and_b32_e32 v81, 0xffff0000, v58
	v_lshlrev_b32_e32 v58, 16, v59
	v_and_b32_e32 v59, 0xffff0000, v59
	v_pk_fma_f32 v[54:55], v[54:55], v[56:57], v[68:69]
	v_pk_fma_f32 v[52:53], v[52:53], v[78:79], v[74:75]
	v_pk_fma_f32 v[56:57], v[50:51], v[58:59], v[70:71]
	v_pk_fma_f32 v[50:51], v[48:49], v[80:81], v[76:77]
	v_cvt_pk_bf16_f32 v48, v52, v53
	v_cvt_pk_bf16_f32 v49, v54, v55
	v_cvt_pk_bf16_f32 v50, v50, v51
	v_cvt_pk_bf16_f32 v51, v56, v57
	global_store_dwordx4 v[82:83], v[48:51], off offset:256
	s_waitcnt vmcnt(18)
	s_nop 1
	v_mov_b32_e32 v48, v204
	v_mov_b32_e32 v49, v205
	v_mov_b32_e32 v50, v206
	v_mov_b32_e32 v51, v207
	v_lshl_add_u64 v[56:57], v[64:65], 0, v[144:145]
	v_lshlrev_b32_e32 v58, 16, v60
	v_and_b32_e32 v59, 0xffff0000, v60
	v_lshlrev_b32_e32 v60, 16, v61
	v_and_b32_e32 v61, 0xffff0000, v61
	v_lshlrev_b32_e32 v64, 16, v62
	v_and_b32_e32 v65, 0xffff0000, v62
	v_lshlrev_b32_e32 v62, 16, v63
	v_and_b32_e32 v63, 0xffff0000, v63
	s_waitcnt vmcnt(16)
	s_nop 1
	v_mov_b32_e32 v52, v208
	v_mov_b32_e32 v53, v209
	v_mov_b32_e32 v54, v210
	v_mov_b32_e32 v55, v211
	v_lshlrev_b32_e32 v68, 16, v48
	v_and_b32_e32 v69, 0xffff0000, v48
	v_lshlrev_b32_e32 v48, 16, v49
	v_and_b32_e32 v49, 0xffff0000, v49
	v_lshlrev_b32_e32 v70, 16, v50
	v_and_b32_e32 v71, 0xffff0000, v50
	v_lshlrev_b32_e32 v50, 16, v51
	v_and_b32_e32 v51, 0xffff0000, v51
	v_pk_fma_f32 v[46:47], v[46:47], v[48:49], v[60:61]
	v_pk_fma_f32 v[44:45], v[44:45], v[68:69], v[58:59]
	v_pk_fma_f32 v[48:49], v[42:43], v[50:51], v[62:63]
	v_pk_fma_f32 v[42:43], v[40:41], v[70:71], v[64:65]
	v_cvt_pk_bf16_f32 v40, v44, v45
	v_cvt_pk_bf16_f32 v41, v46, v47
	v_cvt_pk_bf16_f32 v42, v42, v43
	v_cvt_pk_bf16_f32 v43, v48, v49
	global_store_dwordx4 v[66:67], v[40:43], off
	s_waitcnt vmcnt(16)
	s_nop 1
	v_mov_b32_e32 v40, v212
	v_mov_b32_e32 v41, v213
	v_mov_b32_e32 v42, v214
	v_mov_b32_e32 v43, v215
	v_add_u32_e32 v44, 0xa0, v148
	v_ashrrev_i32_e32 v45, 31, v44
	v_lshlrev_b64 v[46:47], 13, v[44:45]
	v_lshlrev_b32_e32 v58, 16, v52
	v_and_b32_e32 v59, 0xffff0000, v52
	v_lshlrev_b32_e32 v52, 16, v53
	v_and_b32_e32 v53, 0xffff0000, v53
	v_lshlrev_b32_e32 v60, 16, v54
	v_and_b32_e32 v61, 0xffff0000, v54
	v_lshlrev_b32_e32 v54, 16, v55
	v_and_b32_e32 v55, 0xffff0000, v55
	v_lshlrev_b64 v[44:45], 12, v[44:45]
	v_lshl_add_u64 v[46:47], s[34:35], 0, v[46:47]
	v_lshl_add_u64 v[44:45], s[10:11], 0, v[44:45]
	v_lshl_add_u64 v[48:49], v[46:47], 0, s[16:17]
	v_lshl_add_u64 v[50:51], v[44:45], 0, v[146:147]
	v_lshl_add_u64 v[56:57], v[48:49], 0, v[146:147]
	s_waitcnt vmcnt(14)
	s_nop 1
	v_mov_b32_e32 v44, v226
	v_mov_b32_e32 v45, v227
	v_mov_b32_e32 v46, v228
	v_mov_b32_e32 v47, v229
	v_lshlrev_b32_e32 v62, 16, v40
	v_and_b32_e32 v63, 0xffff0000, v40
	v_lshlrev_b32_e32 v40, 16, v41
	v_and_b32_e32 v41, 0xffff0000, v41
	v_lshlrev_b32_e32 v64, 16, v42
	v_and_b32_e32 v65, 0xffff0000, v42
	v_lshlrev_b32_e32 v42, 16, v43
	v_and_b32_e32 v43, 0xffff0000, v43
	v_pk_fma_f32 v[38:39], v[38:39], v[40:41], v[52:53]
	v_pk_fma_f32 v[36:37], v[36:37], v[62:63], v[58:59]
	v_pk_fma_f32 v[40:41], v[34:35], v[42:43], v[54:55]
	v_pk_fma_f32 v[34:35], v[32:33], v[64:65], v[60:61]
	v_cvt_pk_bf16_f32 v32, v36, v37
	v_cvt_pk_bf16_f32 v33, v38, v39
	v_cvt_pk_bf16_f32 v34, v34, v35
	v_cvt_pk_bf16_f32 v35, v40, v41
	global_store_dwordx4 v[66:67], v[32:35], off offset:256
	s_waitcnt vmcnt(14)
	s_nop 1
	v_mov_b32_e32 v32, v230
	v_mov_b32_e32 v33, v231
	v_mov_b32_e32 v34, v232
	v_mov_b32_e32 v35, v233
	v_lshl_add_u64 v[40:41], v[48:49], 0, v[144:145]
	v_lshlrev_b32_e32 v42, 16, v44
	v_and_b32_e32 v43, 0xffff0000, v44
	v_lshlrev_b32_e32 v44, 16, v45
	v_and_b32_e32 v45, 0xffff0000, v45
	v_lshlrev_b32_e32 v48, 16, v46
	v_and_b32_e32 v49, 0xffff0000, v46
	v_lshlrev_b32_e32 v46, 16, v47
	v_and_b32_e32 v47, 0xffff0000, v47
	s_waitcnt vmcnt(12)
; #define PG8_BAR __builtin_amdgcn_s_barrier()
; #define FOR_ROWS _Pragma("unroll") for (int ai = 0; ai < 2; ++ai) _Pragma("unroll") for (int m = 0; m < 4; ++m)
; #define FOR_BJ _Pragma("unroll") for (int bj = 0; bj < 2; ++bj)
; template <class Epi, class Sched>
; DI void gemm_phase(LAS unsigned char* lds, const Gemm g, const Sched& S, const Epi& E) {
;     ...
;         cur = nxt; cA = nA; cB = nB; ++ui;
;         if (wr == 1) PG8_BAR;
;     DI void operator()(AccRef acc, const Unit& u, int wr, int wc, int fr, int fq) const {
;     ...
;         FOR_ROWS { const int row = row0 + ai * 128 + m * 16;
;             FOR_BJ { const int col = u.pn * 256 + bj * 128 + c8; f32x4 g0, g1; load8_bf16(gates + (size_t)row * 4096 + 2048 + col, g0, g1);
;                 f32x4 t0, t1; load8_bf16(merged + (size_t)row * 2048 + col, t0, t1);
;                 store8_bf16(merged + (size_t)row * 2048 + col, t0 + acc[ai][bj][m][0] * g0, t1 + acc[ai][bj][m][1] * g1); } }
	s_nop 1
	v_mov_b32_e32 v36, v234
	v_mov_b32_e32 v37, v235
	v_mov_b32_e32 v38, v236
	v_mov_b32_e32 v39, v237
	v_lshlrev_b32_e32 v52, 16, v32
	v_and_b32_e32 v53, 0xffff0000, v32
	v_lshlrev_b32_e32 v32, 16, v33
	v_and_b32_e32 v33, 0xffff0000, v33
	v_lshlrev_b32_e32 v54, 16, v34
	v_and_b32_e32 v55, 0xffff0000, v34
	v_lshlrev_b32_e32 v34, 16, v35
	v_and_b32_e32 v35, 0xffff0000, v35
	v_pk_fma_f32 v[30:31], v[30:31], v[32:33], v[44:45]
	v_pk_fma_f32 v[28:29], v[28:29], v[52:53], v[42:43]
	v_pk_fma_f32 v[32:33], v[26:27], v[34:35], v[46:47]
	v_pk_fma_f32 v[26:27], v[24:25], v[54:55], v[48:49]
	v_cvt_pk_bf16_f32 v24, v28, v29
	v_cvt_pk_bf16_f32 v25, v30, v31
	v_cvt_pk_bf16_f32 v26, v26, v27
	v_cvt_pk_bf16_f32 v27, v32, v33
	global_store_dwordx4 v[50:51], v[24:27], off
	s_waitcnt vmcnt(12)
	s_nop 1
	v_mov_b32_e32 v24, v238
	v_mov_b32_e32 v25, v239
	v_mov_b32_e32 v26, v240
	v_mov_b32_e32 v27, v241
	v_add_u32_e32 v28, 0xb0, v148
	v_ashrrev_i32_e32 v29, 31, v28
	v_lshlrev_b64 v[30:31], 13, v[28:29]
	v_lshlrev_b32_e32 v42, 16, v36
	v_and_b32_e32 v43, 0xffff0000, v36
	v_lshlrev_b32_e32 v36, 16, v37
	v_and_b32_e32 v37, 0xffff0000, v37
	v_lshlrev_b32_e32 v44, 16, v38
	v_and_b32_e32 v45, 0xffff0000, v38
	v_lshlrev_b32_e32 v38, 16, v39
	v_and_b32_e32 v39, 0xffff0000, v39
	v_lshlrev_b64 v[28:29], 12, v[28:29]
	v_lshl_add_u64 v[30:31], s[34:35], 0, v[30:31]
	v_lshl_add_u64 v[28:29], s[10:11], 0, v[28:29]
	v_lshl_add_u64 v[32:33], v[30:31], 0, s[16:17]
	v_lshl_add_u64 v[34:35], v[28:29], 0, v[146:147]
	v_lshl_add_u64 v[40:41], v[32:33], 0, v[146:147]
	s_waitcnt vmcnt(10)
	s_nop 1
	v_mov_b32_e32 v28, v244
	v_mov_b32_e32 v29, v245
	v_mov_b32_e32 v30, v246
	v_mov_b32_e32 v31, v247
	v_lshlrev_b32_e32 v46, 16, v24
	v_and_b32_e32 v47, 0xffff0000, v24
	v_lshlrev_b32_e32 v24, 16, v25
	v_and_b32_e32 v25, 0xffff0000, v25
	v_lshlrev_b32_e32 v48, 16, v26
	v_and_b32_e32 v49, 0xffff0000, v26
	v_lshlrev_b32_e32 v26, 16, v27
	v_and_b32_e32 v27, 0xffff0000, v27
	v_pk_fma_f32 v[22:23], v[22:23], v[24:25], v[36:37]
	v_pk_fma_f32 v[20:21], v[20:21], v[46:47], v[42:43]
	v_pk_fma_f32 v[24:25], v[18:19], v[26:27], v[38:39]
	v_pk_fma_f32 v[18:19], v[16:17], v[48:49], v[44:45]
	v_cvt_pk_bf16_f32 v16, v20, v21
	v_cvt_pk_bf16_f32 v17, v22, v23
	v_cvt_pk_bf16_f32 v18, v18, v19
	v_cvt_pk_bf16_f32 v19, v24, v25
	global_store_dwordx4 v[50:51], v[16:19], off offset:256
	s_waitcnt vmcnt(10)
	s_nop 1
	v_mov_b32_e32 v16, v248
	v_mov_b32_e32 v17, v249
	v_mov_b32_e32 v18, v250
	v_mov_b32_e32 v19, v251
	v_lshl_add_u64 v[24:25], v[32:33], 0, v[144:145]
	v_lshlrev_b32_e32 v26, 16, v28
	v_and_b32_e32 v27, 0xffff0000, v28
	v_lshlrev_b32_e32 v28, 16, v29
	v_and_b32_e32 v29, 0xffff0000, v29
	v_lshlrev_b32_e32 v32, 16, v30
	v_and_b32_e32 v33, 0xffff0000, v30
	v_lshlrev_b32_e32 v30, 16, v31
	v_and_b32_e32 v31, 0xffff0000, v31
	s_waitcnt vmcnt(8)
	s_nop 1
	v_mov_b32_e32 v20, v180
	v_mov_b32_e32 v21, v181
	v_mov_b32_e32 v22, v182
	v_mov_b32_e32 v23, v183
	v_lshlrev_b32_e32 v36, 16, v16
	v_and_b32_e32 v37, 0xffff0000, v16
	v_lshlrev_b32_e32 v16, 16, v17
	v_and_b32_e32 v17, 0xffff0000, v17
	v_lshlrev_b32_e32 v38, 16, v18
	v_and_b32_e32 v39, 0xffff0000, v18
	v_lshlrev_b32_e32 v18, 16, v19
	v_and_b32_e32 v19, 0xffff0000, v19
	v_pk_fma_f32 v[14:15], v[14:15], v[16:17], v[28:29]
	v_pk_fma_f32 v[12:13], v[12:13], v[36:37], v[26:27]
	v_pk_fma_f32 v[16:17], v[10:11], v[18:19], v[30:31]
	v_pk_fma_f32 v[10:11], v[8:9], v[38:39], v[32:33]
	v_cvt_pk_bf16_f32 v8, v12, v13
	v_cvt_pk_bf16_f32 v9, v14, v15
	v_cvt_pk_bf16_f32 v10, v10, v11
	v_cvt_pk_bf16_f32 v11, v16, v17
	global_store_dwordx4 v[34:35], v[8:11], off
	s_waitcnt vmcnt(8)
	s_nop 1
	v_mov_b32_e32 v8, v184
	v_mov_b32_e32 v9, v185
	v_mov_b32_e32 v10, v186
	v_mov_b32_e32 v11, v187
	v_lshlrev_b32_e32 v12, 16, v20
	v_and_b32_e32 v13, 0xffff0000, v20
	v_lshlrev_b32_e32 v14, 16, v21
	v_and_b32_e32 v15, 0xffff0000, v21
	v_lshlrev_b32_e32 v16, 16, v22
	v_and_b32_e32 v17, 0xffff0000, v22
	v_lshlrev_b32_e32 v18, 16, v23
	v_and_b32_e32 v19, 0xffff0000, v23
	v_lshlrev_b32_e32 v20, 16, v8
	v_and_b32_e32 v21, 0xffff0000, v8
	v_lshlrev_b32_e32 v8, 16, v9
	v_and_b32_e32 v9, 0xffff0000, v9
	v_lshlrev_b32_e32 v22, 16, v10
	v_and_b32_e32 v23, 0xffff0000, v10
	v_lshlrev_b32_e32 v10, 16, v11
	v_and_b32_e32 v11, 0xffff0000, v11
	v_pk_fma_f32 v[6:7], v[6:7], v[8:9], v[14:15]
	v_pk_fma_f32 v[4:5], v[4:5], v[20:21], v[12:13]
	v_pk_fma_f32 v[8:9], v[2:3], v[10:11], v[18:19]
	v_pk_fma_f32 v[2:3], v[0:1], v[22:23], v[16:17]
	v_cvt_pk_bf16_f32 v0, v4, v5
	v_cvt_pk_bf16_f32 v1, v6, v7
	v_cvt_pk_bf16_f32 v2, v2, v3
	v_cvt_pk_bf16_f32 v3, v8, v9
	global_store_dwordx4 v[34:35], v[0:3], off offset:256
	s_cbranch_vccnz .LBB0_1640
	s_andn2_b64 vcc, exec, s[8:9]
	s_cbranch_vccnz .LBB0_1639
	s_barrier
	s_branch .LBB0_1639

; template <int MASK> DI float shx(float v, int lane) { return __builtin_bit_cast(float, __builtin_amdgcn_ds_bpermute((lane ^ MASK) << 2, __builtin_bit_cast(int, v))); }
; DI void atomic_addf(float* p, float v) { (void)__hip_atomic_fetch_add(p, v, __ATOMIC_RELAXED, __HIP_MEMORY_SCOPE_AGENT); }
; DI float dot4(f32x4 v) { return (v[0] * v[0] + v[1] * v[1]) + (v[2] * v[2] + v[3] * v[3]); }
; #define FOR_ROWS _Pragma("unroll") for (int ai = 0; ai < 2; ++ai) _Pragma("unroll") for (int m = 0; m < 4; ++m)
; #define FOR_BJ _Pragma("unroll") for (int bj = 0; bj < 2; ++bj)
;     DI void operator()(AccRef acc, const Unit& u, int wr, int wc, int fr, int fq) const {
;     ...
;         FOR_ROWS { const int row = row0 + ai * 128 + m * 16; float s = 0.f;
;             FOR_BJ { const size_t off = (size_t)row * 2048 + u.pn * 256 + bj * 128 + c8;
;                 const f32x4 v0 = *(const f32x4*)(base + off) + acc[ai][bj][m][0], v1 = *(const f32x4*)(base + off + 4) + acc[ai][bj][m][1];
;                 *(f32x4*)(out + off) = v0; *(f32x4*)(out + off + 4) = v1;
;                 if (WITH_B) { store8_bf16(outb + off, v0, v1); s += dot4(v0) + dot4(v1); } }
;             if (WITH_B) { s += shx<16>(s, fr | (fq << 4)); s += shx<32>(s, fr | (fq << 4)); if (fq == 0) atomic_addf(ssq + row, s); } }
.LBB0_1729:
	v_lshl_add_u32 v148, s48, 8, v137
	s_lshl_b32 s23, s50, 8
	s_ashr_i32 s25, s23, 31
	v_ashrrev_i32_e32 v149, 31, v148
	v_mov_b32_e32 v147, s25
	v_or_b32_e32 v146, s23, v136
	v_lshlrev_b64 v[156:157], 11, v[148:149]
	v_lshl_add_u64 v[164:165], v[156:157], 0, v[146:147]
	v_lshlrev_b64 v[166:167], 2, v[164:165]
	v_lshl_add_u64 v[168:169], s[14:15], 0, v[166:167]
	v_mov_b32_e32 v224, v168
	v_mov_b32_e32 v225, v169
	v_mov_b32_e32 v226, 0x20000
	v_mov_b32_e32 v227, 0
	global_load_dwordx4 v[172:175], v[224:225], off
	global_load_dwordx4 v[176:179], v[224:225], off offset:16
	global_load_dwordx4 v[180:183], v[224:225], off offset:512
	global_load_dwordx4 v[184:187], v[224:225], off offset:528
	v_lshl_add_u64 v[224:225], v[224:225], 0, v[226:227]
	global_load_dwordx4 v[188:191], v[224:225], off
	global_load_dwordx4 v[192:195], v[224:225], off offset:16
	global_load_dwordx4 v[196:199], v[224:225], off offset:512
	global_load_dwordx4 v[200:203], v[224:225], off offset:528
	v_lshl_add_u64 v[224:225], v[224:225], 0, v[226:227]
	global_load_dwordx4 v[204:207], v[224:225], off
	global_load_dwordx4 v[208:211], v[224:225], off offset:16
	global_load_dwordx4 v[212:215], v[224:225], off offset:512
	global_load_dwordx4 v[216:219], v[224:225], off offset:528
	v_lshl_add_u64 v[224:225], v[224:225], 0, v[226:227]
	global_load_dwordx4 v[220:223], v[224:225], off
	global_load_dwordx4 v[228:231], v[224:225], off offset:16
	global_load_dwordx4 v[232:235], v[224:225], off offset:512
	global_load_dwordx4 v[236:239], v[224:225], off offset:528
	v_lshl_add_u64 v[224:225], v[226:227], 2, v[224:225]
	v_lshl_add_u64 v[224:225], v[224:225], 0, v[226:227]
	global_load_dwordx4 v[244:247], v[224:225], off
	global_load_dwordx4 v[248:251], v[224:225], off offset:16
	s_waitcnt vmcnt(17)
	s_nop 1
	v_mov_b32_e32 v156, v172
	v_mov_b32_e32 v157, v173
	v_mov_b32_e32 v158, v174
	v_mov_b32_e32 v159, v175
	global_load_dwordx4 v[172:175], v[224:225], off offset:512
	s_waitcnt vmcnt(17)
	s_nop 1
	v_mov_b32_e32 v160, v176
	v_mov_b32_e32 v161, v177
	v_mov_b32_e32 v162, v178
	v_mov_b32_e32 v163, v179
	global_load_dwordx4 v[176:179], v[224:225], off offset:528
	v_lshlrev_b64 v[164:165], 1, v[164:165]
	v_lshl_add_u64 v[166:167], s[34:35], 0, v[166:167]
	v_lshl_add_u64 v[170:171], s[44:45], 0, v[164:165]
	v_or_b32_e32 v164, 0x100, v164
	v_pk_add_f32 v[126:127], v[126:127], v[158:159]
	v_pk_add_f32 v[124:125], v[124:125], v[156:157]
	v_pk_add_f32 v[122:123], v[122:123], v[162:163]
	v_pk_add_f32 v[120:121], v[120:121], v[160:161]
	v_cvt_pk_bf16_f32 v156, v124, v125
	v_cvt_pk_bf16_f32 v157, v126, v127
	v_cvt_pk_bf16_f32 v158, v120, v121
	v_cvt_pk_bf16_f32 v159, v122, v123
	global_store_dwordx4 v[166:167], v[124:127], off
	global_store_dwordx4 v[166:167], v[120:123], off offset:16
	global_store_dwordx4 v[170:171], v[156:159], off
	s_waitcnt vmcnt(20)
	s_nop 1
	v_mov_b32_e32 v156, v180
	v_mov_b32_e32 v157, v181
	v_mov_b32_e32 v158, v182
	v_mov_b32_e32 v159, v183
	v_lshl_add_u64 v[224:225], v[224:225], 0, v[226:227]
	global_load_dwordx4 v[180:183], v[224:225], off
	s_nop 0
	s_waitcnt vmcnt(20)
	s_nop 1
	v_mov_b32_e32 v160, v184
	v_mov_b32_e32 v161, v185
	v_mov_b32_e32 v162, v186
	v_mov_b32_e32 v163, v187
	global_load_dwordx4 v[184:187], v[224:225], off offset:16
	v_mul_f32_e32 v125, v125, v125
	v_mul_f32_e32 v127, v127, v127
	v_mul_f32_e32 v121, v121, v121
	v_mul_f32_e32 v123, v123, v123
	v_fmac_f32_e32 v125, v124, v124
	v_fmac_f32_e32 v127, v126, v126
	v_fmac_f32_e32 v121, v120, v120
	v_fmac_f32_e32 v123, v122, v122
	v_add_f32_e32 v120, v125, v127
	v_add_f32_e32 v121, v121, v123
	v_add_f32_e32 v124, v120, v121
	v_pk_add_f32 v[118:119], v[118:119], v[158:159]
	v_pk_add_f32 v[116:117], v[116:117], v[156:157]
	v_pk_add_f32 v[122:123], v[114:115], v[162:163]
	v_pk_add_f32 v[120:121], v[112:113], v[160:161]
	v_mul_f32_e32 v112, v117, v117
	v_mul_f32_e32 v113, v119, v119
	v_mul_f32_e32 v114, v121, v121
	v_mul_f32_e32 v115, v123, v123
	v_fmac_f32_e32 v112, v116, v116
	v_fmac_f32_e32 v113, v118, v118
	v_fmac_f32_e32 v114, v120, v120
	v_fmac_f32_e32 v115, v122, v122
	v_add_f32_e32 v112, v112, v113
	v_add_f32_e32 v113, v114, v115
	v_add_f32_e32 v112, v112, v113
	v_add_f32_e32 v112, v124, v112
	ds_bpermute_b32 v113, v151, v112
	global_store_dwordx4 v[166:167], v[116:119], off offset:512
	v_lshl_add_u64 v[124:125], s[44:45], 0, v[164:165]
	v_cvt_pk_bf16_f32 v114, v116, v117
	v_cvt_pk_bf16_f32 v115, v118, v119
	s_waitcnt lgkmcnt(0)
	v_add_f32_e32 v112, v112, v113
	ds_bpermute_b32 v113, v152, v112
	v_cvt_pk_bf16_f32 v116, v120, v121
	v_cvt_pk_bf16_f32 v117, v122, v123
	global_store_dwordx4 v[166:167], v[120:123], off offset:528
	global_store_dwordx4 v[124:125], v[114:117], off
	s_and_saveexec_b64 s[48:49], s[6:7]
	s_cbranch_execz .LBB0_1731
	v_lshl_add_u64 v[114:115], v[148:149], 2, s[12:13]
	s_waitcnt lgkmcnt(0)
	v_add_f32_e32 v112, v112, v113
	global_atomic_add_f32 v[114:115], v112, off
; template <int MASK> DI float shx(float v, int lane) { return __builtin_bit_cast(float, __builtin_amdgcn_ds_bpermute((lane ^ MASK) << 2, __builtin_bit_cast(int, v))); }
; DI void atomic_addf(float* p, float v) { (void)__hip_atomic_fetch_add(p, v, __ATOMIC_RELAXED, __HIP_MEMORY_SCOPE_AGENT); }
; DI float dot4(f32x4 v) { return (v[0] * v[0] + v[1] * v[1]) + (v[2] * v[2] + v[3] * v[3]); }
; #define FOR_ROWS _Pragma("unroll") for (int ai = 0; ai < 2; ++ai) _Pragma("unroll") for (int m = 0; m < 4; ++m)
; #define FOR_BJ _Pragma("unroll") for (int bj = 0; bj < 2; ++bj)
;     DI void operator()(AccRef acc, const Unit& u, int wr, int wc, int fr, int fq) const {
;     ...
;         FOR_ROWS { const int row = row0 + ai * 128 + m * 16; float s = 0.f;
;             FOR_BJ { const size_t off = (size_t)row * 2048 + u.pn * 256 + bj * 128 + c8;
;                 const f32x4 v0 = *(const f32x4*)(base + off) + acc[ai][bj][m][0], v1 = *(const f32x4*)(base + off + 4) + acc[ai][bj][m][1];
;                 *(f32x4*)(out + off) = v0; *(f32x4*)(out + off + 4) = v1;
;                 if (WITH_B) { store8_bf16(outb + off, v0, v1); s += dot4(v0) + dot4(v1); } }
;             if (WITH_B) { s += shx<16>(s, fr | (fq << 4)); s += shx<32>(s, fr | (fq << 4)); if (fq == 0) atomic_addf(ssq + row, s); } }
.LBB0_1731:
	s_or_b64 exec, exec, s[48:49]
	v_or_b32_e32 v112, 16, v148
	s_waitcnt lgkmcnt(0)
	v_ashrrev_i32_e32 v113, 31, v112
	v_lshlrev_b64 v[114:115], 11, v[112:113]
	v_lshl_add_u64 v[122:123], v[114:115], 0, v[146:147]
	v_lshlrev_b64 v[124:125], 2, v[122:123]
	v_lshl_add_u64 v[126:127], s[14:15], 0, v[124:125]
	s_waitcnt vmcnt(23)
	s_nop 1
	v_mov_b32_e32 v114, v188
	v_mov_b32_e32 v115, v189
	v_mov_b32_e32 v116, v190
	v_mov_b32_e32 v117, v191
	global_load_dwordx4 v[188:191], v[224:225], off offset:512
	s_waitcnt vmcnt(23)
	s_nop 1
	v_mov_b32_e32 v118, v192
	v_mov_b32_e32 v119, v193
	v_mov_b32_e32 v120, v194
	v_mov_b32_e32 v121, v195
	global_load_dwordx4 v[192:195], v[224:225], off offset:528
	v_lshlrev_b64 v[122:123], 1, v[122:123]
	v_lshl_add_u64 v[124:125], s[34:35], 0, v[124:125]
	v_lshl_add_u64 v[156:157], s[44:45], 0, v[122:123]
	v_or_b32_e32 v122, 0x100, v122
	v_pk_add_f32 v[110:111], v[110:111], v[116:117]
	v_pk_add_f32 v[108:109], v[108:109], v[114:115]
	v_pk_add_f32 v[106:107], v[106:107], v[120:121]
	v_pk_add_f32 v[104:105], v[104:105], v[118:119]
	v_cvt_pk_bf16_f32 v114, v108, v109
	v_cvt_pk_bf16_f32 v115, v110, v111
	v_cvt_pk_bf16_f32 v116, v104, v105
	v_cvt_pk_bf16_f32 v117, v106, v107
	global_store_dwordx4 v[124:125], v[108:111], off
	global_store_dwordx4 v[124:125], v[104:107], off offset:16
	global_store_dwordx4 v[156:157], v[114:117], off
	s_waitcnt vmcnt(26)
	s_nop 1
	v_mov_b32_e32 v114, v196
	v_mov_b32_e32 v115, v197
	v_mov_b32_e32 v116, v198
	v_mov_b32_e32 v117, v199
	v_lshl_add_u64 v[224:225], v[224:225], 0, v[226:227]
	global_load_dwordx4 v[196:199], v[224:225], off
	s_nop 0
	s_waitcnt vmcnt(26)
	s_nop 1
	v_mov_b32_e32 v118, v200
	v_mov_b32_e32 v119, v201
	v_mov_b32_e32 v120, v202
	v_mov_b32_e32 v121, v203
	global_load_dwordx4 v[200:203], v[224:225], off offset:16
	v_mul_f32_e32 v109, v109, v109
	v_mul_f32_e32 v111, v111, v111
	v_mul_f32_e32 v105, v105, v105
	v_mul_f32_e32 v107, v107, v107
	v_fmac_f32_e32 v109, v108, v108
	v_fmac_f32_e32 v111, v110, v110
	v_fmac_f32_e32 v105, v104, v104
	v_fmac_f32_e32 v107, v106, v106
	v_add_f32_e32 v104, v109, v111
	v_add_f32_e32 v105, v105, v107
	v_add_f32_e32 v108, v104, v105
	v_pk_add_f32 v[102:103], v[102:103], v[116:117]
	v_pk_add_f32 v[100:101], v[100:101], v[114:115]
	v_pk_add_f32 v[106:107], v[98:99], v[120:121]
	v_pk_add_f32 v[104:105], v[96:97], v[118:119]
	v_mul_f32_e32 v96, v101, v101
	v_mul_f32_e32 v97, v103, v103
	v_mul_f32_e32 v98, v105, v105
	v_mul_f32_e32 v99, v107, v107
	v_fmac_f32_e32 v96, v100, v100
	v_fmac_f32_e32 v97, v102, v102
	v_fmac_f32_e32 v98, v104, v104
	v_fmac_f32_e32 v99, v106, v106
	v_add_f32_e32 v96, v96, v97
	v_add_f32_e32 v97, v98, v99
	v_add_f32_e32 v96, v96, v97
	v_add_f32_e32 v96, v108, v96
	ds_bpermute_b32 v97, v151, v96
	global_store_dwordx4 v[124:125], v[100:103], off offset:512
	v_lshl_add_u64 v[108:109], s[44:45], 0, v[122:123]
	v_cvt_pk_bf16_f32 v98, v100, v101
	v_cvt_pk_bf16_f32 v99, v102, v103
	s_waitcnt lgkmcnt(0)
	v_add_f32_e32 v96, v96, v97
	ds_bpermute_b32 v97, v152, v96
	v_cvt_pk_bf16_f32 v100, v104, v105
	v_cvt_pk_bf16_f32 v101, v106, v107
	global_store_dwordx4 v[124:125], v[104:107], off offset:528
	global_store_dwordx4 v[108:109], v[98:101], off
	s_and_saveexec_b64 s[48:49], s[6:7]
	s_cbranch_execz .LBB0_1733
	v_lshl_add_u64 v[98:99], v[112:113], 2, s[12:13]
	s_waitcnt lgkmcnt(0)
	v_add_f32_e32 v96, v96, v97
	global_atomic_add_f32 v[98:99], v96, off
.LBB0_1733:
	s_or_b64 exec, exec, s[48:49]
	v_or_b32_e32 v96, 32, v148
	s_waitcnt lgkmcnt(0)
	v_ashrrev_i32_e32 v97, 31, v96
	v_lshlrev_b64 v[98:99], 11, v[96:97]
	v_lshl_add_u64 v[106:107], v[98:99], 0, v[146:147]
	v_lshlrev_b64 v[108:109], 2, v[106:107]
	v_lshl_add_u64 v[110:111], s[14:15], 0, v[108:109]
	s_waitcnt vmcnt(29)
	s_nop 1
	v_mov_b32_e32 v98, v204
	v_mov_b32_e32 v99, v205
	v_mov_b32_e32 v100, v206
	v_mov_b32_e32 v101, v207
	global_load_dwordx4 v[204:207], v[224:225], off offset:512
	s_waitcnt vmcnt(29)
	s_nop 1
	v_mov_b32_e32 v102, v208
	v_mov_b32_e32 v103, v209
	v_mov_b32_e32 v104, v210
	v_mov_b32_e32 v105, v211
	global_load_dwordx4 v[208:211], v[224:225], off offset:528
	v_lshlrev_b64 v[106:107], 1, v[106:107]
	v_lshl_add_u64 v[108:109], s[34:35], 0, v[108:109]
	v_lshl_add_u64 v[112:113], s[44:45], 0, v[106:107]
	v_or_b32_e32 v106, 0x100, v106
	v_pk_add_f32 v[94:95], v[94:95], v[100:101]
	v_pk_add_f32 v[92:93], v[92:93], v[98:99]
	v_pk_add_f32 v[90:91], v[90:91], v[104:105]
	v_pk_add_f32 v[88:89], v[88:89], v[102:103]
	v_cvt_pk_bf16_f32 v98, v92, v93
	v_cvt_pk_bf16_f32 v99, v94, v95
	v_cvt_pk_bf16_f32 v100, v88, v89
	v_cvt_pk_bf16_f32 v101, v90, v91
	global_store_dwordx4 v[108:109], v[92:95], off
	global_store_dwordx4 v[108:109], v[88:91], off offset:16
	global_store_dwordx4 v[112:113], v[98:101], off
	s_waitcnt vmcnt(32)
	s_nop 1
	v_mov_b32_e32 v98, v212
	v_mov_b32_e32 v99, v213
	v_mov_b32_e32 v100, v214
	v_mov_b32_e32 v101, v215
	v_lshl_add_u64 v[224:225], v[224:225], 0, v[226:227]
	global_load_dwordx4 v[212:215], v[224:225], off
	s_nop 0
	s_waitcnt vmcnt(32)
	s_nop 1
	v_mov_b32_e32 v102, v216
	v_mov_b32_e32 v103, v217
	v_mov_b32_e32 v104, v218
	v_mov_b32_e32 v105, v219
	global_load_dwordx4 v[216:219], v[224:225], off offset:16
	v_mul_f32_e32 v93, v93, v93
	v_mul_f32_e32 v95, v95, v95
	v_mul_f32_e32 v89, v89, v89
	v_mul_f32_e32 v91, v91, v91
	v_fmac_f32_e32 v93, v92, v92
	v_fmac_f32_e32 v95, v94, v94
	v_fmac_f32_e32 v89, v88, v88
	v_fmac_f32_e32 v91, v90, v90
	v_add_f32_e32 v88, v93, v95
	v_add_f32_e32 v89, v89, v91
	v_add_f32_e32 v92, v88, v89
	v_pk_add_f32 v[86:87], v[86:87], v[100:101]
	v_pk_add_f32 v[84:85], v[84:85], v[98:99]
	v_pk_add_f32 v[90:91], v[82:83], v[104:105]
	v_pk_add_f32 v[88:89], v[80:81], v[102:103]
	v_mul_f32_e32 v80, v85, v85
	v_mul_f32_e32 v81, v87, v87
	v_mul_f32_e32 v82, v89, v89
	v_mul_f32_e32 v83, v91, v91
	v_fmac_f32_e32 v80, v84, v84
	v_fmac_f32_e32 v81, v86, v86
	v_fmac_f32_e32 v82, v88, v88
	v_fmac_f32_e32 v83, v90, v90
	v_add_f32_e32 v80, v80, v81
	v_add_f32_e32 v81, v82, v83
	v_add_f32_e32 v80, v80, v81
	v_add_f32_e32 v80, v92, v80
	ds_bpermute_b32 v81, v151, v80
	global_store_dwordx4 v[108:109], v[84:87], off offset:512
	v_lshl_add_u64 v[92:93], s[44:45], 0, v[106:107]
	v_cvt_pk_bf16_f32 v82, v84, v85
	v_cvt_pk_bf16_f32 v83, v86, v87
	s_waitcnt lgkmcnt(0)
	v_add_f32_e32 v80, v80, v81
	ds_bpermute_b32 v81, v152, v80
	v_cvt_pk_bf16_f32 v84, v88, v89
	v_cvt_pk_bf16_f32 v85, v90, v91
	global_store_dwordx4 v[108:109], v[88:91], off offset:528
	global_store_dwordx4 v[92:93], v[82:85], off
	s_and_saveexec_b64 s[48:49], s[6:7]
	s_cbranch_execz .LBB0_1735
	v_lshl_add_u64 v[82:83], v[96:97], 2, s[12:13]
	s_waitcnt lgkmcnt(0)
	v_add_f32_e32 v80, v80, v81
	global_atomic_add_f32 v[82:83], v80, off
; template <int MASK> DI float shx(float v, int lane) { return __builtin_bit_cast(float, __builtin_amdgcn_ds_bpermute((lane ^ MASK) << 2, __builtin_bit_cast(int, v))); }
; DI void atomic_addf(float* p, float v) { (void)__hip_atomic_fetch_add(p, v, __ATOMIC_RELAXED, __HIP_MEMORY_SCOPE_AGENT); }
; DI float dot4(f32x4 v) { return (v[0] * v[0] + v[1] * v[1]) + (v[2] * v[2] + v[3] * v[3]); }
; #define FOR_ROWS _Pragma("unroll") for (int ai = 0; ai < 2; ++ai) _Pragma("unroll") for (int m = 0; m < 4; ++m)
; #define FOR_BJ _Pragma("unroll") for (int bj = 0; bj < 2; ++bj)
;     DI void operator()(AccRef acc, const Unit& u, int wr, int wc, int fr, int fq) const {
;     ...
;         FOR_ROWS { const int row = row0 + ai * 128 + m * 16; float s = 0.f;
;             FOR_BJ { const size_t off = (size_t)row * 2048 + u.pn * 256 + bj * 128 + c8;
;                 const f32x4 v0 = *(const f32x4*)(base + off) + acc[ai][bj][m][0], v1 = *(const f32x4*)(base + off + 4) + acc[ai][bj][m][1];
;                 *(f32x4*)(out + off) = v0; *(f32x4*)(out + off + 4) = v1;
;                 if (WITH_B) { store8_bf16(outb + off, v0, v1); s += dot4(v0) + dot4(v1); } }
;             if (WITH_B) { s += shx<16>(s, fr | (fq << 4)); s += shx<32>(s, fr | (fq << 4)); if (fq == 0) atomic_addf(ssq + row, s); } }
.LBB0_1735:
	s_or_b64 exec, exec, s[48:49]
	v_or_b32_e32 v80, 48, v148
	s_waitcnt lgkmcnt(0)
	v_ashrrev_i32_e32 v81, 31, v80
	v_lshlrev_b64 v[82:83], 11, v[80:81]
	v_lshl_add_u64 v[90:91], v[82:83], 0, v[146:147]
	v_lshlrev_b64 v[92:93], 2, v[90:91]
	v_lshl_add_u64 v[94:95], s[14:15], 0, v[92:93]
	s_waitcnt vmcnt(35)
	s_nop 1
	v_mov_b32_e32 v82, v220
	v_mov_b32_e32 v83, v221
	v_mov_b32_e32 v84, v222
	v_mov_b32_e32 v85, v223
	global_load_dwordx4 v[220:223], v[224:225], off offset:512
	s_waitcnt vmcnt(35)
	s_nop 1
	v_mov_b32_e32 v86, v228
	v_mov_b32_e32 v87, v229
	v_mov_b32_e32 v88, v230
	v_mov_b32_e32 v89, v231
	global_load_dwordx4 v[228:231], v[224:225], off offset:528
	v_lshlrev_b64 v[90:91], 1, v[90:91]
	v_lshl_add_u64 v[92:93], s[34:35], 0, v[92:93]
	v_lshl_add_u64 v[96:97], s[44:45], 0, v[90:91]
	v_or_b32_e32 v90, 0x100, v90
	v_pk_add_f32 v[78:79], v[78:79], v[84:85]
	v_pk_add_f32 v[76:77], v[76:77], v[82:83]
	v_pk_add_f32 v[74:75], v[74:75], v[88:89]
	v_pk_add_f32 v[72:73], v[72:73], v[86:87]
	v_cvt_pk_bf16_f32 v82, v76, v77
	v_cvt_pk_bf16_f32 v83, v78, v79
	v_cvt_pk_bf16_f32 v84, v72, v73
	v_cvt_pk_bf16_f32 v85, v74, v75
	global_store_dwordx4 v[92:93], v[76:79], off
	global_store_dwordx4 v[92:93], v[72:75], off offset:16
	global_store_dwordx4 v[96:97], v[82:85], off
	s_waitcnt vmcnt(38)
	s_nop 1
	v_mov_b32_e32 v82, v232
	v_mov_b32_e32 v83, v233
	v_mov_b32_e32 v84, v234
	v_mov_b32_e32 v85, v235
	s_nop 0
	s_waitcnt vmcnt(37)
	s_nop 1
	v_mov_b32_e32 v86, v236
	v_mov_b32_e32 v87, v237
	v_mov_b32_e32 v88, v238
	v_mov_b32_e32 v89, v239
	v_mul_f32_e32 v77, v77, v77
	v_mul_f32_e32 v79, v79, v79
	v_mul_f32_e32 v73, v73, v73
	v_mul_f32_e32 v75, v75, v75
	v_fmac_f32_e32 v77, v76, v76
	v_fmac_f32_e32 v79, v78, v78
	v_fmac_f32_e32 v73, v72, v72
	v_fmac_f32_e32 v75, v74, v74
	v_add_f32_e32 v72, v77, v79
	v_add_f32_e32 v73, v73, v75
	v_add_f32_e32 v76, v72, v73
	v_pk_add_f32 v[70:71], v[70:71], v[84:85]
	v_pk_add_f32 v[68:69], v[68:69], v[82:83]
	v_pk_add_f32 v[74:75], v[66:67], v[88:89]
	v_pk_add_f32 v[72:73], v[64:65], v[86:87]
	v_mul_f32_e32 v64, v69, v69
	v_mul_f32_e32 v65, v71, v71
	v_mul_f32_e32 v66, v73, v73
	v_mul_f32_e32 v67, v75, v75
	v_fmac_f32_e32 v64, v68, v68
	v_fmac_f32_e32 v65, v70, v70
	v_fmac_f32_e32 v66, v72, v72
	v_fmac_f32_e32 v67, v74, v74
	v_add_f32_e32 v64, v64, v65
	v_add_f32_e32 v65, v66, v67
	v_add_f32_e32 v64, v64, v65
	v_add_f32_e32 v64, v76, v64
	ds_bpermute_b32 v65, v151, v64
	global_store_dwordx4 v[92:93], v[68:71], off offset:512
	v_lshl_add_u64 v[76:77], s[44:45], 0, v[90:91]
	v_cvt_pk_bf16_f32 v66, v68, v69
	v_cvt_pk_bf16_f32 v67, v70, v71
	s_waitcnt lgkmcnt(0)
	v_add_f32_e32 v64, v64, v65
	ds_bpermute_b32 v65, v152, v64
	v_cvt_pk_bf16_f32 v68, v72, v73
	v_cvt_pk_bf16_f32 v69, v74, v75
	global_store_dwordx4 v[92:93], v[72:75], off offset:528
	global_store_dwordx4 v[76:77], v[66:69], off
	s_and_saveexec_b64 s[48:49], s[6:7]
	s_cbranch_execz .LBB0_1737
	v_lshl_add_u64 v[66:67], v[80:81], 2, s[12:13]
	s_waitcnt lgkmcnt(0)
	v_add_f32_e32 v64, v64, v65
	global_atomic_add_f32 v[66:67], v64, off
.LBB0_1737:
	s_or_b64 exec, exec, s[48:49]
	v_add_u32_e32 v64, 0x80, v148
	s_waitcnt lgkmcnt(0)
	v_ashrrev_i32_e32 v65, 31, v64
	v_lshlrev_b64 v[66:67], 11, v[64:65]
	v_lshl_add_u64 v[74:75], v[66:67], 0, v[146:147]
	v_lshlrev_b64 v[76:77], 2, v[74:75]
	v_lshl_add_u64 v[78:79], s[14:15], 0, v[76:77]
	s_waitcnt vmcnt(39)
	s_nop 1
	v_mov_b32_e32 v66, v244
	v_mov_b32_e32 v67, v245
	v_mov_b32_e32 v68, v246
	v_mov_b32_e32 v69, v247
	s_waitcnt vmcnt(38)
	s_nop 1
	v_mov_b32_e32 v70, v248
	v_mov_b32_e32 v71, v249
	v_mov_b32_e32 v72, v250
	v_mov_b32_e32 v73, v251
	v_lshlrev_b64 v[74:75], 1, v[74:75]
	v_lshl_add_u64 v[76:77], s[34:35], 0, v[76:77]
	v_lshl_add_u64 v[80:81], s[44:45], 0, v[74:75]
	v_or_b32_e32 v74, 0x100, v74
	v_pk_add_f32 v[62:63], v[62:63], v[68:69]
	v_pk_add_f32 v[60:61], v[60:61], v[66:67]
	v_pk_add_f32 v[58:59], v[58:59], v[72:73]
	v_pk_add_f32 v[56:57], v[56:57], v[70:71]
	v_cvt_pk_bf16_f32 v66, v60, v61
	v_cvt_pk_bf16_f32 v67, v62, v63
	v_cvt_pk_bf16_f32 v68, v56, v57
	v_cvt_pk_bf16_f32 v69, v58, v59
	global_store_dwordx4 v[76:77], v[60:63], off
	global_store_dwordx4 v[76:77], v[56:59], off offset:16
	global_store_dwordx4 v[80:81], v[66:69], off
	s_waitcnt vmcnt(40)
	s_nop 1
	v_mov_b32_e32 v66, v172
	v_mov_b32_e32 v67, v173
	v_mov_b32_e32 v68, v174
	v_mov_b32_e32 v69, v175
	s_nop 0
	s_waitcnt vmcnt(39)
	s_nop 1
	v_mov_b32_e32 v70, v176
	v_mov_b32_e32 v71, v177
	v_mov_b32_e32 v72, v178
	v_mov_b32_e32 v73, v179
	v_mul_f32_e32 v61, v61, v61
	v_mul_f32_e32 v63, v63, v63
	v_mul_f32_e32 v57, v57, v57
	v_mul_f32_e32 v59, v59, v59
	v_fmac_f32_e32 v61, v60, v60
	v_fmac_f32_e32 v63, v62, v62
	v_fmac_f32_e32 v57, v56, v56
	v_fmac_f32_e32 v59, v58, v58
	v_add_f32_e32 v56, v61, v63
	v_add_f32_e32 v57, v57, v59
	v_add_f32_e32 v60, v56, v57
	v_pk_add_f32 v[54:55], v[54:55], v[68:69]
	v_pk_add_f32 v[52:53], v[52:53], v[66:67]
	v_pk_add_f32 v[58:59], v[50:51], v[72:73]
	v_pk_add_f32 v[56:57], v[48:49], v[70:71]
	v_mul_f32_e32 v48, v53, v53
	v_mul_f32_e32 v49, v55, v55
	v_mul_f32_e32 v50, v57, v57
	v_mul_f32_e32 v51, v59, v59
	v_fmac_f32_e32 v48, v52, v52
	v_fmac_f32_e32 v49, v54, v54
	v_fmac_f32_e32 v50, v56, v56
	v_fmac_f32_e32 v51, v58, v58
	v_add_f32_e32 v48, v48, v49
	v_add_f32_e32 v49, v50, v51
	v_add_f32_e32 v48, v48, v49
	v_add_f32_e32 v48, v60, v48
	ds_bpermute_b32 v49, v151, v48
	global_store_dwordx4 v[76:77], v[52:55], off offset:512
	v_lshl_add_u64 v[60:61], s[44:45], 0, v[74:75]
	v_cvt_pk_bf16_f32 v50, v52, v53
	v_cvt_pk_bf16_f32 v51, v54, v55
	s_waitcnt lgkmcnt(0)
	v_add_f32_e32 v48, v48, v49
	ds_bpermute_b32 v49, v152, v48
	v_cvt_pk_bf16_f32 v52, v56, v57
	v_cvt_pk_bf16_f32 v53, v58, v59
	global_store_dwordx4 v[76:77], v[56:59], off offset:528
	global_store_dwordx4 v[60:61], v[50:53], off
	s_and_saveexec_b64 s[48:49], s[6:7]
	s_cbranch_execz .LBB0_1739
	v_lshl_add_u64 v[50:51], v[64:65], 2, s[12:13]
	s_waitcnt lgkmcnt(0)
	v_add_f32_e32 v48, v48, v49
	global_atomic_add_f32 v[50:51], v48, off
; template <int MASK> DI float shx(float v, int lane) { return __builtin_bit_cast(float, __builtin_amdgcn_ds_bpermute((lane ^ MASK) << 2, __builtin_bit_cast(int, v))); }
; DI void atomic_addf(float* p, float v) { (void)__hip_atomic_fetch_add(p, v, __ATOMIC_RELAXED, __HIP_MEMORY_SCOPE_AGENT); }
; DI float dot4(f32x4 v) { return (v[0] * v[0] + v[1] * v[1]) + (v[2] * v[2] + v[3] * v[3]); }
; #define FOR_ROWS _Pragma("unroll") for (int ai = 0; ai < 2; ++ai) _Pragma("unroll") for (int m = 0; m < 4; ++m)
; #define FOR_BJ _Pragma("unroll") for (int bj = 0; bj < 2; ++bj)
;     DI void operator()(AccRef acc, const Unit& u, int wr, int wc, int fr, int fq) const {
;     ...
;         FOR_ROWS { const int row = row0 + ai * 128 + m * 16; float s = 0.f;
;             FOR_BJ { const size_t off = (size_t)row * 2048 + u.pn * 256 + bj * 128 + c8;
;                 const f32x4 v0 = *(const f32x4*)(base + off) + acc[ai][bj][m][0], v1 = *(const f32x4*)(base + off + 4) + acc[ai][bj][m][1];
;                 *(f32x4*)(out + off) = v0; *(f32x4*)(out + off + 4) = v1;
;                 if (WITH_B) { store8_bf16(outb + off, v0, v1); s += dot4(v0) + dot4(v1); } }
;             if (WITH_B) { s += shx<16>(s, fr | (fq << 4)); s += shx<32>(s, fr | (fq << 4)); if (fq == 0) atomic_addf(ssq + row, s); } }
.LBB0_1739:
	s_or_b64 exec, exec, s[48:49]
	v_add_u32_e32 v48, 0x90, v148
	s_waitcnt lgkmcnt(0)
	v_ashrrev_i32_e32 v49, 31, v48
	v_lshlrev_b64 v[50:51], 11, v[48:49]
	v_lshl_add_u64 v[58:59], v[50:51], 0, v[146:147]
	v_lshlrev_b64 v[60:61], 2, v[58:59]
	v_lshl_add_u64 v[62:63], s[14:15], 0, v[60:61]
	s_waitcnt vmcnt(38)
	s_nop 1
	v_mov_b32_e32 v50, v180
	v_mov_b32_e32 v51, v181
	v_mov_b32_e32 v52, v182
	v_mov_b32_e32 v53, v183
	s_waitcnt vmcnt(37)
	s_nop 1
	v_mov_b32_e32 v54, v184
	v_mov_b32_e32 v55, v185
	v_mov_b32_e32 v56, v186
	v_mov_b32_e32 v57, v187
	v_lshlrev_b64 v[58:59], 1, v[58:59]
	v_lshl_add_u64 v[60:61], s[34:35], 0, v[60:61]
	v_lshl_add_u64 v[64:65], s[44:45], 0, v[58:59]
	v_or_b32_e32 v58, 0x100, v58
	v_pk_add_f32 v[46:47], v[46:47], v[52:53]
	v_pk_add_f32 v[44:45], v[44:45], v[50:51]
	v_pk_add_f32 v[42:43], v[42:43], v[56:57]
	v_pk_add_f32 v[40:41], v[40:41], v[54:55]
	v_cvt_pk_bf16_f32 v50, v44, v45
	v_cvt_pk_bf16_f32 v51, v46, v47
	v_cvt_pk_bf16_f32 v52, v40, v41
	v_cvt_pk_bf16_f32 v53, v42, v43
	global_store_dwordx4 v[60:61], v[44:47], off
	global_store_dwordx4 v[60:61], v[40:43], off offset:16
	global_store_dwordx4 v[64:65], v[50:53], off
	s_waitcnt vmcnt(36)
	s_nop 1
	v_mov_b32_e32 v50, v188
	v_mov_b32_e32 v51, v189
	v_mov_b32_e32 v52, v190
	v_mov_b32_e32 v53, v191
	s_nop 0
	s_waitcnt vmcnt(35)
	s_nop 1
	v_mov_b32_e32 v54, v192
	v_mov_b32_e32 v55, v193
	v_mov_b32_e32 v56, v194
	v_mov_b32_e32 v57, v195
	v_mul_f32_e32 v45, v45, v45
	v_mul_f32_e32 v47, v47, v47
	v_mul_f32_e32 v41, v41, v41
	v_mul_f32_e32 v43, v43, v43
	v_fmac_f32_e32 v45, v44, v44
	v_fmac_f32_e32 v47, v46, v46
	v_fmac_f32_e32 v41, v40, v40
	v_fmac_f32_e32 v43, v42, v42
	v_add_f32_e32 v40, v45, v47
	v_add_f32_e32 v41, v41, v43
	v_add_f32_e32 v44, v40, v41
	v_pk_add_f32 v[38:39], v[38:39], v[52:53]
	v_pk_add_f32 v[36:37], v[36:37], v[50:51]
	v_pk_add_f32 v[42:43], v[34:35], v[56:57]
	v_pk_add_f32 v[40:41], v[32:33], v[54:55]
	v_mul_f32_e32 v32, v37, v37
	v_mul_f32_e32 v33, v39, v39
	v_mul_f32_e32 v34, v41, v41
	v_mul_f32_e32 v35, v43, v43
	v_fmac_f32_e32 v32, v36, v36
	v_fmac_f32_e32 v33, v38, v38
	v_fmac_f32_e32 v34, v40, v40
	v_fmac_f32_e32 v35, v42, v42
	v_add_f32_e32 v32, v32, v33
	v_add_f32_e32 v33, v34, v35
	v_add_f32_e32 v32, v32, v33
	v_add_f32_e32 v32, v44, v32
	ds_bpermute_b32 v33, v151, v32
	global_store_dwordx4 v[60:61], v[36:39], off offset:512
	v_lshl_add_u64 v[44:45], s[44:45], 0, v[58:59]
	v_cvt_pk_bf16_f32 v34, v36, v37
	v_cvt_pk_bf16_f32 v35, v38, v39
	s_waitcnt lgkmcnt(0)
	v_add_f32_e32 v32, v32, v33
	ds_bpermute_b32 v33, v152, v32
	v_cvt_pk_bf16_f32 v36, v40, v41
	v_cvt_pk_bf16_f32 v37, v42, v43
	global_store_dwordx4 v[60:61], v[40:43], off offset:528
	global_store_dwordx4 v[44:45], v[34:37], off
	s_and_saveexec_b64 s[48:49], s[6:7]
	s_cbranch_execz .LBB0_1741
	v_lshl_add_u64 v[34:35], v[48:49], 2, s[12:13]
	s_waitcnt lgkmcnt(0)
	v_add_f32_e32 v32, v32, v33
	global_atomic_add_f32 v[34:35], v32, off
; template <int MASK> DI float shx(float v, int lane) { return __builtin_bit_cast(float, __builtin_amdgcn_ds_bpermute((lane ^ MASK) << 2, __builtin_bit_cast(int, v))); }
; DI void atomic_addf(float* p, float v) { (void)__hip_atomic_fetch_add(p, v, __ATOMIC_RELAXED, __HIP_MEMORY_SCOPE_AGENT); }
; DI float dot4(f32x4 v) { return (v[0] * v[0] + v[1] * v[1]) + (v[2] * v[2] + v[3] * v[3]); }
; #define FOR_ROWS _Pragma("unroll") for (int ai = 0; ai < 2; ++ai) _Pragma("unroll") for (int m = 0; m < 4; ++m)
; #define FOR_BJ _Pragma("unroll") for (int bj = 0; bj < 2; ++bj)
;     DI void operator()(AccRef acc, const Unit& u, int wr, int wc, int fr, int fq) const {
;         const int row0 = u.pm * 256 + wr * 64 + fr, c8 = wc * 32 + 8 * fq;
;         FOR_ROWS { const int row = row0 + ai * 128 + m * 16; float s = 0.f;
;             FOR_BJ { const size_t off = (size_t)row * 2048 + u.pn * 256 + bj * 128 + c8;
;                 const f32x4 v0 = *(const f32x4*)(base + off) + acc[ai][bj][m][0], v1 = *(const f32x4*)(base + off + 4) + acc[ai][bj][m][1];
;                 *(f32x4*)(out + off) = v0; *(f32x4*)(out + off + 4) = v1;
;                 if (WITH_B) { store8_bf16(outb + off, v0, v1); s += dot4(v0) + dot4(v1); } }
;             if (WITH_B) { s += shx<16>(s, fr | (fq << 4)); s += shx<32>(s, fr | (fq << 4)); if (fq == 0) atomic_addf(ssq + row, s); } }
;     }
.LBB0_1741:
	s_or_b64 exec, exec, s[48:49]
	v_add_u32_e32 v32, 0xa0, v148
	s_waitcnt lgkmcnt(0)
	v_ashrrev_i32_e32 v33, 31, v32
	v_lshlrev_b64 v[34:35], 11, v[32:33]
	v_lshl_add_u64 v[42:43], v[34:35], 0, v[146:147]
	v_lshlrev_b64 v[44:45], 2, v[42:43]
	v_lshl_add_u64 v[46:47], s[14:15], 0, v[44:45]
	s_waitcnt vmcnt(34)
	s_nop 1
	v_mov_b32_e32 v34, v196
	v_mov_b32_e32 v35, v197
	v_mov_b32_e32 v36, v198
	v_mov_b32_e32 v37, v199
	s_waitcnt vmcnt(33)
	s_nop 1
	v_mov_b32_e32 v38, v200
	v_mov_b32_e32 v39, v201
	v_mov_b32_e32 v40, v202
	v_mov_b32_e32 v41, v203
	v_lshlrev_b64 v[42:43], 1, v[42:43]
	v_lshl_add_u64 v[44:45], s[34:35], 0, v[44:45]
	v_lshl_add_u64 v[48:49], s[44:45], 0, v[42:43]
	v_or_b32_e32 v42, 0x100, v42
	v_pk_add_f32 v[30:31], v[30:31], v[36:37]
	v_pk_add_f32 v[28:29], v[28:29], v[34:35]
	v_pk_add_f32 v[26:27], v[26:27], v[40:41]
	v_pk_add_f32 v[24:25], v[24:25], v[38:39]
	v_cvt_pk_bf16_f32 v34, v28, v29
	v_cvt_pk_bf16_f32 v35, v30, v31
	v_cvt_pk_bf16_f32 v36, v24, v25
	v_cvt_pk_bf16_f32 v37, v26, v27
	global_store_dwordx4 v[44:45], v[28:31], off
	global_store_dwordx4 v[44:45], v[24:27], off offset:16
	global_store_dwordx4 v[48:49], v[34:37], off
	s_waitcnt vmcnt(32)
	s_nop 1
	v_mov_b32_e32 v34, v204
	v_mov_b32_e32 v35, v205
	v_mov_b32_e32 v36, v206
	v_mov_b32_e32 v37, v207
	s_nop 0
	s_waitcnt vmcnt(31)
	s_nop 1
	v_mov_b32_e32 v38, v208
	v_mov_b32_e32 v39, v209
	v_mov_b32_e32 v40, v210
	v_mov_b32_e32 v41, v211
	v_mul_f32_e32 v29, v29, v29
	v_mul_f32_e32 v31, v31, v31
	v_mul_f32_e32 v25, v25, v25
	v_mul_f32_e32 v27, v27, v27
	v_fmac_f32_e32 v29, v28, v28
	v_fmac_f32_e32 v31, v30, v30
	v_fmac_f32_e32 v25, v24, v24
	v_fmac_f32_e32 v27, v26, v26
	v_add_f32_e32 v24, v29, v31
	v_add_f32_e32 v25, v25, v27
	v_add_f32_e32 v28, v24, v25
	v_pk_add_f32 v[22:23], v[22:23], v[36:37]
	v_pk_add_f32 v[20:21], v[20:21], v[34:35]
	v_pk_add_f32 v[26:27], v[18:19], v[40:41]
	v_pk_add_f32 v[24:25], v[16:17], v[38:39]
	v_mul_f32_e32 v16, v21, v21
	v_mul_f32_e32 v17, v23, v23
	v_mul_f32_e32 v18, v25, v25
	v_mul_f32_e32 v19, v27, v27
	v_fmac_f32_e32 v16, v20, v20
	v_fmac_f32_e32 v17, v22, v22
	v_fmac_f32_e32 v18, v24, v24
	v_fmac_f32_e32 v19, v26, v26
	v_add_f32_e32 v16, v16, v17
	v_add_f32_e32 v17, v18, v19
	v_add_f32_e32 v16, v16, v17
	v_add_f32_e32 v16, v28, v16
	ds_bpermute_b32 v17, v151, v16
	global_store_dwordx4 v[44:45], v[20:23], off offset:512
	v_lshl_add_u64 v[28:29], s[44:45], 0, v[42:43]
	v_cvt_pk_bf16_f32 v18, v20, v21
	v_cvt_pk_bf16_f32 v19, v22, v23
	s_waitcnt lgkmcnt(0)
	v_add_f32_e32 v16, v16, v17
	ds_bpermute_b32 v17, v152, v16
	v_cvt_pk_bf16_f32 v20, v24, v25
	v_cvt_pk_bf16_f32 v21, v26, v27
	global_store_dwordx4 v[44:45], v[24:27], off offset:528
	global_store_dwordx4 v[28:29], v[18:21], off
	s_and_saveexec_b64 s[48:49], s[6:7]
	s_cbranch_execz .LBB0_1743
	v_lshl_add_u64 v[18:19], v[32:33], 2, s[12:13]
	s_waitcnt lgkmcnt(0)
	v_add_f32_e32 v16, v16, v17
	global_atomic_add_f32 v[18:19], v16, off
.LBB0_1743:
	s_or_b64 exec, exec, s[48:49]
	v_add_u32_e32 v16, 0xb0, v148
	s_waitcnt lgkmcnt(0)
	v_ashrrev_i32_e32 v17, 31, v16
	v_lshlrev_b64 v[18:19], 11, v[16:17]
	v_lshl_add_u64 v[26:27], v[18:19], 0, v[146:147]
	v_lshlrev_b64 v[28:29], 2, v[26:27]
	v_lshl_add_u64 v[30:31], s[14:15], 0, v[28:29]
	s_waitcnt vmcnt(30)
	s_nop 1
	v_mov_b32_e32 v18, v212
	v_mov_b32_e32 v19, v213
	v_mov_b32_e32 v20, v214
	v_mov_b32_e32 v21, v215
	s_waitcnt vmcnt(29)
	s_nop 1
	v_mov_b32_e32 v22, v216
	v_mov_b32_e32 v23, v217
	v_mov_b32_e32 v24, v218
	v_mov_b32_e32 v25, v219
	v_lshlrev_b64 v[26:27], 1, v[26:27]
	v_lshl_add_u64 v[28:29], s[34:35], 0, v[28:29]
	v_lshl_add_u64 v[32:33], s[44:45], 0, v[26:27]
	v_or_b32_e32 v26, 0x100, v26
	v_pk_add_f32 v[14:15], v[14:15], v[20:21]
	v_pk_add_f32 v[12:13], v[12:13], v[18:19]
	v_pk_add_f32 v[10:11], v[10:11], v[24:25]
	v_pk_add_f32 v[8:9], v[8:9], v[22:23]
	v_cvt_pk_bf16_f32 v18, v12, v13
	v_cvt_pk_bf16_f32 v19, v14, v15
	v_cvt_pk_bf16_f32 v20, v8, v9
	v_cvt_pk_bf16_f32 v21, v10, v11
	global_store_dwordx4 v[28:29], v[12:15], off
	global_store_dwordx4 v[28:29], v[8:11], off offset:16
	global_store_dwordx4 v[32:33], v[18:21], off
	s_waitcnt vmcnt(28)
	s_nop 1
	v_mov_b32_e32 v18, v220
	v_mov_b32_e32 v19, v221
	v_mov_b32_e32 v20, v222
	v_mov_b32_e32 v21, v223
	s_nop 0
	s_waitcnt vmcnt(27)
	s_nop 1
	v_mov_b32_e32 v22, v228
	v_mov_b32_e32 v23, v229
	v_mov_b32_e32 v24, v230
	v_mov_b32_e32 v25, v231
	v_mul_f32_e32 v13, v13, v13
	v_mul_f32_e32 v15, v15, v15
	v_mul_f32_e32 v9, v9, v9
	v_mul_f32_e32 v11, v11, v11
	v_fmac_f32_e32 v13, v12, v12
	v_fmac_f32_e32 v15, v14, v14
	v_fmac_f32_e32 v9, v8, v8
	v_fmac_f32_e32 v11, v10, v10
	v_add_f32_e32 v8, v13, v15
	v_add_f32_e32 v9, v9, v11
	v_add_f32_e32 v12, v8, v9
	v_pk_add_f32 v[6:7], v[6:7], v[20:21]
	v_pk_add_f32 v[4:5], v[4:5], v[18:19]
	v_pk_add_f32 v[10:11], v[2:3], v[24:25]
	v_pk_add_f32 v[8:9], v[0:1], v[22:23]
	v_mul_f32_e32 v0, v5, v5
	v_mul_f32_e32 v1, v7, v7
	v_mul_f32_e32 v2, v9, v9
	v_mul_f32_e32 v3, v11, v11
	v_fmac_f32_e32 v0, v4, v4
	v_fmac_f32_e32 v1, v6, v6
	v_fmac_f32_e32 v2, v8, v8
	v_fmac_f32_e32 v3, v10, v10
	v_add_f32_e32 v0, v0, v1
	v_add_f32_e32 v1, v2, v3
	v_add_f32_e32 v0, v0, v1
	v_add_f32_e32 v0, v12, v0
	ds_bpermute_b32 v1, v151, v0
	global_store_dwordx4 v[28:29], v[4:7], off offset:512
	v_lshl_add_u64 v[12:13], s[44:45], 0, v[26:27]
	v_cvt_pk_bf16_f32 v2, v4, v5
	v_cvt_pk_bf16_f32 v3, v6, v7
	s_waitcnt lgkmcnt(0)
	v_add_f32_e32 v0, v0, v1
	ds_bpermute_b32 v1, v152, v0
	v_cvt_pk_bf16_f32 v4, v8, v9
	v_cvt_pk_bf16_f32 v5, v10, v11
	global_store_dwordx4 v[28:29], v[8:11], off offset:528
	global_store_dwordx4 v[12:13], v[2:5], off
	s_and_saveexec_b64 s[48:49], s[6:7]
	s_cbranch_execz .LBB0_1745
	v_lshl_add_u64 v[2:3], v[16:17], 2, s[12:13]
	s_waitcnt lgkmcnt(0)
	v_add_f32_e32 v0, v0, v1
	global_atomic_add_f32 v[2:3], v0, off

; #define FOR_ROWS _Pragma("unroll") for (int ai = 0; ai < 2; ++ai) _Pragma("unroll") for (int m = 0; m < 4; ++m)
; #define FOR_BJ _Pragma("unroll") for (int bj = 0; bj < 2; ++bj)
;     DI void operator()(AccRef acc, const Unit& u, int wr, int wc, int fr, int fq) const {
;         const int row0 = u.pm * 256 + wr * 64 + fr, c8 = wc * 32 + 8 * fq;
;         FOR_ROWS { const int row = row0 + ai * 128 + m * 16; float s = 0.f;
;             FOR_BJ { const size_t off = (size_t)row * 2048 + u.pn * 256 + bj * 128 + c8;
;                 const f32x4 v0 = *(const f32x4*)(base + off) + acc[ai][bj][m][0], v1 = *(const f32x4*)(base + off + 4) + acc[ai][bj][m][1];
;                 *(f32x4*)(out + off) = v0; *(f32x4*)(out + off + 4) = v1;
.LBB0_1893:
	v_lshl_add_u32 v148, s58, 8, v137
	s_lshl_b32 s24, s59, 8
	s_ashr_i32 s25, s24, 31
	v_ashrrev_i32_e32 v149, 31, v148
	v_mov_b32_e32 v147, s25
	v_or_b32_e32 v146, s24, v136
	v_lshlrev_b64 v[150:151], 13, v[148:149]
	v_lshl_add_u64 v[156:157], s[34:35], 0, v[150:151]
	v_lshlrev_b64 v[150:151], 2, v[146:147]
	v_lshl_add_u64 v[146:147], v[156:157], 0, v[150:151]
	v_mov_b32_e32 v224, v146
	v_mov_b32_e32 v225, v147
	v_mov_b32_e32 v226, 0x20000
	v_mov_b32_e32 v227, 0
	global_load_dwordx4 v[164:167], v[224:225], off offset:16
	global_load_dwordx4 v[168:171], v[224:225], off
	global_load_dwordx4 v[172:175], v[224:225], off offset:528
	global_load_dwordx4 v[176:179], v[224:225], off offset:512
	v_lshl_add_u64 v[224:225], v[224:225], 0, v[226:227]
	global_load_dwordx4 v[180:183], v[224:225], off offset:16
	global_load_dwordx4 v[184:187], v[224:225], off
	global_load_dwordx4 v[188:191], v[224:225], off offset:528
	global_load_dwordx4 v[192:195], v[224:225], off offset:512
	v_lshl_add_u64 v[224:225], v[224:225], 0, v[226:227]
	global_load_dwordx4 v[196:199], v[224:225], off offset:16
	global_load_dwordx4 v[200:203], v[224:225], off
	global_load_dwordx4 v[204:207], v[224:225], off offset:528
	global_load_dwordx4 v[208:211], v[224:225], off offset:512
	v_lshl_add_u64 v[224:225], v[224:225], 0, v[226:227]
	global_load_dwordx4 v[212:215], v[224:225], off offset:16
	global_load_dwordx4 v[216:219], v[224:225], off
	global_load_dwordx4 v[220:223], v[224:225], off offset:528
	global_load_dwordx4 v[228:231], v[224:225], off offset:512
	v_lshl_add_u64 v[224:225], v[226:227], 2, v[224:225]
	v_lshl_add_u64 v[224:225], v[224:225], 0, v[226:227]
	global_load_dwordx4 v[232:235], v[224:225], off
	global_load_dwordx4 v[236:239], v[224:225], off offset:16
	global_load_dwordx4 v[244:247], v[224:225], off offset:528
	global_load_dwordx4 v[248:251], v[224:225], off offset:512
	s_waitcnt vmcnt(19)
	s_nop 1
	v_mov_b32_e32 v156, v164
	v_mov_b32_e32 v157, v165
	v_mov_b32_e32 v158, v166
	v_mov_b32_e32 v159, v167
	v_lshl_add_u64 v[224:225], v[224:225], 0, v[226:227]
	global_load_dwordx4 v[164:167], v[224:225], off
	s_waitcnt vmcnt(19)
	s_nop 1
	v_mov_b32_e32 v160, v168
	v_mov_b32_e32 v161, v169
	v_mov_b32_e32 v162, v170
	v_mov_b32_e32 v163, v171
	global_load_dwordx4 v[168:171], v[224:225], off offset:16
	s_mov_b64 s[24:25], -1
	v_pk_add_f32 v[122:123], v[122:123], v[158:159]
	v_pk_add_f32 v[126:127], v[126:127], v[162:163]
	v_pk_add_f32 v[124:125], v[124:125], v[160:161]
	v_pk_add_f32 v[120:121], v[120:121], v[156:157]
	global_store_dwordx4 v[146:147], v[124:127], off
	global_store_dwordx4 v[146:147], v[120:123], off offset:16
	s_waitcnt vmcnt(21)
	s_nop 1
	v_mov_b32_e32 v120, v172
	v_mov_b32_e32 v121, v173
	v_mov_b32_e32 v122, v174
	v_mov_b32_e32 v123, v175
	global_load_dwordx4 v[172:175], v[224:225], off offset:528
	s_nop 0
	s_waitcnt vmcnt(21)
	s_nop 1
	v_mov_b32_e32 v124, v176
	v_mov_b32_e32 v125, v177
	v_mov_b32_e32 v126, v178
	v_mov_b32_e32 v127, v179
	global_load_dwordx4 v[176:179], v[224:225], off offset:512
	v_pk_add_f32 v[112:113], v[112:113], v[120:121]
	v_pk_add_f32 v[118:119], v[118:119], v[126:127]
	v_pk_add_f32 v[116:117], v[116:117], v[124:125]
	v_pk_add_f32 v[114:115], v[114:115], v[122:123]
	global_store_dwordx4 v[146:147], v[116:119], off offset:512
	global_store_dwordx4 v[146:147], v[112:115], off offset:528
	s_nop 1
	v_or_b32_e32 v112, 16, v148
	v_ashrrev_i32_e32 v113, 31, v112
	v_lshlrev_b64 v[112:113], 13, v[112:113]
	v_lshl_add_u64 v[112:113], s[34:35], 0, v[112:113]
	v_lshl_add_u64 v[120:121], v[112:113], 0, v[150:151]
	s_waitcnt vmcnt(23)
	s_nop 1
	v_mov_b32_e32 v112, v180
	v_mov_b32_e32 v113, v181
	v_mov_b32_e32 v114, v182
	v_mov_b32_e32 v115, v183
	v_lshl_add_u64 v[224:225], v[224:225], 0, v[226:227]
	global_load_dwordx4 v[180:183], v[224:225], off
	s_waitcnt vmcnt(23)
	s_nop 1
	v_mov_b32_e32 v116, v184
	v_mov_b32_e32 v117, v185
	v_mov_b32_e32 v118, v186
	v_mov_b32_e32 v119, v187
	global_load_dwordx4 v[184:187], v[224:225], off offset:16
	v_pk_add_f32 v[106:107], v[106:107], v[114:115]
	v_pk_add_f32 v[110:111], v[110:111], v[118:119]
	v_pk_add_f32 v[108:109], v[108:109], v[116:117]
	v_pk_add_f32 v[104:105], v[104:105], v[112:113]
	global_store_dwordx4 v[120:121], v[108:111], off
	global_store_dwordx4 v[120:121], v[104:107], off offset:16
	s_waitcnt vmcnt(25)
	s_nop 1
	v_mov_b32_e32 v104, v188
	v_mov_b32_e32 v105, v189
	v_mov_b32_e32 v106, v190
	v_mov_b32_e32 v107, v191
	global_load_dwordx4 v[188:191], v[224:225], off offset:528
	s_nop 0
	s_waitcnt vmcnt(25)
	s_nop 1
	v_mov_b32_e32 v108, v192
	v_mov_b32_e32 v109, v193
	v_mov_b32_e32 v110, v194
	v_mov_b32_e32 v111, v195
	global_load_dwordx4 v[192:195], v[224:225], off offset:512
	v_pk_add_f32 v[96:97], v[96:97], v[104:105]
	v_pk_add_f32 v[102:103], v[102:103], v[110:111]
	v_pk_add_f32 v[100:101], v[100:101], v[108:109]
	v_pk_add_f32 v[98:99], v[98:99], v[106:107]
	global_store_dwordx4 v[120:121], v[100:103], off offset:512
	global_store_dwordx4 v[120:121], v[96:99], off offset:528
	s_nop 1
	v_or_b32_e32 v96, 32, v148
	v_ashrrev_i32_e32 v97, 31, v96
	v_lshlrev_b64 v[96:97], 13, v[96:97]
	v_lshl_add_u64 v[96:97], s[34:35], 0, v[96:97]
	v_lshl_add_u64 v[104:105], v[96:97], 0, v[150:151]
	s_waitcnt vmcnt(27)
	s_nop 1
	v_mov_b32_e32 v96, v196
	v_mov_b32_e32 v97, v197
	v_mov_b32_e32 v98, v198
	v_mov_b32_e32 v99, v199
	v_lshl_add_u64 v[224:225], v[224:225], 0, v[226:227]
	global_load_dwordx4 v[196:199], v[224:225], off
	s_waitcnt vmcnt(27)
; #define FOR_ROWS _Pragma("unroll") for (int ai = 0; ai < 2; ++ai) _Pragma("unroll") for (int m = 0; m < 4; ++m)
; #define FOR_BJ _Pragma("unroll") for (int bj = 0; bj < 2; ++bj)
;     DI void operator()(AccRef acc, const Unit& u, int wr, int wc, int fr, int fq) const {
;     ...
;         FOR_ROWS { const int row = row0 + ai * 128 + m * 16; float s = 0.f;
;             FOR_BJ { const size_t off = (size_t)row * 2048 + u.pn * 256 + bj * 128 + c8;
;                 const f32x4 v0 = *(const f32x4*)(base + off) + acc[ai][bj][m][0], v1 = *(const f32x4*)(base + off + 4) + acc[ai][bj][m][1];
;                 *(f32x4*)(out + off) = v0; *(f32x4*)(out + off + 4) = v1;
	s_nop 1
	v_mov_b32_e32 v100, v200
	v_mov_b32_e32 v101, v201
	v_mov_b32_e32 v102, v202
	v_mov_b32_e32 v103, v203
	global_load_dwordx4 v[200:203], v[224:225], off offset:16
	v_pk_add_f32 v[90:91], v[90:91], v[98:99]
	v_pk_add_f32 v[94:95], v[94:95], v[102:103]
	v_pk_add_f32 v[92:93], v[92:93], v[100:101]
	v_pk_add_f32 v[88:89], v[88:89], v[96:97]
	global_store_dwordx4 v[104:105], v[92:95], off
	global_store_dwordx4 v[104:105], v[88:91], off offset:16
	s_waitcnt vmcnt(29)
	s_nop 1
	v_mov_b32_e32 v88, v204
	v_mov_b32_e32 v89, v205
	v_mov_b32_e32 v90, v206
	v_mov_b32_e32 v91, v207
	global_load_dwordx4 v[204:207], v[224:225], off offset:528
	s_nop 0
	s_waitcnt vmcnt(29)
	s_nop 1
	v_mov_b32_e32 v92, v208
	v_mov_b32_e32 v93, v209
	v_mov_b32_e32 v94, v210
	v_mov_b32_e32 v95, v211
	global_load_dwordx4 v[208:211], v[224:225], off offset:512
	v_pk_add_f32 v[80:81], v[80:81], v[88:89]
	v_pk_add_f32 v[86:87], v[86:87], v[94:95]
	v_pk_add_f32 v[84:85], v[84:85], v[92:93]
	v_pk_add_f32 v[82:83], v[82:83], v[90:91]
	global_store_dwordx4 v[104:105], v[84:87], off offset:512
	global_store_dwordx4 v[104:105], v[80:83], off offset:528
	s_nop 1
	v_or_b32_e32 v80, 48, v148
	v_ashrrev_i32_e32 v81, 31, v80
	v_lshlrev_b64 v[80:81], 13, v[80:81]
	v_lshl_add_u64 v[80:81], s[34:35], 0, v[80:81]
	v_lshl_add_u64 v[88:89], v[80:81], 0, v[150:151]
	s_waitcnt vmcnt(31)
	s_nop 1
	v_mov_b32_e32 v80, v212
	v_mov_b32_e32 v81, v213
	v_mov_b32_e32 v82, v214
	v_mov_b32_e32 v83, v215
	s_waitcnt vmcnt(30)
	s_nop 1
	v_mov_b32_e32 v84, v216
	v_mov_b32_e32 v85, v217
	v_mov_b32_e32 v86, v218
	v_mov_b32_e32 v87, v219
	v_pk_add_f32 v[74:75], v[74:75], v[82:83]
	v_pk_add_f32 v[78:79], v[78:79], v[86:87]
	v_pk_add_f32 v[76:77], v[76:77], v[84:85]
	v_pk_add_f32 v[72:73], v[72:73], v[80:81]
	global_store_dwordx4 v[88:89], v[76:79], off
	global_store_dwordx4 v[88:89], v[72:75], off offset:16
	s_waitcnt vmcnt(31)
	s_nop 1
	v_mov_b32_e32 v72, v220
	v_mov_b32_e32 v73, v221
	v_mov_b32_e32 v74, v222
	v_mov_b32_e32 v75, v223
	s_nop 0
	s_waitcnt vmcnt(30)
	s_nop 1
	v_mov_b32_e32 v76, v228
	v_mov_b32_e32 v77, v229
	v_mov_b32_e32 v78, v230
	v_mov_b32_e32 v79, v231
	v_pk_add_f32 v[66:67], v[66:67], v[74:75]
	v_pk_add_f32 v[70:71], v[70:71], v[78:79]
	v_pk_add_f32 v[68:69], v[68:69], v[76:77]
	v_add_co_u32_e32 v74, vcc, s52, v146
	v_pk_add_f32 v[64:65], v[64:65], v[72:73]
	global_store_dwordx4 v[88:89], v[68:71], off offset:512
	global_store_dwordx4 v[88:89], v[64:67], off offset:528
	v_addc_co_u32_e32 v75, vcc, 0, v147, vcc
	v_lshl_add_u64 v[72:73], v[146:147], 0, s[16:17]
	s_waitcnt vmcnt(31)
	s_nop 1
	v_mov_b32_e32 v64, v232
	v_mov_b32_e32 v65, v233
	v_mov_b32_e32 v66, v234
	v_mov_b32_e32 v67, v235
	s_waitcnt vmcnt(30)
	s_nop 1
	v_mov_b32_e32 v68, v236
	v_mov_b32_e32 v69, v237
	v_mov_b32_e32 v70, v238
	v_mov_b32_e32 v71, v239
	v_pk_add_f32 v[62:63], v[62:63], v[66:67]
	v_pk_add_f32 v[60:61], v[60:61], v[64:65]
	v_pk_add_f32 v[58:59], v[58:59], v[70:71]
	v_pk_add_f32 v[56:57], v[56:57], v[68:69]
	global_store_dwordx4 v[74:75], v[60:63], off
	global_store_dwordx4 v[72:73], v[56:59], off offset:16
	s_waitcnt vmcnt(31)
	s_nop 1
	v_mov_b32_e32 v56, v244
	v_mov_b32_e32 v57, v245
	v_mov_b32_e32 v58, v246
	v_mov_b32_e32 v59, v247
	s_nop 0
	s_waitcnt vmcnt(30)
	s_nop 1
	v_mov_b32_e32 v60, v248
	v_mov_b32_e32 v61, v249
	v_mov_b32_e32 v62, v250
	v_mov_b32_e32 v63, v251
	v_pk_add_f32 v[50:51], v[50:51], v[58:59]
	v_pk_add_f32 v[54:55], v[54:55], v[62:63]
	v_pk_add_f32 v[52:53], v[52:53], v[60:61]
	v_add_co_u32_e32 v58, vcc, s53, v146
	v_pk_add_f32 v[48:49], v[48:49], v[56:57]
	global_store_dwordx4 v[72:73], v[52:55], off offset:512
	global_store_dwordx4 v[72:73], v[48:51], off offset:528
	v_addc_co_u32_e32 v59, vcc, 0, v147, vcc
	v_lshl_add_u64 v[56:57], v[146:147], 0, s[18:19]
	s_waitcnt vmcnt(31)
; #define FOR_ROWS _Pragma("unroll") for (int ai = 0; ai < 2; ++ai) _Pragma("unroll") for (int m = 0; m < 4; ++m)
; #define FOR_BJ _Pragma("unroll") for (int bj = 0; bj < 2; ++bj)
;     DI void operator()(AccRef acc, const Unit& u, int wr, int wc, int fr, int fq) const {
;     ...
;         FOR_ROWS { const int row = row0 + ai * 128 + m * 16; float s = 0.f;
;             FOR_BJ { const size_t off = (size_t)row * 2048 + u.pn * 256 + bj * 128 + c8;
;                 const f32x4 v0 = *(const f32x4*)(base + off) + acc[ai][bj][m][0], v1 = *(const f32x4*)(base + off + 4) + acc[ai][bj][m][1];
;                 *(f32x4*)(out + off) = v0; *(f32x4*)(out + off + 4) = v1;
	s_nop 1
	v_mov_b32_e32 v48, v164
	v_mov_b32_e32 v49, v165
	v_mov_b32_e32 v50, v166
	v_mov_b32_e32 v51, v167
	s_waitcnt vmcnt(30)
	s_nop 1
	v_mov_b32_e32 v52, v168
	v_mov_b32_e32 v53, v169
	v_mov_b32_e32 v54, v170
	v_mov_b32_e32 v55, v171
	v_pk_add_f32 v[46:47], v[46:47], v[50:51]
	v_pk_add_f32 v[44:45], v[44:45], v[48:49]
	v_pk_add_f32 v[42:43], v[42:43], v[54:55]
	v_pk_add_f32 v[40:41], v[40:41], v[52:53]
	global_store_dwordx4 v[58:59], v[44:47], off
	global_store_dwordx4 v[56:57], v[40:43], off offset:16
	s_waitcnt vmcnt(29)
	s_nop 1
	v_mov_b32_e32 v40, v172
	v_mov_b32_e32 v41, v173
	v_mov_b32_e32 v42, v174
	v_mov_b32_e32 v43, v175
	s_nop 0
	s_waitcnt vmcnt(28)
	s_nop 1
	v_mov_b32_e32 v44, v176
	v_mov_b32_e32 v45, v177
	v_mov_b32_e32 v46, v178
	v_mov_b32_e32 v47, v179
	v_pk_add_f32 v[34:35], v[34:35], v[42:43]
	v_pk_add_f32 v[38:39], v[38:39], v[46:47]
	v_pk_add_f32 v[36:37], v[36:37], v[44:45]
	v_add_co_u32_e32 v42, vcc, s54, v146
	v_pk_add_f32 v[32:33], v[32:33], v[40:41]
	global_store_dwordx4 v[56:57], v[36:39], off offset:512
	global_store_dwordx4 v[56:57], v[32:35], off offset:528
	v_addc_co_u32_e32 v43, vcc, 0, v147, vcc
	v_lshl_add_u64 v[40:41], v[146:147], 0, s[20:21]
	s_waitcnt vmcnt(27)
	s_nop 1
	v_mov_b32_e32 v32, v180
	v_mov_b32_e32 v33, v181
	v_mov_b32_e32 v34, v182
	v_mov_b32_e32 v35, v183
	s_waitcnt vmcnt(26)
	s_nop 1
	v_mov_b32_e32 v36, v184
	v_mov_b32_e32 v37, v185
	v_mov_b32_e32 v38, v186
	v_mov_b32_e32 v39, v187
	v_pk_add_f32 v[30:31], v[30:31], v[34:35]
	v_pk_add_f32 v[28:29], v[28:29], v[32:33]
	v_pk_add_f32 v[26:27], v[26:27], v[38:39]
	v_pk_add_f32 v[24:25], v[24:25], v[36:37]
	global_store_dwordx4 v[42:43], v[28:31], off
	global_store_dwordx4 v[40:41], v[24:27], off offset:16
	s_waitcnt vmcnt(25)
	s_nop 1
	v_mov_b32_e32 v24, v188
	v_mov_b32_e32 v25, v189
	v_mov_b32_e32 v26, v190
	v_mov_b32_e32 v27, v191
	s_nop 0
	s_waitcnt vmcnt(24)
	s_nop 1
	v_mov_b32_e32 v28, v192
	v_mov_b32_e32 v29, v193
	v_mov_b32_e32 v30, v194
	v_mov_b32_e32 v31, v195
	v_pk_add_f32 v[18:19], v[18:19], v[26:27]
	v_pk_add_f32 v[22:23], v[22:23], v[30:31]
	v_pk_add_f32 v[20:21], v[20:21], v[28:29]
	v_add_co_u32_e32 v26, vcc, s55, v146
	v_pk_add_f32 v[16:17], v[16:17], v[24:25]
	global_store_dwordx4 v[40:41], v[20:23], off offset:512
	global_store_dwordx4 v[40:41], v[16:19], off offset:528
	v_addc_co_u32_e32 v27, vcc, 0, v147, vcc
	s_nop 0
	v_lshl_add_u64 v[16:17], v[146:147], 0, s[8:9]
	s_waitcnt vmcnt(23)
	s_nop 1
	v_mov_b32_e32 v18, v196
	v_mov_b32_e32 v19, v197
	v_mov_b32_e32 v20, v198
	v_mov_b32_e32 v21, v199
	s_waitcnt vmcnt(22)
	s_nop 1
	v_mov_b32_e32 v22, v200
	v_mov_b32_e32 v23, v201
	v_mov_b32_e32 v24, v202
	v_mov_b32_e32 v25, v203
	s_and_b64 vcc, exec, s[4:5]
	v_pk_add_f32 v[14:15], v[14:15], v[20:21]
	v_pk_add_f32 v[12:13], v[12:13], v[18:19]
	v_pk_add_f32 v[10:11], v[10:11], v[24:25]
	v_pk_add_f32 v[8:9], v[8:9], v[22:23]
	global_store_dwordx4 v[26:27], v[12:15], off
	global_store_dwordx4 v[16:17], v[8:11], off offset:16
	s_waitcnt vmcnt(21)
	s_nop 1
	v_mov_b32_e32 v8, v204
	v_mov_b32_e32 v9, v205
	v_mov_b32_e32 v10, v206
	v_mov_b32_e32 v11, v207
	s_nop 0
	s_waitcnt vmcnt(20)
	s_nop 1
	v_mov_b32_e32 v12, v208
	v_mov_b32_e32 v13, v209
	v_mov_b32_e32 v14, v210
	v_mov_b32_e32 v15, v211
	v_pk_add_f32 v[2:3], v[2:3], v[10:11]
	v_pk_add_f32 v[6:7], v[6:7], v[14:15]
	v_pk_add_f32 v[4:5], v[4:5], v[12:13]
	v_pk_add_f32 v[0:1], v[0:1], v[8:9]
	global_store_dwordx4 v[16:17], v[4:7], off offset:512
	global_store_dwordx4 v[16:17], v[0:3], off offset:528
	s_cbranch_vccnz .LBB0_1878
	s_andn2_b64 vcc, exec, s[10:11]
	s_cbranch_vccnz .LBB0_1877
	s_barrier
	s_branch .LBB0_1877
